# P1 conv epilogue: silu 1+exp2 computed with packed f32 mul/add, fewer hazard nops
# baseline (speedup 1.0000x reference)
; #define LAS __attribute__((address_space(3)))
;     __device__ __forceinline__ void operator()(const f32x4 (&acc)[2][2][4][2], const Unit& u, int wr, int wc, int fr, int fq, LAS unsigned char* hb) const {
;     ...
;         asm volatile("s_waitcnt lgkmcnt(0)" ::: "memory"); __builtin_amdgcn_s_barrier(); asm volatile("" ::: "memory");
;         const int hr1 = H - 1, hr2 = (H - 2 + fr) < (H - 1) ? (H - 2 + fr) : (H - 1), hr3 = (H - 3 + fr) < (H - 1) ? (H - 3 + fr) : (H - 1);
;         const int ch0 = (u.pn - 4) * BM + chl;
; #pragma unroll
;         for (int ai = 0; ai < 2; ++ai)
; #pragma unroll
;             for (int m = 0; m < 4; ++m) { asm volatile("" ::: "memory"); __builtin_amdgcn_sched_barrier(0);
;                 const int q = 8 * ai + 4 * wr + m, prev = q > 0 ? q - 1 : 0; const int lr = ai * HALF + wr * 64 + m * 16 + fr, R = R0 + lr;
;                 const int Rc = R < 0 ? 0 : R; const int b = Rc / LL, p = Rc - b * LL;
;                 const bool ok = (lr >= H && R < TT);
;                 const unsigned ooff = ((unsigned)Rc * (unsigned)LDP + (unsigned)(OFF_XBC + ch0)) * 2u;
; #pragma unroll
;                 for (int bn = 0; bn < 4; ++bn) { const int bj = bn >> 1, n = bn & 1; const int co = bj * HALF + 4 * n;
;                     const unsigned woff = (unsigned)(ch0 + co) * 4u;
;                     const f32x4 w0 = *(const f32x4*)((const char*)cw + woff), w1 = *(const f32x4*)((const char*)cw + woff + XBCW * 4), w2 = *(const f32x4*)((const char*)cw + woff + 2 * XBCW * 4), w3 = *(const f32x4*)((const char*)cw + woff + 3 * XBCW * 4), bs = *(const f32x4*)((const char*)cb + woff);
;                     const LAS unsigned char* hp = hb + (prev * H * NCH + chl + co) * 2;
;                     const u32x2 q1 = *(const LAS u32x2*)(hp + hr1 * NCH * 2), q2 = *(const LAS u32x2*)(hp + hr2 * NCH * 2), q3 = *(const LAS u32x2*)(hp + hr3 * NCH * 2);
;                     const float h1[4] = {__builtin_bit_cast(float, q1.x << 16), __builtin_bit_cast(float, q1.x & 0xffff0000u), __builtin_bit_cast(float, q1.y << 16), __builtin_bit_cast(float, q1.y & 0xffff0000u)};
;                     const float h2[4] = {__builtin_bit_cast(float, q2.x << 16), __builtin_bit_cast(float, q2.x & 0xffff0000u), __builtin_bit_cast(float, q2.y << 16), __builtin_bit_cast(float, q2.y & 0xffff0000u)};
.Lp1w_skipstore:
	s_mov_b32 s98, 0xbfb8aa3b
	s_waitcnt lgkmcnt(0)
	s_barrier
	v_min_i32_e32 v136, 1, v149
	v_min_i32_e32 v146, 2, v149
	s_lshl_b32 s2, s2, 8
	s_add_i32 s22, s2, 0x3ffffc00
	v_add_u32_e32 v164, s2, v148
	v_add_u32_e32 v165, 0xfffffd00, v148
	v_lshlrev_b32_e32 v163, 9, v136
	v_lshlrev_b32_e32 v162, 9, v146
	v_add_u32_e32 v136, s17, v161
	v_max_i32_e32 v146, 0, v136
	v_mul_hi_u32 v147, v146, s56
	v_lshrrev_b32_e32 v147, 11, v147
	v_mul_u32_u24_e32 v147, 0x1010, v147
	v_sub_u32_e32 v147, v146, v147
	v_cmp_gt_i32_e64 s[4:5], s50, v136
	v_mul_lo_u32 v136, v146, s51
	v_add_u32_e32 v146, s37, v165
	v_lshl_add_u32 v166, v146, 1, s53
	v_cmp_lt_i32_e32 vcc, 2, v161
	v_add_u32_e32 v167, v166, v163
	s_and_b64 s[2:3], vcc, s[4:5]
	v_add_lshl_u32 v150, v136, v164, 1
	v_cmp_eq_u32_e64 s[8:9], 0, v147
	v_cmp_lt_u32_e64 s[6:7], 1, v147
	v_cmp_lt_u32_e64 s[4:5], 2, v147
	v_add_lshl_u32 v136, s22, v148, 2
	ds_read_b64 v[146:147], v166 offset:1024
	v_add_u32_e32 v168, v166, v162
	ds_read_b64 v[148:149], v167 offset:512
	ds_read_b64 v[184:185], v168
	v_readlane_b32 s22, v237, 58
	v_mov_b32_e32 v151, v137
	s_waitcnt lgkmcnt(0)
	v_lshlrev_b32_e32 v179, 16, v146
	v_and_b32_e32 v182, 0xffff0000, v146
	v_lshlrev_b32_e32 v173, 16, v147
	v_and_b32_e32 v174, 0xffff0000, v147
	v_lshlrev_b32_e32 v177, 16, v148
	v_and_b32_e32 v178, 0xffff0000, v148
	v_lshlrev_b32_e32 v171, 16, v149
	v_and_b32_e32 v172, 0xffff0000, v149
	v_lshlrev_b32_e32 v175, 16, v184
	v_and_b32_e32 v176, 0xffff0000, v184
	v_lshlrev_b32_e32 v169, 16, v185
	v_and_b32_e32 v170, 0xffff0000, v185
	v_readlane_b32 s23, v237, 59
	v_mov_b32_dpp v179, v124 row_shr:1 row_mask:0xf bank_mask:0xf
	v_mov_b32_dpp v177, v124 row_shr:2 row_mask:0xf bank_mask:0xf
	v_mov_b32_dpp v175, v124 row_shr:3 row_mask:0xf bank_mask:0xf
	v_mov_b32_dpp v182, v125 row_shr:1 row_mask:0xf bank_mask:0xf
	v_mov_b32_dpp v178, v125 row_shr:2 row_mask:0xf bank_mask:0xf
	v_mov_b32_dpp v176, v125 row_shr:3 row_mask:0xf bank_mask:0xf
	v_mov_b32_dpp v173, v126 row_shr:1 row_mask:0xf bank_mask:0xf
	v_mov_b32_dpp v171, v126 row_shr:2 row_mask:0xf bank_mask:0xf
	v_mov_b32_dpp v169, v126 row_shr:3 row_mask:0xf bank_mask:0xf
	v_mov_b32_dpp v174, v127 row_shr:1 row_mask:0xf bank_mask:0xf
	v_mov_b32_dpp v172, v127 row_shr:2 row_mask:0xf bank_mask:0xf
	v_mov_b32_dpp v170, v127 row_shr:3 row_mask:0xf bank_mask:0xf
	v_lshl_add_u64 v[150:151], s[22:23], 0, v[150:151]
	s_and_saveexec_b64 s[22:23], s[2:3]
	s_cbranch_execz .LBB0_185
	ds_read_b128 v[184:187], v238 offset:4096
	ds_read_b128 v[188:191], v238 offset:3072
	ds_read_b128 v[192:195], v238 offset:2048
	v_cndmask_b32_e64 v183, v182, 0, s[8:9]
	ds_read_b128 v[196:199], v238 offset:1024
	s_nop 0
	ds_read_b128 v[200:203], v238
	v_cndmask_b32_e64 v182, v179, 0, s[8:9]
	v_cndmask_b32_e64 v179, 0, v178, s[6:7]
	v_cndmask_b32_e64 v178, 0, v177, s[6:7]
	v_cndmask_b32_e64 v177, 0, v176, s[4:5]
	v_cndmask_b32_e64 v176, 0, v175, s[4:5]
	s_waitcnt lgkmcnt(0)
	v_pk_fma_f32 v[124:125], v[124:125], v[188:189], v[184:185]
	v_pk_fma_f32 v[126:127], v[126:127], v[190:191], v[186:187]
	v_pk_fma_f32 v[124:125], v[182:183], v[192:193], v[124:125]
	s_nop 0
	v_pk_fma_f32 v[124:125], v[178:179], v[196:197], v[124:125]
	s_nop 0
	v_pk_fma_f32 v[124:125], v[176:177], v[200:201], v[124:125]
	s_nop 0
	v_pk_mul_f32 v[176:177], v[124:125], s[98:99] op_sel_hi:[1,0]
	v_exp_f32_e32 v176, v176
	v_exp_f32_e32 v177, v177
	s_nop 0
	v_pk_add_f32 v[176:177], v[176:177], 1.0 op_sel_hi:[1,0]
	v_rcp_f32_e32 v176, v176
	v_rcp_f32_e32 v177, v177
	v_cndmask_b32_e64 v175, v174, 0, s[8:9]
	v_cndmask_b32_e64 v174, v173, 0, s[8:9]
	v_pk_fma_f32 v[126:127], v[174:175], v[194:195], v[126:127]
	v_cndmask_b32_e64 v173, 0, v172, s[6:7]
	v_cndmask_b32_e64 v172, 0, v171, s[6:7]
	v_pk_fma_f32 v[126:127], v[172:173], v[198:199], v[126:127]
	v_cndmask_b32_e64 v171, 0, v170, s[4:5]
	v_cndmask_b32_e64 v170, 0, v169, s[4:5]
	v_pk_mul_f32 v[124:125], v[124:125], v[176:177]
	v_pk_fma_f32 v[126:127], v[170:171], v[202:203], v[126:127]
	v_cvt_pk_bf16_f32 v124, v124, v125
	v_pk_mul_f32 v[170:171], v[126:127], s[98:99] op_sel_hi:[1,0]
	v_exp_f32_e32 v170, v170
	v_exp_f32_e32 v171, v171
	s_nop 0
	v_pk_add_f32 v[170:171], v[170:171], 1.0 op_sel_hi:[1,0]
	v_rcp_f32_e32 v170, v170
	v_rcp_f32_e32 v171, v171
	s_nop 0
	v_pk_mul_f32 v[126:127], v[126:127], v[170:171]
	s_nop 0
	v_cvt_pk_bf16_f32 v125, v126, v127
	global_store_dwordx2 v[150:151], v[124:125], off
; #define LAS __attribute__((address_space(3)))
;     __device__ __forceinline__ void operator()(const f32x4 (&acc)[2][2][4][2], const Unit& u, int wr, int wc, int fr, int fq, LAS unsigned char* hb) const {
;     ...
;                 for (int bn = 0; bn < 4; ++bn) { const int bj = bn >> 1, n = bn & 1; const int co = bj * HALF + 4 * n;
;                     const unsigned woff = (unsigned)(ch0 + co) * 4u;
;                     const f32x4 w0 = *(const f32x4*)((const char*)cw + woff), w1 = *(const f32x4*)((const char*)cw + woff + XBCW * 4), w2 = *(const f32x4*)((const char*)cw + woff + 2 * XBCW * 4), w3 = *(const f32x4*)((const char*)cw + woff + 3 * XBCW * 4), bs = *(const f32x4*)((const char*)cb + woff);
;                     const LAS unsigned char* hp = hb + (prev * H * NCH + chl + co) * 2;
;                     const u32x2 q1 = *(const LAS u32x2*)(hp + hr1 * NCH * 2), q2 = *(const LAS u32x2*)(hp + hr2 * NCH * 2), q3 = *(const LAS u32x2*)(hp + hr3 * NCH * 2);
;                     const float h1[4] = {__builtin_bit_cast(float, q1.x << 16), __builtin_bit_cast(float, q1.x & 0xffff0000u), __builtin_bit_cast(float, q1.y << 16), __builtin_bit_cast(float, q1.y & 0xffff0000u)};
;                     const float h2[4] = {__builtin_bit_cast(float, q2.x << 16), __builtin_bit_cast(float, q2.x & 0xffff0000u), __builtin_bit_cast(float, q2.y << 16), __builtin_bit_cast(float, q2.y & 0xffff0000u)};
;                     const float h3[4] = {__builtin_bit_cast(float, q3.x << 16), __builtin_bit_cast(float, q3.x & 0xffff0000u), __builtin_bit_cast(float, q3.y << 16), __builtin_bit_cast(float, q3.y & 0xffff0000u)};
;                     const f32x4 gv = acc[ai][bj][m][n];
;                     float o[4];
; #pragma unroll
;                     for (int j = 0; j < 4; ++j) { const float g = gv[j];
;                         float g1 = dpp_row_shr<1>(h1[j], g), g2 = dpp_row_shr<2>(h2[j], g), g3 = dpp_row_shr<3>(h3[j], g);
;                         g1 = p >= 1 ? g1 : 0.f; g2 = p >= 2 ? g2 : 0.f; g3 = p >= 3 ? g3 : 0.f;
;                         const float v = bs[j] + w3[j] * g + w2[j] * g1 + w1[j] * g2 + w0[j] * g3;
;                         o[j] = v * __builtin_amdgcn_rcpf(1.f + ex2(-1.4426950408889634f * v)); }
;                     if (ok) { u32x2 w; w.x = pk2e(o[0], o[1]); w.y = pk2e(o[2], o[3]); *(u32x2*)((char*)O + ooff + co * 2) = w; }
.LBB0_185:
	s_or_b64 exec, exec, s[22:23]
	ds_read_b64 v[124:125], v166 offset:1032
	ds_read_b64 v[126:127], v167 offset:520
	ds_read_b64 v[186:187], v168 offset:8
	v_add_u32_e32 v184, 16, v136
	v_mov_b32_e32 v185, v137
	s_waitcnt lgkmcnt(0)
	v_lshlrev_b32_e32 v179, 16, v124
	v_and_b32_e32 v182, 0xffff0000, v124
	v_lshlrev_b32_e32 v173, 16, v125
	v_and_b32_e32 v174, 0xffff0000, v125
	v_lshlrev_b32_e32 v177, 16, v126
	v_and_b32_e32 v178, 0xffff0000, v126
	v_lshlrev_b32_e32 v171, 16, v127
	v_and_b32_e32 v172, 0xffff0000, v127
	v_lshlrev_b32_e32 v175, 16, v186
	v_and_b32_e32 v176, 0xffff0000, v186
	v_lshlrev_b32_e32 v169, 16, v187
	v_and_b32_e32 v170, 0xffff0000, v187
	v_mov_b32_dpp v179, v120 row_shr:1 row_mask:0xf bank_mask:0xf
	v_mov_b32_dpp v177, v120 row_shr:2 row_mask:0xf bank_mask:0xf
	v_mov_b32_dpp v175, v120 row_shr:3 row_mask:0xf bank_mask:0xf
	v_mov_b32_dpp v182, v121 row_shr:1 row_mask:0xf bank_mask:0xf
	v_mov_b32_dpp v178, v121 row_shr:2 row_mask:0xf bank_mask:0xf
	v_mov_b32_dpp v176, v121 row_shr:3 row_mask:0xf bank_mask:0xf
	v_mov_b32_dpp v173, v122 row_shr:1 row_mask:0xf bank_mask:0xf
	v_mov_b32_dpp v171, v122 row_shr:2 row_mask:0xf bank_mask:0xf
	v_mov_b32_dpp v169, v122 row_shr:3 row_mask:0xf bank_mask:0xf
	v_mov_b32_dpp v174, v123 row_shr:1 row_mask:0xf bank_mask:0xf
	v_mov_b32_dpp v172, v123 row_shr:2 row_mask:0xf bank_mask:0xf
	v_mov_b32_dpp v170, v123 row_shr:3 row_mask:0xf bank_mask:0xf
	s_and_saveexec_b64 s[22:23], s[2:3]
	s_cbranch_execz .LBB0_187
	ds_read_b128 v[184:187], v238 offset:4112
	ds_read_b128 v[188:191], v238 offset:3088
	ds_read_b128 v[192:195], v238 offset:2064
	v_cndmask_b32_e64 v183, v182, 0, s[8:9]
	ds_read_b128 v[196:199], v238 offset:1040
	s_nop 0
	ds_read_b128 v[200:203], v238 offset:16
	v_cndmask_b32_e64 v182, v179, 0, s[8:9]
	v_cndmask_b32_e64 v179, 0, v178, s[6:7]
	v_cndmask_b32_e64 v178, 0, v177, s[6:7]
	v_cndmask_b32_e64 v177, 0, v176, s[4:5]
	v_cndmask_b32_e64 v176, 0, v175, s[4:5]
	s_waitcnt lgkmcnt(0)
	v_pk_fma_f32 v[120:121], v[120:121], v[188:189], v[184:185]
	v_pk_fma_f32 v[122:123], v[122:123], v[190:191], v[186:187]
	v_pk_fma_f32 v[120:121], v[182:183], v[192:193], v[120:121]
	s_nop 0
	v_pk_fma_f32 v[120:121], v[178:179], v[196:197], v[120:121]
	s_nop 0
	v_pk_fma_f32 v[120:121], v[176:177], v[200:201], v[120:121]
	s_nop 0
	v_pk_mul_f32 v[176:177], v[120:121], s[98:99] op_sel_hi:[1,0]
	v_exp_f32_e32 v176, v176
	v_exp_f32_e32 v177, v177
	s_nop 0
	v_pk_add_f32 v[176:177], v[176:177], 1.0 op_sel_hi:[1,0]
	v_rcp_f32_e32 v176, v176
	v_rcp_f32_e32 v177, v177
	v_cndmask_b32_e64 v175, v174, 0, s[8:9]
	v_cndmask_b32_e64 v174, v173, 0, s[8:9]
	v_pk_fma_f32 v[122:123], v[174:175], v[194:195], v[122:123]
	v_cndmask_b32_e64 v173, 0, v172, s[6:7]
	v_cndmask_b32_e64 v172, 0, v171, s[6:7]
	v_pk_fma_f32 v[122:123], v[172:173], v[198:199], v[122:123]
	v_cndmask_b32_e64 v171, 0, v170, s[4:5]
	v_cndmask_b32_e64 v170, 0, v169, s[4:5]
	v_pk_mul_f32 v[120:121], v[120:121], v[176:177]
	v_pk_fma_f32 v[122:123], v[170:171], v[202:203], v[122:123]
	v_cvt_pk_bf16_f32 v120, v120, v121
	v_pk_mul_f32 v[170:171], v[122:123], s[98:99] op_sel_hi:[1,0]
	v_exp_f32_e32 v170, v170
	v_exp_f32_e32 v171, v171
	s_nop 0
	v_pk_add_f32 v[170:171], v[170:171], 1.0 op_sel_hi:[1,0]
	v_rcp_f32_e32 v170, v170
	v_rcp_f32_e32 v171, v171
	s_nop 0
	v_pk_mul_f32 v[122:123], v[122:123], v[170:171]
	s_nop 0
	v_cvt_pk_bf16_f32 v121, v122, v123
	global_store_dwordx2 v[150:151], v[120:121], off offset:8
.LBB0_187:
	s_or_b64 exec, exec, s[22:23]
	ds_read_b64 v[120:121], v166 offset:1280
	ds_read_b64 v[122:123], v167 offset:768
	ds_read_b64 v[186:187], v168 offset:256
	v_add_u32_e32 v184, 0x200, v136
	v_mov_b32_e32 v185, v137
	s_waitcnt lgkmcnt(0)
	v_lshlrev_b32_e32 v179, 16, v120
	v_and_b32_e32 v182, 0xffff0000, v120
	v_lshlrev_b32_e32 v173, 16, v121
	v_and_b32_e32 v174, 0xffff0000, v121
	v_lshlrev_b32_e32 v177, 16, v122
	v_and_b32_e32 v178, 0xffff0000, v122
	v_lshlrev_b32_e32 v171, 16, v123
	v_and_b32_e32 v172, 0xffff0000, v123
	v_lshlrev_b32_e32 v175, 16, v186
	v_and_b32_e32 v176, 0xffff0000, v186
	v_lshlrev_b32_e32 v169, 16, v187
	v_and_b32_e32 v170, 0xffff0000, v187
	v_mov_b32_dpp v179, v116 row_shr:1 row_mask:0xf bank_mask:0xf
	v_mov_b32_dpp v177, v116 row_shr:2 row_mask:0xf bank_mask:0xf
	v_mov_b32_dpp v175, v116 row_shr:3 row_mask:0xf bank_mask:0xf
	v_mov_b32_dpp v182, v117 row_shr:1 row_mask:0xf bank_mask:0xf
	v_mov_b32_dpp v178, v117 row_shr:2 row_mask:0xf bank_mask:0xf
	v_mov_b32_dpp v176, v117 row_shr:3 row_mask:0xf bank_mask:0xf
	v_mov_b32_dpp v173, v118 row_shr:1 row_mask:0xf bank_mask:0xf
	v_mov_b32_dpp v171, v118 row_shr:2 row_mask:0xf bank_mask:0xf
	v_mov_b32_dpp v169, v118 row_shr:3 row_mask:0xf bank_mask:0xf
	v_mov_b32_dpp v174, v119 row_shr:1 row_mask:0xf bank_mask:0xf
	v_mov_b32_dpp v172, v119 row_shr:2 row_mask:0xf bank_mask:0xf
	v_mov_b32_dpp v170, v119 row_shr:3 row_mask:0xf bank_mask:0xf
	s_and_saveexec_b64 s[22:23], s[2:3]
	s_cbranch_execz .LBB0_189
	ds_read_b128 v[184:187], v238 offset:4608
	ds_read_b128 v[188:191], v238 offset:3584
	ds_read_b128 v[192:195], v238 offset:2560
	v_cndmask_b32_e64 v183, v182, 0, s[8:9]
	ds_read_b128 v[196:199], v238 offset:1536
	s_nop 0
	ds_read_b128 v[200:203], v238 offset:512
	v_cndmask_b32_e64 v182, v179, 0, s[8:9]
	v_cndmask_b32_e64 v179, 0, v178, s[6:7]
	v_cndmask_b32_e64 v178, 0, v177, s[6:7]
	v_cndmask_b32_e64 v177, 0, v176, s[4:5]
	v_cndmask_b32_e64 v176, 0, v175, s[4:5]
	s_waitcnt lgkmcnt(0)
	v_pk_fma_f32 v[116:117], v[116:117], v[188:189], v[184:185]
	v_pk_fma_f32 v[118:119], v[118:119], v[190:191], v[186:187]
	v_pk_fma_f32 v[116:117], v[182:183], v[192:193], v[116:117]
	s_nop 0
	v_pk_fma_f32 v[116:117], v[178:179], v[196:197], v[116:117]
	s_nop 0
	v_pk_fma_f32 v[116:117], v[176:177], v[200:201], v[116:117]
	s_nop 0
	v_pk_mul_f32 v[176:177], v[116:117], s[98:99] op_sel_hi:[1,0]
	v_exp_f32_e32 v176, v176
	v_exp_f32_e32 v177, v177
	s_nop 0
	v_pk_add_f32 v[176:177], v[176:177], 1.0 op_sel_hi:[1,0]
	v_rcp_f32_e32 v176, v176
	v_rcp_f32_e32 v177, v177
	v_cndmask_b32_e64 v175, v174, 0, s[8:9]
	v_cndmask_b32_e64 v174, v173, 0, s[8:9]
	v_pk_fma_f32 v[118:119], v[174:175], v[194:195], v[118:119]
	v_cndmask_b32_e64 v173, 0, v172, s[6:7]
	v_cndmask_b32_e64 v172, 0, v171, s[6:7]
	v_pk_fma_f32 v[118:119], v[172:173], v[198:199], v[118:119]
	v_cndmask_b32_e64 v171, 0, v170, s[4:5]
	v_cndmask_b32_e64 v170, 0, v169, s[4:5]
	v_pk_mul_f32 v[116:117], v[116:117], v[176:177]
	v_pk_fma_f32 v[118:119], v[170:171], v[202:203], v[118:119]
	v_cvt_pk_bf16_f32 v116, v116, v117
	v_pk_mul_f32 v[170:171], v[118:119], s[98:99] op_sel_hi:[1,0]
	v_exp_f32_e32 v170, v170
	v_exp_f32_e32 v171, v171
	s_nop 0
	v_pk_add_f32 v[170:171], v[170:171], 1.0 op_sel_hi:[1,0]
	v_rcp_f32_e32 v170, v170
	v_rcp_f32_e32 v171, v171
	s_nop 0
	v_pk_mul_f32 v[118:119], v[118:119], v[170:171]
	s_nop 0
	v_cvt_pk_bf16_f32 v117, v118, v119
	global_store_dwordx2 v[150:151], v[116:117], off offset:256
;     __device__ __forceinline__ void operator()(const f32x4 (&acc)[2][2][4][2], const Unit& u, int wr, int wc, int fr, int fq, LAS unsigned char* hb) const {
;     ...
;             for (int m = 0; m < 4; ++m) { asm volatile("" ::: "memory"); __builtin_amdgcn_sched_barrier(0);
;                 const int q = 8 * ai + 4 * wr + m, prev = q > 0 ? q - 1 : 0; const int lr = ai * HALF + wr * 64 + m * 16 + fr, R = R0 + lr;
;                 const int Rc = R < 0 ? 0 : R; const int b = Rc / LL, p = Rc - b * LL;
;                 const bool ok = (lr >= H && R < TT);
;                 const unsigned ooff = ((unsigned)Rc * (unsigned)LDP + (unsigned)(OFF_XBC + ch0)) * 2u;
; #pragma unroll
;                 for (int bn = 0; bn < 4; ++bn) { const int bj = bn >> 1, n = bn & 1; const int co = bj * HALF + 4 * n;
;                     const unsigned woff = (unsigned)(ch0 + co) * 4u;
;                     const f32x4 w0 = *(const f32x4*)((const char*)cw + woff), w1 = *(const f32x4*)((const char*)cw + woff + XBCW * 4), w2 = *(const f32x4*)((const char*)cw + woff + 2 * XBCW * 4), w3 = *(const f32x4*)((const char*)cw + woff + 3 * XBCW * 4), bs = *(const f32x4*)((const char*)cb + woff);
;                     const LAS unsigned char* hp = hb + (prev * H * NCH + chl + co) * 2;
;                     const u32x2 q1 = *(const LAS u32x2*)(hp + hr1 * NCH * 2), q2 = *(const LAS u32x2*)(hp + hr2 * NCH * 2), q3 = *(const LAS u32x2*)(hp + hr3 * NCH * 2);
;                     const float h1[4] = {__builtin_bit_cast(float, q1.x << 16), __builtin_bit_cast(float, q1.x & 0xffff0000u), __builtin_bit_cast(float, q1.y << 16), __builtin_bit_cast(float, q1.y & 0xffff0000u)};
;                     const float h2[4] = {__builtin_bit_cast(float, q2.x << 16), __builtin_bit_cast(float, q2.x & 0xffff0000u), __builtin_bit_cast(float, q2.y << 16), __builtin_bit_cast(float, q2.y & 0xffff0000u)};
;                     const float h3[4] = {__builtin_bit_cast(float, q3.x << 16), __builtin_bit_cast(float, q3.x & 0xffff0000u), __builtin_bit_cast(float, q3.y << 16), __builtin_bit_cast(float, q3.y & 0xffff0000u)};
;                     const f32x4 gv = acc[ai][bj][m][n];
;                     float o[4];
; #pragma unroll
;                     for (int j = 0; j < 4; ++j) { const float g = gv[j];
;                         float g1 = dpp_row_shr<1>(h1[j], g), g2 = dpp_row_shr<2>(h2[j], g), g3 = dpp_row_shr<3>(h3[j], g);
.LBB0_189:
	s_or_b64 exec, exec, s[22:23]
	ds_read_b64 v[116:117], v166 offset:1288
	ds_read_b64 v[118:119], v167 offset:776
	ds_read_b64 v[166:167], v168 offset:264
	v_add_u32_e32 v136, 0x210, v136
	s_waitcnt lgkmcnt(0)
	v_lshlrev_b32_e32 v176, 16, v116
	v_and_b32_e32 v177, 0xffff0000, v116
	v_lshlrev_b32_e32 v170, 16, v117
	v_and_b32_e32 v171, 0xffff0000, v117
	v_lshlrev_b32_e32 v174, 16, v118
	v_and_b32_e32 v175, 0xffff0000, v118
	v_lshlrev_b32_e32 v168, 16, v119
	v_and_b32_e32 v169, 0xffff0000, v119
	v_lshlrev_b32_e32 v172, 16, v166
	v_and_b32_e32 v173, 0xffff0000, v166
	v_lshlrev_b32_e32 v166, 16, v167
	v_and_b32_e32 v167, 0xffff0000, v167
	v_mov_b32_dpp v176, v112 row_shr:1 row_mask:0xf bank_mask:0xf
	v_mov_b32_dpp v174, v112 row_shr:2 row_mask:0xf bank_mask:0xf
	v_mov_b32_dpp v172, v112 row_shr:3 row_mask:0xf bank_mask:0xf
	v_mov_b32_dpp v177, v113 row_shr:1 row_mask:0xf bank_mask:0xf
	v_mov_b32_dpp v175, v113 row_shr:2 row_mask:0xf bank_mask:0xf
	v_mov_b32_dpp v173, v113 row_shr:3 row_mask:0xf bank_mask:0xf
	v_mov_b32_dpp v170, v114 row_shr:1 row_mask:0xf bank_mask:0xf
	v_mov_b32_dpp v168, v114 row_shr:2 row_mask:0xf bank_mask:0xf
	v_mov_b32_dpp v166, v114 row_shr:3 row_mask:0xf bank_mask:0xf
	v_mov_b32_dpp v171, v115 row_shr:1 row_mask:0xf bank_mask:0xf
	v_mov_b32_dpp v169, v115 row_shr:2 row_mask:0xf bank_mask:0xf
	v_mov_b32_dpp v167, v115 row_shr:3 row_mask:0xf bank_mask:0xf
	s_and_saveexec_b64 s[22:23], s[2:3]
	s_cbranch_execz .LBB0_191
	ds_read_b128 v[182:185], v238 offset:4624
	ds_read_b128 v[186:189], v238 offset:3600
	v_cndmask_b32_e64 v177, v177, 0, s[8:9]
	ds_read_b128 v[190:193], v238 offset:2576
	v_cndmask_b32_e64 v176, v176, 0, s[8:9]
	ds_read_b128 v[194:197], v238 offset:1552
	ds_read_b128 v[198:201], v238 offset:528
	v_cndmask_b32_e64 v175, 0, v175, s[6:7]
	v_cndmask_b32_e64 v174, 0, v174, s[6:7]
	v_cndmask_b32_e64 v173, 0, v173, s[4:5]
	v_cndmask_b32_e64 v172, 0, v172, s[4:5]
	v_cndmask_b32_e64 v171, v171, 0, s[8:9]
	v_cndmask_b32_e64 v170, v170, 0, s[8:9]
	v_cndmask_b32_e64 v169, 0, v169, s[6:7]
	v_cndmask_b32_e64 v168, 0, v168, s[6:7]
	v_cndmask_b32_e64 v167, 0, v167, s[4:5]
	v_cndmask_b32_e64 v166, 0, v166, s[4:5]
	s_waitcnt lgkmcnt(0)
	v_pk_fma_f32 v[112:113], v[112:113], v[186:187], v[182:183]
	v_pk_fma_f32 v[114:115], v[114:115], v[188:189], v[184:185]
	v_pk_fma_f32 v[112:113], v[176:177], v[190:191], v[112:113]
	v_pk_fma_f32 v[114:115], v[170:171], v[192:193], v[114:115]
	v_pk_fma_f32 v[112:113], v[174:175], v[194:195], v[112:113]
	s_nop 0
	v_pk_fma_f32 v[112:113], v[172:173], v[198:199], v[112:113]
	v_pk_fma_f32 v[114:115], v[168:169], v[196:197], v[114:115]
	v_pk_fma_f32 v[114:115], v[166:167], v[200:201], v[114:115]
	v_pk_mul_f32 v[172:173], v[112:113], s[98:99] op_sel_hi:[1,0]
	v_exp_f32_e32 v172, v172
	v_exp_f32_e32 v173, v173
	s_nop 0
	v_pk_add_f32 v[172:173], v[172:173], 1.0 op_sel_hi:[1,0]
	v_rcp_f32_e32 v172, v172
	v_rcp_f32_e32 v173, v173
	s_nop 0
	v_pk_mul_f32 v[112:113], v[112:113], v[172:173]
	s_nop 0
	v_cvt_pk_bf16_f32 v112, v112, v113
	v_pk_mul_f32 v[166:167], v[114:115], s[98:99] op_sel_hi:[1,0]
	v_exp_f32_e32 v166, v166
	v_exp_f32_e32 v167, v167
	s_nop 0
	v_pk_add_f32 v[166:167], v[166:167], 1.0 op_sel_hi:[1,0]
	v_rcp_f32_e32 v166, v166
	v_rcp_f32_e32 v167, v167
	s_nop 0
	v_pk_mul_f32 v[114:115], v[114:115], v[166:167]
	s_nop 0
	v_cvt_pk_bf16_f32 v113, v114, v115
	global_store_dwordx2 v[150:151], v[112:113], off offset:264
.LBB0_191:
	s_or_b64 exec, exec, s[22:23]
	v_add_u32_e32 v112, 16, v161
	v_add_u32_e32 v113, s17, v112
	v_max_i32_e32 v114, 0, v113
	v_mul_hi_u32 v115, v114, s56
	v_lshrrev_b32_e32 v115, 11, v115
	v_cmp_lt_i32_e32 vcc, 2, v112
	v_mul_lo_u32 v112, v114, s51
	v_mul_u32_u24_e32 v115, 0x1010, v115
	v_add_lshl_u32 v136, v112, v164, 1
	v_add_u32_e32 v112, s38, v165
	v_sub_u32_e32 v115, v114, v115
	v_cmp_gt_i32_e64 s[4:5], s50, v113
	v_lshl_add_u32 v114, v112, 1, s53
	s_and_b64 s[2:3], vcc, s[4:5]
	v_cmp_eq_u32_e64 s[8:9], 0, v115
	v_cmp_lt_u32_e64 s[6:7], 1, v115
	v_cmp_lt_u32_e64 s[4:5], 2, v115
	v_add_u32_e32 v115, v114, v163
	ds_read_b64 v[112:113], v114 offset:1024
	v_add_u32_e32 v150, v114, v162
	ds_read_b64 v[178:179], v115 offset:512
	ds_read_b64 v[182:183], v150
	v_readlane_b32 s22, v237, 58
	v_readlane_b32 s23, v237, 59
	s_waitcnt lgkmcnt(0)
	v_lshlrev_b32_e32 v175, 16, v112
	v_and_b32_e32 v176, 0xffff0000, v112
	v_lshlrev_b32_e32 v169, 16, v113
	v_and_b32_e32 v170, 0xffff0000, v113
	v_lshlrev_b32_e32 v173, 16, v178
	v_and_b32_e32 v174, 0xffff0000, v178
	v_lshlrev_b32_e32 v167, 16, v179
	v_and_b32_e32 v168, 0xffff0000, v179
	v_lshlrev_b32_e32 v171, 16, v182
	v_and_b32_e32 v172, 0xffff0000, v182
	v_lshlrev_b32_e32 v151, 16, v183
	v_and_b32_e32 v166, 0xffff0000, v183
	v_mov_b32_dpp v175, v108 row_shr:1 row_mask:0xf bank_mask:0xf
	v_mov_b32_dpp v173, v108 row_shr:2 row_mask:0xf bank_mask:0xf
	v_mov_b32_dpp v171, v108 row_shr:3 row_mask:0xf bank_mask:0xf
	v_mov_b32_dpp v176, v109 row_shr:1 row_mask:0xf bank_mask:0xf
	v_mov_b32_dpp v174, v109 row_shr:2 row_mask:0xf bank_mask:0xf
	v_mov_b32_dpp v172, v109 row_shr:3 row_mask:0xf bank_mask:0xf
	v_mov_b32_dpp v169, v110 row_shr:1 row_mask:0xf bank_mask:0xf
	v_mov_b32_dpp v167, v110 row_shr:2 row_mask:0xf bank_mask:0xf
	v_mov_b32_dpp v151, v110 row_shr:3 row_mask:0xf bank_mask:0xf
	v_mov_b32_dpp v170, v111 row_shr:1 row_mask:0xf bank_mask:0xf
	v_mov_b32_dpp v168, v111 row_shr:2 row_mask:0xf bank_mask:0xf
	v_mov_b32_dpp v166, v111 row_shr:3 row_mask:0xf bank_mask:0xf
	v_lshl_add_u64 v[112:113], s[22:23], 0, v[136:137]
	s_and_saveexec_b64 s[22:23], s[2:3]
	s_cbranch_execz .LBB0_193
;     __device__ __forceinline__ void operator()(const f32x4 (&acc)[2][2][4][2], const Unit& u, int wr, int wc, int fr, int fq, LAS unsigned char* hb) const {
;     ...
;             for (int m = 0; m < 4; ++m) { asm volatile("" ::: "memory"); __builtin_amdgcn_sched_barrier(0);
;                 const int q = 8 * ai + 4 * wr + m, prev = q > 0 ? q - 1 : 0; const int lr = ai * HALF + wr * 64 + m * 16 + fr, R = R0 + lr;
;                 const int Rc = R < 0 ? 0 : R; const int b = Rc / LL, p = Rc - b * LL;
;                 const bool ok = (lr >= H && R < TT);
;                 const unsigned ooff = ((unsigned)Rc * (unsigned)LDP + (unsigned)(OFF_XBC + ch0)) * 2u;
; #pragma unroll
;                 for (int bn = 0; bn < 4; ++bn) { const int bj = bn >> 1, n = bn & 1; const int co = bj * HALF + 4 * n;
;                     const unsigned woff = (unsigned)(ch0 + co) * 4u;
;                     const f32x4 w0 = *(const f32x4*)((const char*)cw + woff), w1 = *(const f32x4*)((const char*)cw + woff + XBCW * 4), w2 = *(const f32x4*)((const char*)cw + woff + 2 * XBCW * 4), w3 = *(const f32x4*)((const char*)cw + woff + 3 * XBCW * 4), bs = *(const f32x4*)((const char*)cb + woff);
;                     const LAS unsigned char* hp = hb + (prev * H * NCH + chl + co) * 2;
;                     const u32x2 q1 = *(const LAS u32x2*)(hp + hr1 * NCH * 2), q2 = *(const LAS u32x2*)(hp + hr2 * NCH * 2), q3 = *(const LAS u32x2*)(hp + hr3 * NCH * 2);
;                     const float h1[4] = {__builtin_bit_cast(float, q1.x << 16), __builtin_bit_cast(float, q1.x & 0xffff0000u), __builtin_bit_cast(float, q1.y << 16), __builtin_bit_cast(float, q1.y & 0xffff0000u)};
;                     const float h2[4] = {__builtin_bit_cast(float, q2.x << 16), __builtin_bit_cast(float, q2.x & 0xffff0000u), __builtin_bit_cast(float, q2.y << 16), __builtin_bit_cast(float, q2.y & 0xffff0000u)};
;                     const float h3[4] = {__builtin_bit_cast(float, q3.x << 16), __builtin_bit_cast(float, q3.x & 0xffff0000u), __builtin_bit_cast(float, q3.y << 16), __builtin_bit_cast(float, q3.y & 0xffff0000u)};
;                     const f32x4 gv = acc[ai][bj][m][n];
;                     float o[4];
; #pragma unroll
;                     for (int j = 0; j < 4; ++j) { const float g = gv[j];
;                         float g1 = dpp_row_shr<1>(h1[j], g), g2 = dpp_row_shr<2>(h2[j], g), g3 = dpp_row_shr<3>(h3[j], g);
	ds_read_b128 v[182:185], v238 offset:4096
	ds_read_b128 v[186:189], v238 offset:3072
	v_cndmask_b32_e64 v177, v176, 0, s[8:9]
	ds_read_b128 v[190:193], v238 offset:2048
	v_cndmask_b32_e64 v176, v175, 0, s[8:9]
	ds_read_b128 v[194:197], v238 offset:1024
	ds_read_b128 v[198:201], v238
	v_cndmask_b32_e64 v175, 0, v174, s[6:7]
	v_cndmask_b32_e64 v174, 0, v173, s[6:7]
	v_cndmask_b32_e64 v173, 0, v172, s[4:5]
	v_cndmask_b32_e64 v172, 0, v171, s[4:5]
	v_cndmask_b32_e64 v171, v170, 0, s[8:9]
	v_cndmask_b32_e64 v170, v169, 0, s[8:9]
	v_cndmask_b32_e64 v169, 0, v168, s[6:7]
	v_cndmask_b32_e64 v168, 0, v167, s[6:7]
	v_cndmask_b32_e64 v167, 0, v166, s[4:5]
	v_cndmask_b32_e64 v166, 0, v151, s[4:5]
	s_waitcnt lgkmcnt(0)
	v_pk_fma_f32 v[108:109], v[108:109], v[186:187], v[182:183]
	v_pk_fma_f32 v[110:111], v[110:111], v[188:189], v[184:185]
	v_pk_fma_f32 v[108:109], v[176:177], v[190:191], v[108:109]
	v_pk_fma_f32 v[110:111], v[170:171], v[192:193], v[110:111]
	v_pk_fma_f32 v[108:109], v[174:175], v[194:195], v[108:109]
	s_nop 0
	v_pk_fma_f32 v[108:109], v[172:173], v[198:199], v[108:109]
	v_pk_fma_f32 v[110:111], v[168:169], v[196:197], v[110:111]
	v_pk_fma_f32 v[110:111], v[166:167], v[200:201], v[110:111]
	v_pk_mul_f32 v[172:173], v[108:109], s[98:99] op_sel_hi:[1,0]
	v_exp_f32_e32 v172, v172
	v_exp_f32_e32 v173, v173
	s_nop 0
	v_pk_add_f32 v[172:173], v[172:173], 1.0 op_sel_hi:[1,0]
	v_rcp_f32_e32 v172, v172
	v_rcp_f32_e32 v173, v173
	s_nop 0
	v_pk_mul_f32 v[108:109], v[108:109], v[172:173]
	s_nop 0
	v_cvt_pk_bf16_f32 v108, v108, v109
	v_pk_mul_f32 v[166:167], v[110:111], s[98:99] op_sel_hi:[1,0]
	v_exp_f32_e32 v166, v166
	v_exp_f32_e32 v167, v167
	s_nop 0
	v_pk_add_f32 v[166:167], v[166:167], 1.0 op_sel_hi:[1,0]
	v_rcp_f32_e32 v166, v166
	v_rcp_f32_e32 v167, v167
	s_nop 0
	v_pk_mul_f32 v[110:111], v[110:111], v[166:167]
	s_nop 0
	v_cvt_pk_bf16_f32 v109, v110, v111
	global_store_dwordx2 v[112:113], v[108:109], off
.LBB0_193:
	s_or_b64 exec, exec, s[22:23]
	ds_read_b64 v[108:109], v114 offset:1032
	ds_read_b64 v[110:111], v115 offset:520
	ds_read_b64 v[172:173], v150 offset:8
	s_waitcnt lgkmcnt(0)
	v_lshlrev_b32_e32 v170, 16, v108
	v_and_b32_e32 v171, 0xffff0000, v108
	v_lshlrev_b32_e32 v136, 16, v109
	v_and_b32_e32 v151, 0xffff0000, v109
	v_lshlrev_b32_e32 v168, 16, v110
	v_and_b32_e32 v169, 0xffff0000, v110
	v_lshlrev_b32_e32 v110, 16, v111
	v_and_b32_e32 v111, 0xffff0000, v111
	v_lshlrev_b32_e32 v166, 16, v172
	v_and_b32_e32 v167, 0xffff0000, v172
	v_lshlrev_b32_e32 v108, 16, v173
	v_and_b32_e32 v109, 0xffff0000, v173
	v_mov_b32_dpp v170, v104 row_shr:1 row_mask:0xf bank_mask:0xf
	v_mov_b32_dpp v168, v104 row_shr:2 row_mask:0xf bank_mask:0xf
	v_mov_b32_dpp v166, v104 row_shr:3 row_mask:0xf bank_mask:0xf
	v_mov_b32_dpp v171, v105 row_shr:1 row_mask:0xf bank_mask:0xf
	v_mov_b32_dpp v169, v105 row_shr:2 row_mask:0xf bank_mask:0xf
	v_mov_b32_dpp v167, v105 row_shr:3 row_mask:0xf bank_mask:0xf
	v_mov_b32_dpp v136, v106 row_shr:1 row_mask:0xf bank_mask:0xf
	v_mov_b32_dpp v110, v106 row_shr:2 row_mask:0xf bank_mask:0xf
	v_mov_b32_dpp v108, v106 row_shr:3 row_mask:0xf bank_mask:0xf
	v_mov_b32_dpp v151, v107 row_shr:1 row_mask:0xf bank_mask:0xf
	v_mov_b32_dpp v111, v107 row_shr:2 row_mask:0xf bank_mask:0xf
	v_mov_b32_dpp v109, v107 row_shr:3 row_mask:0xf bank_mask:0xf
	s_and_saveexec_b64 s[22:23], s[2:3]
	s_cbranch_execz .LBB0_195
	ds_read_b128 v[172:175], v238 offset:4112
	ds_read_b128 v[176:179], v238 offset:3088
	ds_read_b128 v[182:185], v238 offset:2064
	v_cndmask_b32_e64 v171, v171, 0, s[8:9]
	ds_read_b128 v[186:189], v238 offset:1040
	s_nop 0
	ds_read_b128 v[190:193], v238 offset:16
	v_cndmask_b32_e64 v170, v170, 0, s[8:9]
	v_cndmask_b32_e64 v169, 0, v169, s[6:7]
	v_cndmask_b32_e64 v168, 0, v168, s[6:7]
	v_cndmask_b32_e64 v167, 0, v167, s[4:5]
	v_cndmask_b32_e64 v166, 0, v166, s[4:5]
	v_cndmask_b32_e64 v111, 0, v111, s[6:7]
	v_cndmask_b32_e64 v110, 0, v110, s[6:7]
	v_cndmask_b32_e64 v109, 0, v109, s[4:5]
	v_cndmask_b32_e64 v108, 0, v108, s[4:5]
	s_waitcnt lgkmcnt(0)
	v_pk_fma_f32 v[104:105], v[104:105], v[176:177], v[172:173]
	v_pk_fma_f32 v[106:107], v[106:107], v[178:179], v[174:175]
	v_pk_fma_f32 v[104:105], v[170:171], v[182:183], v[104:105]
	s_nop 0
	v_pk_fma_f32 v[104:105], v[168:169], v[186:187], v[104:105]
	s_nop 0
	v_pk_fma_f32 v[104:105], v[166:167], v[190:191], v[104:105]
	s_nop 0
	v_pk_mul_f32 v[166:167], v[104:105], s[98:99] op_sel_hi:[1,0]
	v_exp_f32_e32 v166, v166
	v_exp_f32_e32 v167, v167
	s_nop 0
	v_pk_add_f32 v[166:167], v[166:167], 1.0 op_sel_hi:[1,0]
	v_rcp_f32_e32 v166, v166
	v_rcp_f32_e32 v167, v167
	s_nop 0
	v_pk_mul_f32 v[104:105], v[104:105], v[166:167]
	v_cndmask_b32_e64 v167, v151, 0, s[8:9]
	v_cndmask_b32_e64 v166, v136, 0, s[8:9]
	v_pk_fma_f32 v[106:107], v[166:167], v[184:185], v[106:107]
	v_cvt_pk_bf16_f32 v104, v104, v105
	v_pk_fma_f32 v[106:107], v[110:111], v[188:189], v[106:107]
	s_nop 0
	v_pk_fma_f32 v[106:107], v[108:109], v[192:193], v[106:107]
	s_nop 0
	v_pk_mul_f32 v[108:109], v[106:107], s[98:99] op_sel_hi:[1,0]
	v_exp_f32_e32 v108, v108
	v_exp_f32_e32 v109, v109
	s_nop 0
	v_pk_add_f32 v[108:109], v[108:109], 1.0 op_sel_hi:[1,0]
	v_rcp_f32_e32 v108, v108
	v_rcp_f32_e32 v109, v109
	s_nop 0
	v_pk_mul_f32 v[106:107], v[106:107], v[108:109]
	s_nop 0
	v_cvt_pk_bf16_f32 v105, v106, v107
	global_store_dwordx2 v[112:113], v[104:105], off offset:8
;     __device__ __forceinline__ void operator()(const f32x4 (&acc)[2][2][4][2], const Unit& u, int wr, int wc, int fr, int fq, LAS unsigned char* hb) const {
;     ...
;             for (int m = 0; m < 4; ++m) { asm volatile("" ::: "memory"); __builtin_amdgcn_sched_barrier(0);
;                 const int q = 8 * ai + 4 * wr + m, prev = q > 0 ? q - 1 : 0; const int lr = ai * HALF + wr * 64 + m * 16 + fr, R = R0 + lr;
;                 const int Rc = R < 0 ? 0 : R; const int b = Rc / LL, p = Rc - b * LL;
;                 const bool ok = (lr >= H && R < TT);
;                 const unsigned ooff = ((unsigned)Rc * (unsigned)LDP + (unsigned)(OFF_XBC + ch0)) * 2u;
; #pragma unroll
;                 for (int bn = 0; bn < 4; ++bn) { const int bj = bn >> 1, n = bn & 1; const int co = bj * HALF + 4 * n;
;                     const unsigned woff = (unsigned)(ch0 + co) * 4u;
;                     const f32x4 w0 = *(const f32x4*)((const char*)cw + woff), w1 = *(const f32x4*)((const char*)cw + woff + XBCW * 4), w2 = *(const f32x4*)((const char*)cw + woff + 2 * XBCW * 4), w3 = *(const f32x4*)((const char*)cw + woff + 3 * XBCW * 4), bs = *(const f32x4*)((const char*)cb + woff);
;                     const LAS unsigned char* hp = hb + (prev * H * NCH + chl + co) * 2;
;                     const u32x2 q1 = *(const LAS u32x2*)(hp + hr1 * NCH * 2), q2 = *(const LAS u32x2*)(hp + hr2 * NCH * 2), q3 = *(const LAS u32x2*)(hp + hr3 * NCH * 2);
;                     const float h1[4] = {__builtin_bit_cast(float, q1.x << 16), __builtin_bit_cast(float, q1.x & 0xffff0000u), __builtin_bit_cast(float, q1.y << 16), __builtin_bit_cast(float, q1.y & 0xffff0000u)};
;                     const float h2[4] = {__builtin_bit_cast(float, q2.x << 16), __builtin_bit_cast(float, q2.x & 0xffff0000u), __builtin_bit_cast(float, q2.y << 16), __builtin_bit_cast(float, q2.y & 0xffff0000u)};
;                     const float h3[4] = {__builtin_bit_cast(float, q3.x << 16), __builtin_bit_cast(float, q3.x & 0xffff0000u), __builtin_bit_cast(float, q3.y << 16), __builtin_bit_cast(float, q3.y & 0xffff0000u)};
;                     const f32x4 gv = acc[ai][bj][m][n];
;                     float o[4];
; #pragma unroll
;                     for (int j = 0; j < 4; ++j) { const float g = gv[j];
;                         float g1 = dpp_row_shr<1>(h1[j], g), g2 = dpp_row_shr<2>(h2[j], g), g3 = dpp_row_shr<3>(h3[j], g);
.LBB0_195:
	s_or_b64 exec, exec, s[22:23]
	ds_read_b64 v[104:105], v114 offset:1280
	ds_read_b64 v[106:107], v115 offset:768
	ds_read_b64 v[168:169], v150 offset:256
	s_waitcnt lgkmcnt(0)
	v_lshlrev_b32_e32 v166, 16, v104
	v_and_b32_e32 v167, 0xffff0000, v104
	v_lshlrev_b32_e32 v108, 16, v105
	v_and_b32_e32 v109, 0xffff0000, v105
	v_lshlrev_b32_e32 v136, 16, v106
	v_and_b32_e32 v151, 0xffff0000, v106
	v_lshlrev_b32_e32 v106, 16, v107
	v_and_b32_e32 v107, 0xffff0000, v107
	v_lshlrev_b32_e32 v110, 16, v168
	v_and_b32_e32 v111, 0xffff0000, v168
	v_lshlrev_b32_e32 v104, 16, v169
	v_and_b32_e32 v105, 0xffff0000, v169
	v_mov_b32_dpp v166, v100 row_shr:1 row_mask:0xf bank_mask:0xf
	v_mov_b32_dpp v136, v100 row_shr:2 row_mask:0xf bank_mask:0xf
	v_mov_b32_dpp v110, v100 row_shr:3 row_mask:0xf bank_mask:0xf
	v_mov_b32_dpp v167, v101 row_shr:1 row_mask:0xf bank_mask:0xf
	v_mov_b32_dpp v151, v101 row_shr:2 row_mask:0xf bank_mask:0xf
	v_mov_b32_dpp v111, v101 row_shr:3 row_mask:0xf bank_mask:0xf
	v_mov_b32_dpp v108, v102 row_shr:1 row_mask:0xf bank_mask:0xf
	v_mov_b32_dpp v106, v102 row_shr:2 row_mask:0xf bank_mask:0xf
	v_mov_b32_dpp v104, v102 row_shr:3 row_mask:0xf bank_mask:0xf
	v_mov_b32_dpp v109, v103 row_shr:1 row_mask:0xf bank_mask:0xf
	v_mov_b32_dpp v107, v103 row_shr:2 row_mask:0xf bank_mask:0xf
	v_mov_b32_dpp v105, v103 row_shr:3 row_mask:0xf bank_mask:0xf
	s_and_saveexec_b64 s[22:23], s[2:3]
	s_cbranch_execz .LBB0_197
	ds_read_b128 v[168:171], v238 offset:4608
	ds_read_b128 v[172:175], v238 offset:3584
	ds_read_b128 v[176:179], v238 offset:2560
	v_cndmask_b32_e64 v167, v167, 0, s[8:9]
	ds_read_b128 v[182:185], v238 offset:1536
	s_nop 0
	ds_read_b128 v[186:189], v238 offset:512
	v_cndmask_b32_e64 v166, v166, 0, s[8:9]
	v_cndmask_b32_e64 v111, 0, v111, s[4:5]
	v_cndmask_b32_e64 v110, 0, v110, s[4:5]
	v_cndmask_b32_e64 v109, v109, 0, s[8:9]
	v_cndmask_b32_e64 v108, v108, 0, s[8:9]
	v_cndmask_b32_e64 v107, 0, v107, s[6:7]
	v_cndmask_b32_e64 v106, 0, v106, s[6:7]
	v_cndmask_b32_e64 v105, 0, v105, s[4:5]
	v_cndmask_b32_e64 v104, 0, v104, s[4:5]
	s_waitcnt lgkmcnt(0)
	v_pk_fma_f32 v[100:101], v[100:101], v[172:173], v[168:169]
	v_pk_fma_f32 v[102:103], v[102:103], v[174:175], v[170:171]
	v_pk_fma_f32 v[100:101], v[166:167], v[176:177], v[100:101]
	v_cndmask_b32_e64 v167, 0, v151, s[6:7]
	v_cndmask_b32_e64 v166, 0, v136, s[6:7]
	v_pk_fma_f32 v[102:103], v[108:109], v[178:179], v[102:103]
	v_pk_fma_f32 v[100:101], v[166:167], v[182:183], v[100:101]
	s_nop 0
	v_pk_fma_f32 v[100:101], v[110:111], v[186:187], v[100:101]
	v_pk_fma_f32 v[102:103], v[106:107], v[184:185], v[102:103]
	v_pk_fma_f32 v[102:103], v[104:105], v[188:189], v[102:103]
	v_pk_mul_f32 v[110:111], v[100:101], s[98:99] op_sel_hi:[1,0]
	v_exp_f32_e32 v110, v110
	v_exp_f32_e32 v111, v111
	s_nop 0
	v_pk_add_f32 v[110:111], v[110:111], 1.0 op_sel_hi:[1,0]
	v_rcp_f32_e32 v110, v110
	v_rcp_f32_e32 v111, v111
	s_nop 0
	v_pk_mul_f32 v[100:101], v[100:101], v[110:111]
	s_nop 0
	v_cvt_pk_bf16_f32 v100, v100, v101
	v_pk_mul_f32 v[104:105], v[102:103], s[98:99] op_sel_hi:[1,0]
	v_exp_f32_e32 v104, v104
	v_exp_f32_e32 v105, v105
	s_nop 0
	v_pk_add_f32 v[104:105], v[104:105], 1.0 op_sel_hi:[1,0]
	v_rcp_f32_e32 v104, v104
	v_rcp_f32_e32 v105, v105
	s_nop 0
	v_pk_mul_f32 v[102:103], v[102:103], v[104:105]
	s_nop 0
	v_cvt_pk_bf16_f32 v101, v102, v103
	global_store_dwordx2 v[112:113], v[100:101], off offset:256
.LBB0_197:
	s_or_b64 exec, exec, s[22:23]
	ds_read_b64 v[100:101], v114 offset:1288
	ds_read_b64 v[102:103], v115 offset:776
	ds_read_b64 v[114:115], v150 offset:264
	s_waitcnt lgkmcnt(0)
	v_lshlrev_b32_e32 v110, 16, v100
	v_and_b32_e32 v111, 0xffff0000, v100
	v_lshlrev_b32_e32 v104, 16, v101
	v_and_b32_e32 v105, 0xffff0000, v101
	v_lshlrev_b32_e32 v108, 16, v102
	v_and_b32_e32 v109, 0xffff0000, v102
	v_lshlrev_b32_e32 v102, 16, v103
	v_and_b32_e32 v103, 0xffff0000, v103
	v_lshlrev_b32_e32 v106, 16, v114
	v_and_b32_e32 v107, 0xffff0000, v114
	v_lshlrev_b32_e32 v100, 16, v115
	v_and_b32_e32 v101, 0xffff0000, v115
	v_mov_b32_dpp v110, v96 row_shr:1 row_mask:0xf bank_mask:0xf
	v_mov_b32_dpp v108, v96 row_shr:2 row_mask:0xf bank_mask:0xf
	v_mov_b32_dpp v106, v96 row_shr:3 row_mask:0xf bank_mask:0xf
	v_mov_b32_dpp v111, v97 row_shr:1 row_mask:0xf bank_mask:0xf
	v_mov_b32_dpp v109, v97 row_shr:2 row_mask:0xf bank_mask:0xf
	v_mov_b32_dpp v107, v97 row_shr:3 row_mask:0xf bank_mask:0xf
	v_mov_b32_dpp v104, v98 row_shr:1 row_mask:0xf bank_mask:0xf
	v_mov_b32_dpp v102, v98 row_shr:2 row_mask:0xf bank_mask:0xf
	v_mov_b32_dpp v100, v98 row_shr:3 row_mask:0xf bank_mask:0xf
	v_mov_b32_dpp v105, v99 row_shr:1 row_mask:0xf bank_mask:0xf
	v_mov_b32_dpp v103, v99 row_shr:2 row_mask:0xf bank_mask:0xf
	v_mov_b32_dpp v101, v99 row_shr:3 row_mask:0xf bank_mask:0xf
	s_and_saveexec_b64 s[22:23], s[2:3]
	s_cbranch_execz .LBB0_199
	ds_read_b128 v[166:169], v238 offset:4624
	ds_read_b128 v[170:173], v238 offset:3600
	v_cndmask_b32_e64 v111, v111, 0, s[8:9]
	ds_read_b128 v[174:177], v238 offset:2576
	v_cndmask_b32_e64 v110, v110, 0, s[8:9]
	ds_read_b128 v[182:185], v238 offset:1552
	ds_read_b128 v[186:189], v238 offset:528
	v_cndmask_b32_e64 v109, 0, v109, s[6:7]
	v_cndmask_b32_e64 v108, 0, v108, s[6:7]
	v_cndmask_b32_e64 v107, 0, v107, s[4:5]
	v_cndmask_b32_e64 v106, 0, v106, s[4:5]
	v_cndmask_b32_e64 v105, v105, 0, s[8:9]
	v_cndmask_b32_e64 v104, v104, 0, s[8:9]
	v_cndmask_b32_e64 v103, 0, v103, s[6:7]
	v_cndmask_b32_e64 v102, 0, v102, s[6:7]
	v_cndmask_b32_e64 v101, 0, v101, s[4:5]
	v_cndmask_b32_e64 v100, 0, v100, s[4:5]
	s_waitcnt lgkmcnt(0)
	v_pk_fma_f32 v[96:97], v[96:97], v[170:171], v[166:167]
	v_pk_fma_f32 v[98:99], v[98:99], v[172:173], v[168:169]
	v_pk_fma_f32 v[96:97], v[110:111], v[174:175], v[96:97]
	v_pk_fma_f32 v[98:99], v[104:105], v[176:177], v[98:99]
	v_pk_fma_f32 v[96:97], v[108:109], v[182:183], v[96:97]
	s_nop 0
	v_pk_fma_f32 v[96:97], v[106:107], v[186:187], v[96:97]
	v_pk_fma_f32 v[98:99], v[102:103], v[184:185], v[98:99]
	v_pk_fma_f32 v[98:99], v[100:101], v[188:189], v[98:99]
	v_pk_mul_f32 v[106:107], v[96:97], s[98:99] op_sel_hi:[1,0]
	v_exp_f32_e32 v106, v106
	v_exp_f32_e32 v107, v107
	s_nop 0
	v_pk_add_f32 v[106:107], v[106:107], 1.0 op_sel_hi:[1,0]
	v_rcp_f32_e32 v106, v106
	v_rcp_f32_e32 v107, v107
	s_nop 0
	v_pk_mul_f32 v[96:97], v[96:97], v[106:107]
	s_nop 0
	v_cvt_pk_bf16_f32 v96, v96, v97
	v_pk_mul_f32 v[100:101], v[98:99], s[98:99] op_sel_hi:[1,0]
	v_exp_f32_e32 v100, v100
	v_exp_f32_e32 v101, v101
	s_nop 0
	v_pk_add_f32 v[100:101], v[100:101], 1.0 op_sel_hi:[1,0]
	v_rcp_f32_e32 v100, v100
	v_rcp_f32_e32 v101, v101
	s_nop 0
	v_pk_mul_f32 v[98:99], v[98:99], v[100:101]
	s_nop 0
	v_cvt_pk_bf16_f32 v97, v98, v99
	global_store_dwordx2 v[112:113], v[96:97], off offset:264
;     __device__ __forceinline__ void operator()(const f32x4 (&acc)[2][2][4][2], const Unit& u, int wr, int wc, int fr, int fq, LAS unsigned char* hb) const {
;     ...
;             for (int m = 0; m < 4; ++m) { asm volatile("" ::: "memory"); __builtin_amdgcn_sched_barrier(0);
;                 const int q = 8 * ai + 4 * wr + m, prev = q > 0 ? q - 1 : 0; const int lr = ai * HALF + wr * 64 + m * 16 + fr, R = R0 + lr;
;                 const int Rc = R < 0 ? 0 : R; const int b = Rc / LL, p = Rc - b * LL;
;                 const bool ok = (lr >= H && R < TT);
;                 const unsigned ooff = ((unsigned)Rc * (unsigned)LDP + (unsigned)(OFF_XBC + ch0)) * 2u;
; #pragma unroll
;                 for (int bn = 0; bn < 4; ++bn) { const int bj = bn >> 1, n = bn & 1; const int co = bj * HALF + 4 * n;
;                     const unsigned woff = (unsigned)(ch0 + co) * 4u;
;                     const f32x4 w0 = *(const f32x4*)((const char*)cw + woff), w1 = *(const f32x4*)((const char*)cw + woff + XBCW * 4), w2 = *(const f32x4*)((const char*)cw + woff + 2 * XBCW * 4), w3 = *(const f32x4*)((const char*)cw + woff + 3 * XBCW * 4), bs = *(const f32x4*)((const char*)cb + woff);
;                     const LAS unsigned char* hp = hb + (prev * H * NCH + chl + co) * 2;
;                     const u32x2 q1 = *(const LAS u32x2*)(hp + hr1 * NCH * 2), q2 = *(const LAS u32x2*)(hp + hr2 * NCH * 2), q3 = *(const LAS u32x2*)(hp + hr3 * NCH * 2);
;                     const float h1[4] = {__builtin_bit_cast(float, q1.x << 16), __builtin_bit_cast(float, q1.x & 0xffff0000u), __builtin_bit_cast(float, q1.y << 16), __builtin_bit_cast(float, q1.y & 0xffff0000u)};
;                     const float h2[4] = {__builtin_bit_cast(float, q2.x << 16), __builtin_bit_cast(float, q2.x & 0xffff0000u), __builtin_bit_cast(float, q2.y << 16), __builtin_bit_cast(float, q2.y & 0xffff0000u)};
;                     const float h3[4] = {__builtin_bit_cast(float, q3.x << 16), __builtin_bit_cast(float, q3.x & 0xffff0000u), __builtin_bit_cast(float, q3.y << 16), __builtin_bit_cast(float, q3.y & 0xffff0000u)};
;                     const f32x4 gv = acc[ai][bj][m][n];
;                     float o[4];
; #pragma unroll
;                     for (int j = 0; j < 4; ++j) { const float g = gv[j];
;                         float g1 = dpp_row_shr<1>(h1[j], g), g2 = dpp_row_shr<2>(h2[j], g), g3 = dpp_row_shr<3>(h3[j], g);
.LBB0_199:
	s_or_b64 exec, exec, s[22:23]
	v_add_u32_e32 v96, 32, v161
	v_add_u32_e32 v97, s17, v96
	v_max_i32_e32 v98, 0, v97
	v_mul_hi_u32 v99, v98, s56
	v_lshrrev_b32_e32 v99, 11, v99
	v_cmp_lt_i32_e32 vcc, 2, v96
	v_mul_lo_u32 v96, v98, s51
	v_mul_u32_u24_e32 v99, 0x1010, v99
	v_add_lshl_u32 v136, v96, v164, 1
	v_add_u32_e32 v96, s39, v165
	v_sub_u32_e32 v99, v98, v99
	v_cmp_gt_i32_e64 s[4:5], s50, v97
	v_lshl_add_u32 v98, v96, 1, s53
	s_and_b64 s[2:3], vcc, s[4:5]
	v_cmp_eq_u32_e64 s[8:9], 0, v99
	v_cmp_lt_u32_e64 s[6:7], 1, v99
	v_cmp_lt_u32_e64 s[4:5], 2, v99
	v_add_u32_e32 v99, v98, v163
	ds_read_b64 v[96:97], v98 offset:1024
	v_add_u32_e32 v100, v98, v162
	ds_read_b64 v[114:115], v99 offset:512
	ds_read_b64 v[150:151], v100
	v_readlane_b32 s22, v237, 58
	v_readlane_b32 s23, v237, 59
	s_waitcnt lgkmcnt(0)
	v_lshlrev_b32_e32 v111, 16, v96
	v_and_b32_e32 v112, 0xffff0000, v96
	v_lshlrev_b32_e32 v105, 16, v97
	v_and_b32_e32 v106, 0xffff0000, v97
	v_lshlrev_b32_e32 v109, 16, v114
	v_and_b32_e32 v110, 0xffff0000, v114
	v_lshlrev_b32_e32 v103, 16, v115
	v_and_b32_e32 v104, 0xffff0000, v115
	v_lshlrev_b32_e32 v107, 16, v150
	v_and_b32_e32 v108, 0xffff0000, v150
	v_lshlrev_b32_e32 v101, 16, v151
	v_and_b32_e32 v102, 0xffff0000, v151
	v_mov_b32_dpp v111, v92 row_shr:1 row_mask:0xf bank_mask:0xf
	v_mov_b32_dpp v109, v92 row_shr:2 row_mask:0xf bank_mask:0xf
	v_mov_b32_dpp v107, v92 row_shr:3 row_mask:0xf bank_mask:0xf
	v_mov_b32_dpp v112, v93 row_shr:1 row_mask:0xf bank_mask:0xf
	v_mov_b32_dpp v110, v93 row_shr:2 row_mask:0xf bank_mask:0xf
	v_mov_b32_dpp v108, v93 row_shr:3 row_mask:0xf bank_mask:0xf
	v_mov_b32_dpp v105, v94 row_shr:1 row_mask:0xf bank_mask:0xf
	v_mov_b32_dpp v103, v94 row_shr:2 row_mask:0xf bank_mask:0xf
	v_mov_b32_dpp v101, v94 row_shr:3 row_mask:0xf bank_mask:0xf
	v_mov_b32_dpp v106, v95 row_shr:1 row_mask:0xf bank_mask:0xf
	v_mov_b32_dpp v104, v95 row_shr:2 row_mask:0xf bank_mask:0xf
	v_mov_b32_dpp v102, v95 row_shr:3 row_mask:0xf bank_mask:0xf
	v_lshl_add_u64 v[96:97], s[22:23], 0, v[136:137]
	s_and_saveexec_b64 s[22:23], s[2:3]
	s_cbranch_execz .LBB0_201
	ds_read_b128 v[166:169], v238 offset:4096
	ds_read_b128 v[170:173], v238 offset:3072
	v_cndmask_b32_e64 v113, v112, 0, s[8:9]
	ds_read_b128 v[174:177], v238 offset:2048
	v_cndmask_b32_e64 v112, v111, 0, s[8:9]
	ds_read_b128 v[182:185], v238 offset:1024
	ds_read_b128 v[186:189], v238
	v_cndmask_b32_e64 v111, 0, v110, s[6:7]
	v_cndmask_b32_e64 v110, 0, v109, s[6:7]
	v_cndmask_b32_e64 v109, 0, v108, s[4:5]
	v_cndmask_b32_e64 v108, 0, v107, s[4:5]
	s_waitcnt lgkmcnt(0)
	v_pk_fma_f32 v[92:93], v[92:93], v[170:171], v[166:167]
	v_pk_fma_f32 v[94:95], v[94:95], v[172:173], v[168:169]
	v_pk_fma_f32 v[92:93], v[112:113], v[174:175], v[92:93]
	s_nop 0
	v_pk_fma_f32 v[92:93], v[110:111], v[182:183], v[92:93]
	s_nop 0
	v_pk_fma_f32 v[92:93], v[108:109], v[186:187], v[92:93]
	s_nop 0
	v_pk_mul_f32 v[108:109], v[92:93], s[98:99] op_sel_hi:[1,0]
	v_exp_f32_e32 v108, v108
	v_exp_f32_e32 v109, v109
	s_nop 0
	v_pk_add_f32 v[108:109], v[108:109], 1.0 op_sel_hi:[1,0]
	v_rcp_f32_e32 v108, v108
	v_rcp_f32_e32 v109, v109
	v_cndmask_b32_e64 v107, v106, 0, s[8:9]
	v_cndmask_b32_e64 v106, v105, 0, s[8:9]
	v_pk_fma_f32 v[94:95], v[106:107], v[176:177], v[94:95]
	v_cndmask_b32_e64 v105, 0, v104, s[6:7]
	v_cndmask_b32_e64 v104, 0, v103, s[6:7]
	v_pk_fma_f32 v[94:95], v[104:105], v[184:185], v[94:95]
	v_cndmask_b32_e64 v103, 0, v102, s[4:5]
	v_cndmask_b32_e64 v102, 0, v101, s[4:5]
	v_pk_mul_f32 v[92:93], v[92:93], v[108:109]
	v_pk_fma_f32 v[94:95], v[102:103], v[188:189], v[94:95]
	v_cvt_pk_bf16_f32 v92, v92, v93
	v_pk_mul_f32 v[102:103], v[94:95], s[98:99] op_sel_hi:[1,0]
	v_exp_f32_e32 v102, v102
	v_exp_f32_e32 v103, v103
	s_nop 0
	v_pk_add_f32 v[102:103], v[102:103], 1.0 op_sel_hi:[1,0]
	v_rcp_f32_e32 v102, v102
	v_rcp_f32_e32 v103, v103
	s_nop 0
	v_pk_mul_f32 v[94:95], v[94:95], v[102:103]
	s_nop 0
	v_cvt_pk_bf16_f32 v93, v94, v95
	global_store_dwordx2 v[96:97], v[92:93], off
.LBB0_201:
	s_or_b64 exec, exec, s[22:23]
	ds_read_b64 v[92:93], v98 offset:1032
	ds_read_b64 v[94:95], v99 offset:520
	ds_read_b64 v[110:111], v100 offset:8
	s_waitcnt lgkmcnt(0)
	v_lshlrev_b32_e32 v107, 16, v92
	v_and_b32_e32 v108, 0xffff0000, v92
	v_lshlrev_b32_e32 v101, 16, v93
	v_and_b32_e32 v102, 0xffff0000, v93
	v_lshlrev_b32_e32 v105, 16, v94
	v_and_b32_e32 v106, 0xffff0000, v94
	v_lshlrev_b32_e32 v94, 16, v95
	v_and_b32_e32 v95, 0xffff0000, v95
	v_lshlrev_b32_e32 v103, 16, v110
	v_and_b32_e32 v104, 0xffff0000, v110
	v_lshlrev_b32_e32 v92, 16, v111
	v_and_b32_e32 v93, 0xffff0000, v111
	v_mov_b32_dpp v107, v88 row_shr:1 row_mask:0xf bank_mask:0xf
	v_mov_b32_dpp v105, v88 row_shr:2 row_mask:0xf bank_mask:0xf
	v_mov_b32_dpp v103, v88 row_shr:3 row_mask:0xf bank_mask:0xf
	v_mov_b32_dpp v108, v89 row_shr:1 row_mask:0xf bank_mask:0xf
	v_mov_b32_dpp v106, v89 row_shr:2 row_mask:0xf bank_mask:0xf
	v_mov_b32_dpp v104, v89 row_shr:3 row_mask:0xf bank_mask:0xf
	v_mov_b32_dpp v101, v90 row_shr:1 row_mask:0xf bank_mask:0xf
	v_mov_b32_dpp v94, v90 row_shr:2 row_mask:0xf bank_mask:0xf
	v_mov_b32_dpp v92, v90 row_shr:3 row_mask:0xf bank_mask:0xf
	v_mov_b32_dpp v102, v91 row_shr:1 row_mask:0xf bank_mask:0xf
	v_mov_b32_dpp v95, v91 row_shr:2 row_mask:0xf bank_mask:0xf
	v_mov_b32_dpp v93, v91 row_shr:3 row_mask:0xf bank_mask:0xf
	s_and_saveexec_b64 s[22:23], s[2:3]
	s_cbranch_execz .LBB0_203
;     __device__ __forceinline__ void operator()(const f32x4 (&acc)[2][2][4][2], const Unit& u, int wr, int wc, int fr, int fq, LAS unsigned char* hb) const {
;     ...
;             for (int m = 0; m < 4; ++m) { asm volatile("" ::: "memory"); __builtin_amdgcn_sched_barrier(0);
;                 const int q = 8 * ai + 4 * wr + m, prev = q > 0 ? q - 1 : 0; const int lr = ai * HALF + wr * 64 + m * 16 + fr, R = R0 + lr;
;                 const int Rc = R < 0 ? 0 : R; const int b = Rc / LL, p = Rc - b * LL;
;                 const bool ok = (lr >= H && R < TT);
;                 const unsigned ooff = ((unsigned)Rc * (unsigned)LDP + (unsigned)(OFF_XBC + ch0)) * 2u;
; #pragma unroll
;                 for (int bn = 0; bn < 4; ++bn) { const int bj = bn >> 1, n = bn & 1; const int co = bj * HALF + 4 * n;
;                     const unsigned woff = (unsigned)(ch0 + co) * 4u;
;                     const f32x4 w0 = *(const f32x4*)((const char*)cw + woff), w1 = *(const f32x4*)((const char*)cw + woff + XBCW * 4), w2 = *(const f32x4*)((const char*)cw + woff + 2 * XBCW * 4), w3 = *(const f32x4*)((const char*)cw + woff + 3 * XBCW * 4), bs = *(const f32x4*)((const char*)cb + woff);
;                     const LAS unsigned char* hp = hb + (prev * H * NCH + chl + co) * 2;
;                     const u32x2 q1 = *(const LAS u32x2*)(hp + hr1 * NCH * 2), q2 = *(const LAS u32x2*)(hp + hr2 * NCH * 2), q3 = *(const LAS u32x2*)(hp + hr3 * NCH * 2);
;                     const float h1[4] = {__builtin_bit_cast(float, q1.x << 16), __builtin_bit_cast(float, q1.x & 0xffff0000u), __builtin_bit_cast(float, q1.y << 16), __builtin_bit_cast(float, q1.y & 0xffff0000u)};
;                     const float h2[4] = {__builtin_bit_cast(float, q2.x << 16), __builtin_bit_cast(float, q2.x & 0xffff0000u), __builtin_bit_cast(float, q2.y << 16), __builtin_bit_cast(float, q2.y & 0xffff0000u)};
;                     const float h3[4] = {__builtin_bit_cast(float, q3.x << 16), __builtin_bit_cast(float, q3.x & 0xffff0000u), __builtin_bit_cast(float, q3.y << 16), __builtin_bit_cast(float, q3.y & 0xffff0000u)};
;                     const f32x4 gv = acc[ai][bj][m][n];
;                     float o[4];
; #pragma unroll
;                     for (int j = 0; j < 4; ++j) { const float g = gv[j];
;                         float g1 = dpp_row_shr<1>(h1[j], g), g2 = dpp_row_shr<2>(h2[j], g), g3 = dpp_row_shr<3>(h3[j], g);
	ds_read_b128 v[110:113], v238 offset:4112
	ds_read_b128 v[166:169], v238 offset:3088
	v_cndmask_b32_e64 v109, v108, 0, s[8:9]
	ds_read_b128 v[170:173], v238 offset:2064
	v_cndmask_b32_e64 v108, v107, 0, s[8:9]
	ds_read_b128 v[174:177], v238 offset:1040
	ds_read_b128 v[182:185], v238 offset:16
	v_cndmask_b32_e64 v107, 0, v106, s[6:7]
	v_cndmask_b32_e64 v106, 0, v105, s[6:7]
	v_cndmask_b32_e64 v105, 0, v104, s[4:5]
	v_cndmask_b32_e64 v104, 0, v103, s[4:5]
	v_cndmask_b32_e64 v95, 0, v95, s[6:7]
	v_cndmask_b32_e64 v94, 0, v94, s[6:7]
	v_cndmask_b32_e64 v93, 0, v93, s[4:5]
	v_cndmask_b32_e64 v92, 0, v92, s[4:5]
	s_waitcnt lgkmcnt(0)
	v_pk_fma_f32 v[88:89], v[88:89], v[166:167], v[110:111]
	v_pk_fma_f32 v[90:91], v[90:91], v[168:169], v[112:113]
	v_pk_fma_f32 v[88:89], v[108:109], v[170:171], v[88:89]
	s_nop 0
	v_pk_fma_f32 v[88:89], v[106:107], v[174:175], v[88:89]
	s_nop 0
	v_pk_fma_f32 v[88:89], v[104:105], v[182:183], v[88:89]
	s_nop 0
	v_pk_mul_f32 v[104:105], v[88:89], s[98:99] op_sel_hi:[1,0]
	v_exp_f32_e32 v104, v104
	v_exp_f32_e32 v105, v105
	s_nop 0
	v_pk_add_f32 v[104:105], v[104:105], 1.0 op_sel_hi:[1,0]
	v_rcp_f32_e32 v104, v104
	v_rcp_f32_e32 v105, v105
	v_cndmask_b32_e64 v103, v102, 0, s[8:9]
	v_cndmask_b32_e64 v102, v101, 0, s[8:9]
	v_pk_fma_f32 v[90:91], v[102:103], v[172:173], v[90:91]
	v_pk_mul_f32 v[88:89], v[88:89], v[104:105]
	v_pk_fma_f32 v[90:91], v[94:95], v[176:177], v[90:91]
	v_cvt_pk_bf16_f32 v88, v88, v89
	v_pk_fma_f32 v[90:91], v[92:93], v[184:185], v[90:91]
	s_nop 0
	v_pk_mul_f32 v[92:93], v[90:91], s[98:99] op_sel_hi:[1,0]
	v_exp_f32_e32 v92, v92
	v_exp_f32_e32 v93, v93
	s_nop 0
	v_pk_add_f32 v[92:93], v[92:93], 1.0 op_sel_hi:[1,0]
	v_rcp_f32_e32 v92, v92
	v_rcp_f32_e32 v93, v93
	s_nop 0
	v_pk_mul_f32 v[90:91], v[90:91], v[92:93]
	s_nop 0
	v_cvt_pk_bf16_f32 v89, v90, v91
	global_store_dwordx2 v[96:97], v[88:89], off offset:8
.LBB0_203:
	s_or_b64 exec, exec, s[22:23]
	ds_read_b64 v[88:89], v98 offset:1280
	ds_read_b64 v[90:91], v99 offset:768
	ds_read_b64 v[106:107], v100 offset:256
	s_waitcnt lgkmcnt(0)
	v_lshlrev_b32_e32 v103, 16, v88
	v_and_b32_e32 v104, 0xffff0000, v88
	v_lshlrev_b32_e32 v92, 16, v89
	v_and_b32_e32 v93, 0xffff0000, v89
	v_lshlrev_b32_e32 v101, 16, v90
	v_and_b32_e32 v102, 0xffff0000, v90
	v_lshlrev_b32_e32 v90, 16, v91
	v_and_b32_e32 v91, 0xffff0000, v91
	v_lshlrev_b32_e32 v94, 16, v106
	v_and_b32_e32 v95, 0xffff0000, v106
	v_lshlrev_b32_e32 v88, 16, v107
	v_and_b32_e32 v89, 0xffff0000, v107
	v_mov_b32_dpp v103, v84 row_shr:1 row_mask:0xf bank_mask:0xf
	v_mov_b32_dpp v101, v84 row_shr:2 row_mask:0xf bank_mask:0xf
	v_mov_b32_dpp v94, v84 row_shr:3 row_mask:0xf bank_mask:0xf
	v_mov_b32_dpp v104, v85 row_shr:1 row_mask:0xf bank_mask:0xf
	v_mov_b32_dpp v102, v85 row_shr:2 row_mask:0xf bank_mask:0xf
	v_mov_b32_dpp v95, v85 row_shr:3 row_mask:0xf bank_mask:0xf
	v_mov_b32_dpp v92, v86 row_shr:1 row_mask:0xf bank_mask:0xf
	v_mov_b32_dpp v90, v86 row_shr:2 row_mask:0xf bank_mask:0xf
	v_mov_b32_dpp v88, v86 row_shr:3 row_mask:0xf bank_mask:0xf
	v_mov_b32_dpp v93, v87 row_shr:1 row_mask:0xf bank_mask:0xf
	v_mov_b32_dpp v91, v87 row_shr:2 row_mask:0xf bank_mask:0xf
	v_mov_b32_dpp v89, v87 row_shr:3 row_mask:0xf bank_mask:0xf
	s_and_saveexec_b64 s[22:23], s[2:3]
	s_cbranch_execz .LBB0_205
	ds_read_b128 v[106:109], v238 offset:4608
	ds_read_b128 v[110:113], v238 offset:3584
	ds_read_b128 v[166:169], v238 offset:2560
	v_cndmask_b32_e64 v105, v104, 0, s[8:9]
	ds_read_b128 v[170:173], v238 offset:1536
	ds_read_b128 v[174:177], v238 offset:512
	v_cndmask_b32_e64 v104, v103, 0, s[8:9]
	v_cndmask_b32_e64 v103, 0, v102, s[6:7]
	v_cndmask_b32_e64 v102, 0, v101, s[6:7]
	v_cndmask_b32_e64 v95, 0, v95, s[4:5]
	v_cndmask_b32_e64 v94, 0, v94, s[4:5]
	v_cndmask_b32_e64 v93, v93, 0, s[8:9]
	v_cndmask_b32_e64 v92, v92, 0, s[8:9]
	v_cndmask_b32_e64 v91, 0, v91, s[6:7]
	v_cndmask_b32_e64 v90, 0, v90, s[6:7]
	v_cndmask_b32_e64 v89, 0, v89, s[4:5]
	v_cndmask_b32_e64 v88, 0, v88, s[4:5]
	s_waitcnt lgkmcnt(0)
	v_pk_fma_f32 v[84:85], v[84:85], v[110:111], v[106:107]
	v_pk_fma_f32 v[86:87], v[86:87], v[112:113], v[108:109]
	v_pk_fma_f32 v[84:85], v[104:105], v[166:167], v[84:85]
	v_pk_fma_f32 v[86:87], v[92:93], v[168:169], v[86:87]
	v_pk_fma_f32 v[84:85], v[102:103], v[170:171], v[84:85]
	s_nop 0
	v_pk_fma_f32 v[84:85], v[94:95], v[174:175], v[84:85]
	v_pk_fma_f32 v[86:87], v[90:91], v[172:173], v[86:87]
	v_pk_fma_f32 v[86:87], v[88:89], v[176:177], v[86:87]
	v_pk_mul_f32 v[94:95], v[84:85], s[98:99] op_sel_hi:[1,0]
	v_exp_f32_e32 v94, v94
	v_exp_f32_e32 v95, v95
	s_nop 0
	v_pk_add_f32 v[94:95], v[94:95], 1.0 op_sel_hi:[1,0]
	v_rcp_f32_e32 v94, v94
	v_rcp_f32_e32 v95, v95
	s_nop 0
	v_pk_mul_f32 v[84:85], v[84:85], v[94:95]
	s_nop 0
	v_cvt_pk_bf16_f32 v84, v84, v85
	v_pk_mul_f32 v[88:89], v[86:87], s[98:99] op_sel_hi:[1,0]
	v_exp_f32_e32 v88, v88
	v_exp_f32_e32 v89, v89
	s_nop 0
	v_pk_add_f32 v[88:89], v[88:89], 1.0 op_sel_hi:[1,0]
	v_rcp_f32_e32 v88, v88
	v_rcp_f32_e32 v89, v89
	s_nop 0
	v_pk_mul_f32 v[86:87], v[86:87], v[88:89]
	s_nop 0
	v_cvt_pk_bf16_f32 v85, v86, v87
	global_store_dwordx2 v[96:97], v[84:85], off offset:256
;     __device__ __forceinline__ void operator()(const f32x4 (&acc)[2][2][4][2], const Unit& u, int wr, int wc, int fr, int fq, LAS unsigned char* hb) const {
;     ...
;             for (int m = 0; m < 4; ++m) { asm volatile("" ::: "memory"); __builtin_amdgcn_sched_barrier(0);
;                 const int q = 8 * ai + 4 * wr + m, prev = q > 0 ? q - 1 : 0; const int lr = ai * HALF + wr * 64 + m * 16 + fr, R = R0 + lr;
;                 const int Rc = R < 0 ? 0 : R; const int b = Rc / LL, p = Rc - b * LL;
;                 const bool ok = (lr >= H && R < TT);
;                 const unsigned ooff = ((unsigned)Rc * (unsigned)LDP + (unsigned)(OFF_XBC + ch0)) * 2u;
; #pragma unroll
;                 for (int bn = 0; bn < 4; ++bn) { const int bj = bn >> 1, n = bn & 1; const int co = bj * HALF + 4 * n;
;                     const unsigned woff = (unsigned)(ch0 + co) * 4u;
;                     const f32x4 w0 = *(const f32x4*)((const char*)cw + woff), w1 = *(const f32x4*)((const char*)cw + woff + XBCW * 4), w2 = *(const f32x4*)((const char*)cw + woff + 2 * XBCW * 4), w3 = *(const f32x4*)((const char*)cw + woff + 3 * XBCW * 4), bs = *(const f32x4*)((const char*)cb + woff);
;                     const LAS unsigned char* hp = hb + (prev * H * NCH + chl + co) * 2;
;                     const u32x2 q1 = *(const LAS u32x2*)(hp + hr1 * NCH * 2), q2 = *(const LAS u32x2*)(hp + hr2 * NCH * 2), q3 = *(const LAS u32x2*)(hp + hr3 * NCH * 2);
;                     const float h1[4] = {__builtin_bit_cast(float, q1.x << 16), __builtin_bit_cast(float, q1.x & 0xffff0000u), __builtin_bit_cast(float, q1.y << 16), __builtin_bit_cast(float, q1.y & 0xffff0000u)};
;                     const float h2[4] = {__builtin_bit_cast(float, q2.x << 16), __builtin_bit_cast(float, q2.x & 0xffff0000u), __builtin_bit_cast(float, q2.y << 16), __builtin_bit_cast(float, q2.y & 0xffff0000u)};
;                     const float h3[4] = {__builtin_bit_cast(float, q3.x << 16), __builtin_bit_cast(float, q3.x & 0xffff0000u), __builtin_bit_cast(float, q3.y << 16), __builtin_bit_cast(float, q3.y & 0xffff0000u)};
;                     const f32x4 gv = acc[ai][bj][m][n];
;                     float o[4];
; #pragma unroll
;                     for (int j = 0; j < 4; ++j) { const float g = gv[j];
;                         float g1 = dpp_row_shr<1>(h1[j], g), g2 = dpp_row_shr<2>(h2[j], g), g3 = dpp_row_shr<3>(h3[j], g);
.LBB0_205:
	s_or_b64 exec, exec, s[22:23]
	ds_read_b64 v[84:85], v98 offset:1288
	ds_read_b64 v[86:87], v99 offset:776
	ds_read_b64 v[98:99], v100 offset:264
	s_waitcnt lgkmcnt(0)
	v_lshlrev_b32_e32 v94, 16, v84
	v_and_b32_e32 v95, 0xffff0000, v84
	v_lshlrev_b32_e32 v88, 16, v85
	v_and_b32_e32 v89, 0xffff0000, v85
	v_lshlrev_b32_e32 v92, 16, v86
	v_and_b32_e32 v93, 0xffff0000, v86
	v_lshlrev_b32_e32 v86, 16, v87
	v_and_b32_e32 v87, 0xffff0000, v87
	v_lshlrev_b32_e32 v90, 16, v98
	v_and_b32_e32 v91, 0xffff0000, v98
	v_lshlrev_b32_e32 v84, 16, v99
	v_and_b32_e32 v85, 0xffff0000, v99
	v_mov_b32_dpp v94, v80 row_shr:1 row_mask:0xf bank_mask:0xf
	v_mov_b32_dpp v92, v80 row_shr:2 row_mask:0xf bank_mask:0xf
	v_mov_b32_dpp v90, v80 row_shr:3 row_mask:0xf bank_mask:0xf
	v_mov_b32_dpp v95, v81 row_shr:1 row_mask:0xf bank_mask:0xf
	v_mov_b32_dpp v93, v81 row_shr:2 row_mask:0xf bank_mask:0xf
	v_mov_b32_dpp v91, v81 row_shr:3 row_mask:0xf bank_mask:0xf
	v_mov_b32_dpp v88, v82 row_shr:1 row_mask:0xf bank_mask:0xf
	v_mov_b32_dpp v86, v82 row_shr:2 row_mask:0xf bank_mask:0xf
	v_mov_b32_dpp v84, v82 row_shr:3 row_mask:0xf bank_mask:0xf
	v_mov_b32_dpp v89, v83 row_shr:1 row_mask:0xf bank_mask:0xf
	v_mov_b32_dpp v87, v83 row_shr:2 row_mask:0xf bank_mask:0xf
	v_mov_b32_dpp v85, v83 row_shr:3 row_mask:0xf bank_mask:0xf
	s_and_saveexec_b64 s[22:23], s[2:3]
	s_cbranch_execz .LBB0_207
	ds_read_b128 v[98:101], v238 offset:4624
	ds_read_b128 v[102:105], v238 offset:3600
	ds_read_b128 v[106:109], v238 offset:2576
	v_cndmask_b32_e64 v95, v95, 0, s[8:9]
	ds_read_b128 v[110:113], v238 offset:1552
	s_nop 0
	ds_read_b128 v[166:169], v238 offset:528
	v_cndmask_b32_e64 v94, v94, 0, s[8:9]
	v_cndmask_b32_e64 v93, 0, v93, s[6:7]
	v_cndmask_b32_e64 v92, 0, v92, s[6:7]
	v_cndmask_b32_e64 v91, 0, v91, s[4:5]
	v_cndmask_b32_e64 v90, 0, v90, s[4:5]
	v_cndmask_b32_e64 v89, v89, 0, s[8:9]
	v_cndmask_b32_e64 v88, v88, 0, s[8:9]
	v_cndmask_b32_e64 v87, 0, v87, s[6:7]
	v_cndmask_b32_e64 v86, 0, v86, s[6:7]
	v_cndmask_b32_e64 v85, 0, v85, s[4:5]
	v_cndmask_b32_e64 v84, 0, v84, s[4:5]
	s_waitcnt lgkmcnt(0)
	v_pk_fma_f32 v[80:81], v[80:81], v[102:103], v[98:99]
	v_pk_fma_f32 v[82:83], v[82:83], v[104:105], v[100:101]
	v_pk_fma_f32 v[80:81], v[94:95], v[106:107], v[80:81]
	v_pk_fma_f32 v[82:83], v[88:89], v[108:109], v[82:83]
	v_pk_fma_f32 v[80:81], v[92:93], v[110:111], v[80:81]
	s_nop 0
	v_pk_fma_f32 v[80:81], v[90:91], v[166:167], v[80:81]
	v_pk_fma_f32 v[82:83], v[86:87], v[112:113], v[82:83]
	v_pk_fma_f32 v[82:83], v[84:85], v[168:169], v[82:83]
	v_pk_mul_f32 v[90:91], v[80:81], s[98:99] op_sel_hi:[1,0]
	v_exp_f32_e32 v90, v90
	v_exp_f32_e32 v91, v91
	s_nop 0
	v_pk_add_f32 v[90:91], v[90:91], 1.0 op_sel_hi:[1,0]
	v_rcp_f32_e32 v90, v90
	v_rcp_f32_e32 v91, v91
	s_nop 0
	v_pk_mul_f32 v[80:81], v[80:81], v[90:91]
	s_nop 0
	v_cvt_pk_bf16_f32 v80, v80, v81
	v_pk_mul_f32 v[84:85], v[82:83], s[98:99] op_sel_hi:[1,0]
	v_exp_f32_e32 v84, v84
	v_exp_f32_e32 v85, v85
	s_nop 0
	v_pk_add_f32 v[84:85], v[84:85], 1.0 op_sel_hi:[1,0]
	v_rcp_f32_e32 v84, v84
	v_rcp_f32_e32 v85, v85
	s_nop 0
	v_pk_mul_f32 v[82:83], v[82:83], v[84:85]
	s_nop 0
	v_cvt_pk_bf16_f32 v81, v82, v83
	global_store_dwordx2 v[96:97], v[80:81], off offset:264
.LBB0_207:
	s_or_b64 exec, exec, s[22:23]
	v_add_u32_e32 v80, 48, v161
	v_add_u32_e32 v81, s17, v80
	v_max_i32_e32 v82, 0, v81
	v_mul_hi_u32 v83, v82, s56
	v_lshrrev_b32_e32 v83, 11, v83
	v_cmp_lt_i32_e32 vcc, 2, v80
	v_mul_lo_u32 v80, v82, s51
	v_mul_u32_u24_e32 v83, 0x1010, v83
	v_add_lshl_u32 v136, v80, v164, 1
	v_add_u32_e32 v80, s40, v165
	v_sub_u32_e32 v83, v82, v83
	v_cmp_gt_i32_e64 s[4:5], s50, v81
	v_lshl_add_u32 v82, v80, 1, s53
	s_and_b64 s[2:3], vcc, s[4:5]
	v_cmp_eq_u32_e64 s[8:9], 0, v83
	v_cmp_lt_u32_e64 s[6:7], 1, v83
	v_cmp_lt_u32_e64 s[4:5], 2, v83
	v_add_u32_e32 v83, v82, v163
	ds_read_b64 v[80:81], v82 offset:1024
	v_add_u32_e32 v84, v82, v162
	ds_read_b64 v[98:99], v83 offset:512
	ds_read_b64 v[100:101], v84
	v_readlane_b32 s22, v237, 58
	v_readlane_b32 s23, v237, 59
	s_waitcnt lgkmcnt(0)
	v_lshlrev_b32_e32 v95, 16, v80
	v_and_b32_e32 v96, 0xffff0000, v80
	v_lshlrev_b32_e32 v89, 16, v81
	v_and_b32_e32 v90, 0xffff0000, v81
	v_lshlrev_b32_e32 v93, 16, v98
	v_and_b32_e32 v94, 0xffff0000, v98
	v_lshlrev_b32_e32 v87, 16, v99
	v_and_b32_e32 v88, 0xffff0000, v99
	v_lshlrev_b32_e32 v91, 16, v100
	v_and_b32_e32 v92, 0xffff0000, v100
	v_lshlrev_b32_e32 v85, 16, v101
	v_and_b32_e32 v86, 0xffff0000, v101
	v_mov_b32_dpp v95, v76 row_shr:1 row_mask:0xf bank_mask:0xf
	v_mov_b32_dpp v93, v76 row_shr:2 row_mask:0xf bank_mask:0xf
	v_mov_b32_dpp v91, v76 row_shr:3 row_mask:0xf bank_mask:0xf
	v_mov_b32_dpp v96, v77 row_shr:1 row_mask:0xf bank_mask:0xf
	v_mov_b32_dpp v94, v77 row_shr:2 row_mask:0xf bank_mask:0xf
	v_mov_b32_dpp v92, v77 row_shr:3 row_mask:0xf bank_mask:0xf
	v_mov_b32_dpp v89, v78 row_shr:1 row_mask:0xf bank_mask:0xf
	v_mov_b32_dpp v87, v78 row_shr:2 row_mask:0xf bank_mask:0xf
	v_mov_b32_dpp v85, v78 row_shr:3 row_mask:0xf bank_mask:0xf
	v_mov_b32_dpp v90, v79 row_shr:1 row_mask:0xf bank_mask:0xf
	v_mov_b32_dpp v88, v79 row_shr:2 row_mask:0xf bank_mask:0xf
	v_mov_b32_dpp v86, v79 row_shr:3 row_mask:0xf bank_mask:0xf
	v_lshl_add_u64 v[80:81], s[22:23], 0, v[136:137]
	s_and_saveexec_b64 s[22:23], s[2:3]
	s_cbranch_execz .LBB0_209
;     __device__ __forceinline__ void operator()(const f32x4 (&acc)[2][2][4][2], const Unit& u, int wr, int wc, int fr, int fq, LAS unsigned char* hb) const {
;     ...
;             for (int m = 0; m < 4; ++m) { asm volatile("" ::: "memory"); __builtin_amdgcn_sched_barrier(0);
;                 const int q = 8 * ai + 4 * wr + m, prev = q > 0 ? q - 1 : 0; const int lr = ai * HALF + wr * 64 + m * 16 + fr, R = R0 + lr;
;                 const int Rc = R < 0 ? 0 : R; const int b = Rc / LL, p = Rc - b * LL;
;                 const bool ok = (lr >= H && R < TT);
;                 const unsigned ooff = ((unsigned)Rc * (unsigned)LDP + (unsigned)(OFF_XBC + ch0)) * 2u;
; #pragma unroll
;                 for (int bn = 0; bn < 4; ++bn) { const int bj = bn >> 1, n = bn & 1; const int co = bj * HALF + 4 * n;
;                     const unsigned woff = (unsigned)(ch0 + co) * 4u;
;                     const f32x4 w0 = *(const f32x4*)((const char*)cw + woff), w1 = *(const f32x4*)((const char*)cw + woff + XBCW * 4), w2 = *(const f32x4*)((const char*)cw + woff + 2 * XBCW * 4), w3 = *(const f32x4*)((const char*)cw + woff + 3 * XBCW * 4), bs = *(const f32x4*)((const char*)cb + woff);
;                     const LAS unsigned char* hp = hb + (prev * H * NCH + chl + co) * 2;
;                     const u32x2 q1 = *(const LAS u32x2*)(hp + hr1 * NCH * 2), q2 = *(const LAS u32x2*)(hp + hr2 * NCH * 2), q3 = *(const LAS u32x2*)(hp + hr3 * NCH * 2);
;                     const float h1[4] = {__builtin_bit_cast(float, q1.x << 16), __builtin_bit_cast(float, q1.x & 0xffff0000u), __builtin_bit_cast(float, q1.y << 16), __builtin_bit_cast(float, q1.y & 0xffff0000u)};
;                     const float h2[4] = {__builtin_bit_cast(float, q2.x << 16), __builtin_bit_cast(float, q2.x & 0xffff0000u), __builtin_bit_cast(float, q2.y << 16), __builtin_bit_cast(float, q2.y & 0xffff0000u)};
;                     const float h3[4] = {__builtin_bit_cast(float, q3.x << 16), __builtin_bit_cast(float, q3.x & 0xffff0000u), __builtin_bit_cast(float, q3.y << 16), __builtin_bit_cast(float, q3.y & 0xffff0000u)};
;                     const f32x4 gv = acc[ai][bj][m][n];
;                     float o[4];
; #pragma unroll
;                     for (int j = 0; j < 4; ++j) { const float g = gv[j];
;                         float g1 = dpp_row_shr<1>(h1[j], g), g2 = dpp_row_shr<2>(h2[j], g), g3 = dpp_row_shr<3>(h3[j], g);
	ds_read_b128 v[98:101], v238 offset:4096
	ds_read_b128 v[102:105], v238 offset:3072
	ds_read_b128 v[106:109], v238 offset:2048
	v_cndmask_b32_e64 v97, v96, 0, s[8:9]
	ds_read_b128 v[110:113], v238 offset:1024
	s_nop 0
	ds_read_b128 v[166:169], v238
	v_cndmask_b32_e64 v96, v95, 0, s[8:9]
	v_cndmask_b32_e64 v95, 0, v94, s[6:7]
	v_cndmask_b32_e64 v94, 0, v93, s[6:7]
	v_cndmask_b32_e64 v93, 0, v92, s[4:5]
	v_cndmask_b32_e64 v92, 0, v91, s[4:5]
	s_waitcnt lgkmcnt(0)
	v_pk_fma_f32 v[76:77], v[76:77], v[102:103], v[98:99]
	v_pk_fma_f32 v[78:79], v[78:79], v[104:105], v[100:101]
	v_pk_fma_f32 v[76:77], v[96:97], v[106:107], v[76:77]
	s_nop 0
	v_pk_fma_f32 v[76:77], v[94:95], v[110:111], v[76:77]
	s_nop 0
	v_pk_fma_f32 v[76:77], v[92:93], v[166:167], v[76:77]
	s_nop 0
	v_pk_mul_f32 v[92:93], v[76:77], s[98:99] op_sel_hi:[1,0]
	v_exp_f32_e32 v92, v92
	v_exp_f32_e32 v93, v93
	s_nop 0
	v_pk_add_f32 v[92:93], v[92:93], 1.0 op_sel_hi:[1,0]
	v_rcp_f32_e32 v92, v92
	v_rcp_f32_e32 v93, v93
	v_cndmask_b32_e64 v91, v90, 0, s[8:9]
	v_cndmask_b32_e64 v90, v89, 0, s[8:9]
	v_pk_fma_f32 v[78:79], v[90:91], v[108:109], v[78:79]
	v_cndmask_b32_e64 v89, 0, v88, s[6:7]
	v_cndmask_b32_e64 v88, 0, v87, s[6:7]
	v_pk_fma_f32 v[78:79], v[88:89], v[112:113], v[78:79]
	v_cndmask_b32_e64 v87, 0, v86, s[4:5]
	v_cndmask_b32_e64 v86, 0, v85, s[4:5]
	v_pk_mul_f32 v[76:77], v[76:77], v[92:93]
	v_pk_fma_f32 v[78:79], v[86:87], v[168:169], v[78:79]
	v_cvt_pk_bf16_f32 v76, v76, v77
	v_pk_mul_f32 v[86:87], v[78:79], s[98:99] op_sel_hi:[1,0]
	v_exp_f32_e32 v86, v86
	v_exp_f32_e32 v87, v87
	s_nop 0
	v_pk_add_f32 v[86:87], v[86:87], 1.0 op_sel_hi:[1,0]
	v_rcp_f32_e32 v86, v86
	v_rcp_f32_e32 v87, v87
	s_nop 0
	v_pk_mul_f32 v[78:79], v[78:79], v[86:87]
	s_nop 0
	v_cvt_pk_bf16_f32 v77, v78, v79
	global_store_dwordx2 v[80:81], v[76:77], off
.LBB0_209:
	s_or_b64 exec, exec, s[22:23]
	ds_read_b64 v[76:77], v82 offset:1032
	ds_read_b64 v[78:79], v83 offset:520
	ds_read_b64 v[94:95], v84 offset:8
	s_waitcnt lgkmcnt(0)
	v_lshlrev_b32_e32 v91, 16, v76
	v_and_b32_e32 v92, 0xffff0000, v76
	v_lshlrev_b32_e32 v85, 16, v77
	v_and_b32_e32 v86, 0xffff0000, v77
	v_lshlrev_b32_e32 v89, 16, v78
	v_and_b32_e32 v90, 0xffff0000, v78
	v_lshlrev_b32_e32 v78, 16, v79
	v_and_b32_e32 v79, 0xffff0000, v79
	v_lshlrev_b32_e32 v87, 16, v94
	v_and_b32_e32 v88, 0xffff0000, v94
	v_lshlrev_b32_e32 v76, 16, v95
	v_and_b32_e32 v77, 0xffff0000, v95
	v_mov_b32_dpp v91, v72 row_shr:1 row_mask:0xf bank_mask:0xf
	v_mov_b32_dpp v89, v72 row_shr:2 row_mask:0xf bank_mask:0xf
	v_mov_b32_dpp v87, v72 row_shr:3 row_mask:0xf bank_mask:0xf
	v_mov_b32_dpp v92, v73 row_shr:1 row_mask:0xf bank_mask:0xf
	v_mov_b32_dpp v90, v73 row_shr:2 row_mask:0xf bank_mask:0xf
	v_mov_b32_dpp v88, v73 row_shr:3 row_mask:0xf bank_mask:0xf
	v_mov_b32_dpp v85, v74 row_shr:1 row_mask:0xf bank_mask:0xf
	v_mov_b32_dpp v78, v74 row_shr:2 row_mask:0xf bank_mask:0xf
	v_mov_b32_dpp v76, v74 row_shr:3 row_mask:0xf bank_mask:0xf
	v_mov_b32_dpp v86, v75 row_shr:1 row_mask:0xf bank_mask:0xf
	v_mov_b32_dpp v79, v75 row_shr:2 row_mask:0xf bank_mask:0xf
	v_mov_b32_dpp v77, v75 row_shr:3 row_mask:0xf bank_mask:0xf
	s_and_saveexec_b64 s[22:23], s[2:3]
	s_cbranch_execz .LBB0_211
	ds_read_b128 v[94:97], v238 offset:4112
	ds_read_b128 v[98:101], v238 offset:3088
	ds_read_b128 v[102:105], v238 offset:2064
	v_cndmask_b32_e64 v93, v92, 0, s[8:9]
	ds_read_b128 v[106:109], v238 offset:1040
	s_nop 0
	ds_read_b128 v[110:113], v238 offset:16
	v_cndmask_b32_e64 v92, v91, 0, s[8:9]
	v_cndmask_b32_e64 v91, 0, v90, s[6:7]
	v_cndmask_b32_e64 v90, 0, v89, s[6:7]
	v_cndmask_b32_e64 v89, 0, v88, s[4:5]
	v_cndmask_b32_e64 v88, 0, v87, s[4:5]
	v_cndmask_b32_e64 v79, 0, v79, s[6:7]
	v_cndmask_b32_e64 v78, 0, v78, s[6:7]
	v_cndmask_b32_e64 v77, 0, v77, s[4:5]
	v_cndmask_b32_e64 v76, 0, v76, s[4:5]
	s_waitcnt lgkmcnt(0)
	v_pk_fma_f32 v[72:73], v[72:73], v[98:99], v[94:95]
	v_pk_fma_f32 v[74:75], v[74:75], v[100:101], v[96:97]
	v_pk_fma_f32 v[72:73], v[92:93], v[102:103], v[72:73]
	s_nop 0
	v_pk_fma_f32 v[72:73], v[90:91], v[106:107], v[72:73]
	s_nop 0
	v_pk_fma_f32 v[72:73], v[88:89], v[110:111], v[72:73]
	s_nop 0
	v_pk_mul_f32 v[88:89], v[72:73], s[98:99] op_sel_hi:[1,0]
	v_exp_f32_e32 v88, v88
	v_exp_f32_e32 v89, v89
	s_nop 0
	v_pk_add_f32 v[88:89], v[88:89], 1.0 op_sel_hi:[1,0]
	v_rcp_f32_e32 v88, v88
	v_rcp_f32_e32 v89, v89
	v_cndmask_b32_e64 v87, v86, 0, s[8:9]
	v_cndmask_b32_e64 v86, v85, 0, s[8:9]
	v_pk_fma_f32 v[74:75], v[86:87], v[104:105], v[74:75]
	v_pk_mul_f32 v[72:73], v[72:73], v[88:89]
	v_pk_fma_f32 v[74:75], v[78:79], v[108:109], v[74:75]
	v_cvt_pk_bf16_f32 v72, v72, v73
	v_pk_fma_f32 v[74:75], v[76:77], v[112:113], v[74:75]
	s_nop 0
	v_pk_mul_f32 v[76:77], v[74:75], s[98:99] op_sel_hi:[1,0]
	v_exp_f32_e32 v76, v76
	v_exp_f32_e32 v77, v77
	s_nop 0
	v_pk_add_f32 v[76:77], v[76:77], 1.0 op_sel_hi:[1,0]
	v_rcp_f32_e32 v76, v76
	v_rcp_f32_e32 v77, v77
	s_nop 0
	v_pk_mul_f32 v[74:75], v[74:75], v[76:77]
	s_nop 0
	v_cvt_pk_bf16_f32 v73, v74, v75
	global_store_dwordx2 v[80:81], v[72:73], off offset:8
;     __device__ __forceinline__ void operator()(const f32x4 (&acc)[2][2][4][2], const Unit& u, int wr, int wc, int fr, int fq, LAS unsigned char* hb) const {
;     ...
;             for (int m = 0; m < 4; ++m) { asm volatile("" ::: "memory"); __builtin_amdgcn_sched_barrier(0);
;                 const int q = 8 * ai + 4 * wr + m, prev = q > 0 ? q - 1 : 0; const int lr = ai * HALF + wr * 64 + m * 16 + fr, R = R0 + lr;
;                 const int Rc = R < 0 ? 0 : R; const int b = Rc / LL, p = Rc - b * LL;
;                 const bool ok = (lr >= H && R < TT);
;                 const unsigned ooff = ((unsigned)Rc * (unsigned)LDP + (unsigned)(OFF_XBC + ch0)) * 2u;
; #pragma unroll
;                 for (int bn = 0; bn < 4; ++bn) { const int bj = bn >> 1, n = bn & 1; const int co = bj * HALF + 4 * n;
;                     const unsigned woff = (unsigned)(ch0 + co) * 4u;
;                     const f32x4 w0 = *(const f32x4*)((const char*)cw + woff), w1 = *(const f32x4*)((const char*)cw + woff + XBCW * 4), w2 = *(const f32x4*)((const char*)cw + woff + 2 * XBCW * 4), w3 = *(const f32x4*)((const char*)cw + woff + 3 * XBCW * 4), bs = *(const f32x4*)((const char*)cb + woff);
;                     const LAS unsigned char* hp = hb + (prev * H * NCH + chl + co) * 2;
;                     const u32x2 q1 = *(const LAS u32x2*)(hp + hr1 * NCH * 2), q2 = *(const LAS u32x2*)(hp + hr2 * NCH * 2), q3 = *(const LAS u32x2*)(hp + hr3 * NCH * 2);
;                     const float h1[4] = {__builtin_bit_cast(float, q1.x << 16), __builtin_bit_cast(float, q1.x & 0xffff0000u), __builtin_bit_cast(float, q1.y << 16), __builtin_bit_cast(float, q1.y & 0xffff0000u)};
;                     const float h2[4] = {__builtin_bit_cast(float, q2.x << 16), __builtin_bit_cast(float, q2.x & 0xffff0000u), __builtin_bit_cast(float, q2.y << 16), __builtin_bit_cast(float, q2.y & 0xffff0000u)};
;                     const float h3[4] = {__builtin_bit_cast(float, q3.x << 16), __builtin_bit_cast(float, q3.x & 0xffff0000u), __builtin_bit_cast(float, q3.y << 16), __builtin_bit_cast(float, q3.y & 0xffff0000u)};
;                     const f32x4 gv = acc[ai][bj][m][n];
;                     float o[4];
; #pragma unroll
;                     for (int j = 0; j < 4; ++j) { const float g = gv[j];
;                         float g1 = dpp_row_shr<1>(h1[j], g), g2 = dpp_row_shr<2>(h2[j], g), g3 = dpp_row_shr<3>(h3[j], g);
.LBB0_211:
	s_or_b64 exec, exec, s[22:23]
	ds_read_b64 v[72:73], v82 offset:1280
	ds_read_b64 v[74:75], v83 offset:768
	ds_read_b64 v[90:91], v84 offset:256
	s_waitcnt lgkmcnt(0)
	v_lshlrev_b32_e32 v87, 16, v72
	v_and_b32_e32 v88, 0xffff0000, v72
	v_lshlrev_b32_e32 v76, 16, v73
	v_and_b32_e32 v77, 0xffff0000, v73
	v_lshlrev_b32_e32 v85, 16, v74
	v_and_b32_e32 v86, 0xffff0000, v74
	v_lshlrev_b32_e32 v74, 16, v75
	v_and_b32_e32 v75, 0xffff0000, v75
	v_lshlrev_b32_e32 v78, 16, v90
	v_and_b32_e32 v79, 0xffff0000, v90
	v_lshlrev_b32_e32 v72, 16, v91
	v_and_b32_e32 v73, 0xffff0000, v91
	v_mov_b32_dpp v87, v68 row_shr:1 row_mask:0xf bank_mask:0xf
	v_mov_b32_dpp v85, v68 row_shr:2 row_mask:0xf bank_mask:0xf
	v_mov_b32_dpp v78, v68 row_shr:3 row_mask:0xf bank_mask:0xf
	v_mov_b32_dpp v88, v69 row_shr:1 row_mask:0xf bank_mask:0xf
	v_mov_b32_dpp v86, v69 row_shr:2 row_mask:0xf bank_mask:0xf
	v_mov_b32_dpp v79, v69 row_shr:3 row_mask:0xf bank_mask:0xf
	v_mov_b32_dpp v76, v70 row_shr:1 row_mask:0xf bank_mask:0xf
	v_mov_b32_dpp v74, v70 row_shr:2 row_mask:0xf bank_mask:0xf
	v_mov_b32_dpp v72, v70 row_shr:3 row_mask:0xf bank_mask:0xf
	v_mov_b32_dpp v77, v71 row_shr:1 row_mask:0xf bank_mask:0xf
	v_mov_b32_dpp v75, v71 row_shr:2 row_mask:0xf bank_mask:0xf
	v_mov_b32_dpp v73, v71 row_shr:3 row_mask:0xf bank_mask:0xf
	s_and_saveexec_b64 s[22:23], s[2:3]
	s_cbranch_execz .LBB0_213
	ds_read_b128 v[90:93], v238 offset:4608
	ds_read_b128 v[94:97], v238 offset:3584
	ds_read_b128 v[98:101], v238 offset:2560
	v_cndmask_b32_e64 v89, v88, 0, s[8:9]
	ds_read_b128 v[102:105], v238 offset:1536
	s_nop 0
	ds_read_b128 v[106:109], v238 offset:512
	v_cndmask_b32_e64 v88, v87, 0, s[8:9]
	v_cndmask_b32_e64 v87, 0, v86, s[6:7]
	v_cndmask_b32_e64 v86, 0, v85, s[6:7]
	v_cndmask_b32_e64 v79, 0, v79, s[4:5]
	v_cndmask_b32_e64 v78, 0, v78, s[4:5]
	v_cndmask_b32_e64 v77, v77, 0, s[8:9]
	v_cndmask_b32_e64 v76, v76, 0, s[8:9]
	v_cndmask_b32_e64 v75, 0, v75, s[6:7]
	v_cndmask_b32_e64 v74, 0, v74, s[6:7]
	v_cndmask_b32_e64 v73, 0, v73, s[4:5]
	v_cndmask_b32_e64 v72, 0, v72, s[4:5]
	s_waitcnt lgkmcnt(0)
	v_pk_fma_f32 v[68:69], v[68:69], v[94:95], v[90:91]
	v_pk_fma_f32 v[70:71], v[70:71], v[96:97], v[92:93]
	v_pk_fma_f32 v[68:69], v[88:89], v[98:99], v[68:69]
	v_pk_fma_f32 v[70:71], v[76:77], v[100:101], v[70:71]
	v_pk_fma_f32 v[68:69], v[86:87], v[102:103], v[68:69]
	s_nop 0
	v_pk_fma_f32 v[68:69], v[78:79], v[106:107], v[68:69]
	v_pk_fma_f32 v[70:71], v[74:75], v[104:105], v[70:71]
	v_pk_fma_f32 v[70:71], v[72:73], v[108:109], v[70:71]
	v_pk_mul_f32 v[78:79], v[68:69], s[98:99] op_sel_hi:[1,0]
	v_exp_f32_e32 v78, v78
	v_exp_f32_e32 v79, v79
	s_nop 0
	v_pk_add_f32 v[78:79], v[78:79], 1.0 op_sel_hi:[1,0]
	v_rcp_f32_e32 v78, v78
	v_rcp_f32_e32 v79, v79
	s_nop 0
	v_pk_mul_f32 v[68:69], v[68:69], v[78:79]
	s_nop 0
	v_cvt_pk_bf16_f32 v68, v68, v69
	v_pk_mul_f32 v[72:73], v[70:71], s[98:99] op_sel_hi:[1,0]
	v_exp_f32_e32 v72, v72
	v_exp_f32_e32 v73, v73
	s_nop 0
	v_pk_add_f32 v[72:73], v[72:73], 1.0 op_sel_hi:[1,0]
	v_rcp_f32_e32 v72, v72
	v_rcp_f32_e32 v73, v73
	s_nop 0
	v_pk_mul_f32 v[70:71], v[70:71], v[72:73]
	s_nop 0
	v_cvt_pk_bf16_f32 v69, v70, v71
	global_store_dwordx2 v[80:81], v[68:69], off offset:256
.LBB0_213:
	s_or_b64 exec, exec, s[22:23]
	ds_read_b64 v[68:69], v82 offset:1288
	ds_read_b64 v[70:71], v83 offset:776
	ds_read_b64 v[82:83], v84 offset:264
	s_waitcnt lgkmcnt(0)
	v_lshlrev_b32_e32 v78, 16, v68
	v_and_b32_e32 v79, 0xffff0000, v68
	v_lshlrev_b32_e32 v72, 16, v69
	v_and_b32_e32 v73, 0xffff0000, v69
	v_lshlrev_b32_e32 v76, 16, v70
	v_and_b32_e32 v77, 0xffff0000, v70
	v_lshlrev_b32_e32 v70, 16, v71
	v_and_b32_e32 v71, 0xffff0000, v71
	v_lshlrev_b32_e32 v74, 16, v82
	v_and_b32_e32 v75, 0xffff0000, v82
	v_lshlrev_b32_e32 v68, 16, v83
	v_and_b32_e32 v69, 0xffff0000, v83
	v_mov_b32_dpp v78, v64 row_shr:1 row_mask:0xf bank_mask:0xf
	v_mov_b32_dpp v76, v64 row_shr:2 row_mask:0xf bank_mask:0xf
	v_mov_b32_dpp v74, v64 row_shr:3 row_mask:0xf bank_mask:0xf
	v_mov_b32_dpp v79, v65 row_shr:1 row_mask:0xf bank_mask:0xf
	v_mov_b32_dpp v77, v65 row_shr:2 row_mask:0xf bank_mask:0xf
	v_mov_b32_dpp v75, v65 row_shr:3 row_mask:0xf bank_mask:0xf
	v_mov_b32_dpp v72, v66 row_shr:1 row_mask:0xf bank_mask:0xf
	v_mov_b32_dpp v70, v66 row_shr:2 row_mask:0xf bank_mask:0xf
	v_mov_b32_dpp v68, v66 row_shr:3 row_mask:0xf bank_mask:0xf
	v_mov_b32_dpp v73, v67 row_shr:1 row_mask:0xf bank_mask:0xf
	v_mov_b32_dpp v71, v67 row_shr:2 row_mask:0xf bank_mask:0xf
	v_mov_b32_dpp v69, v67 row_shr:3 row_mask:0xf bank_mask:0xf
	s_and_saveexec_b64 s[22:23], s[2:3]
	s_cbranch_execz .LBB0_215
	ds_read_b128 v[82:85], v238 offset:4624
	ds_read_b128 v[86:89], v238 offset:3600
	ds_read_b128 v[90:93], v238 offset:2576
	v_cndmask_b32_e64 v79, v79, 0, s[8:9]
	ds_read_b128 v[94:97], v238 offset:1552
	s_nop 0
	ds_read_b128 v[98:101], v238 offset:528
	v_cndmask_b32_e64 v78, v78, 0, s[8:9]
	v_cndmask_b32_e64 v77, 0, v77, s[6:7]
	v_cndmask_b32_e64 v76, 0, v76, s[6:7]
	v_cndmask_b32_e64 v75, 0, v75, s[4:5]
	v_cndmask_b32_e64 v74, 0, v74, s[4:5]
	v_cndmask_b32_e64 v73, v73, 0, s[8:9]
	v_cndmask_b32_e64 v72, v72, 0, s[8:9]
	v_cndmask_b32_e64 v71, 0, v71, s[6:7]
	v_cndmask_b32_e64 v70, 0, v70, s[6:7]
	v_cndmask_b32_e64 v69, 0, v69, s[4:5]
	v_cndmask_b32_e64 v68, 0, v68, s[4:5]
	s_waitcnt lgkmcnt(0)
	v_pk_fma_f32 v[64:65], v[64:65], v[86:87], v[82:83]
	v_pk_fma_f32 v[66:67], v[66:67], v[88:89], v[84:85]
	v_pk_fma_f32 v[64:65], v[78:79], v[90:91], v[64:65]
	v_pk_fma_f32 v[66:67], v[72:73], v[92:93], v[66:67]
	v_pk_fma_f32 v[64:65], v[76:77], v[94:95], v[64:65]
	s_nop 0
	v_pk_fma_f32 v[64:65], v[74:75], v[98:99], v[64:65]
	v_pk_fma_f32 v[66:67], v[70:71], v[96:97], v[66:67]
	v_pk_fma_f32 v[66:67], v[68:69], v[100:101], v[66:67]
	v_pk_mul_f32 v[74:75], v[64:65], s[98:99] op_sel_hi:[1,0]
	v_exp_f32_e32 v74, v74
	v_exp_f32_e32 v75, v75
	s_nop 0
	v_pk_add_f32 v[74:75], v[74:75], 1.0 op_sel_hi:[1,0]
	v_rcp_f32_e32 v74, v74
	v_rcp_f32_e32 v75, v75
	s_nop 0
	v_pk_mul_f32 v[64:65], v[64:65], v[74:75]
	s_nop 0
	v_cvt_pk_bf16_f32 v64, v64, v65
	v_pk_mul_f32 v[68:69], v[66:67], s[98:99] op_sel_hi:[1,0]
	v_exp_f32_e32 v68, v68
	v_exp_f32_e32 v69, v69
	s_nop 0
	v_pk_add_f32 v[68:69], v[68:69], 1.0 op_sel_hi:[1,0]
	v_rcp_f32_e32 v68, v68
	v_rcp_f32_e32 v69, v69
	s_nop 0
	v_pk_mul_f32 v[66:67], v[66:67], v[68:69]
	s_nop 0
	v_cvt_pk_bf16_f32 v65, v66, v67
	global_store_dwordx2 v[80:81], v[64:65], off offset:264
;     __device__ __forceinline__ void operator()(const f32x4 (&acc)[2][2][4][2], const Unit& u, int wr, int wc, int fr, int fq, LAS unsigned char* hb) const {
;     ...
;             for (int m = 0; m < 4; ++m) { asm volatile("" ::: "memory"); __builtin_amdgcn_sched_barrier(0);
;                 const int q = 8 * ai + 4 * wr + m, prev = q > 0 ? q - 1 : 0; const int lr = ai * HALF + wr * 64 + m * 16 + fr, R = R0 + lr;
;                 const int Rc = R < 0 ? 0 : R; const int b = Rc / LL, p = Rc - b * LL;
;                 const bool ok = (lr >= H && R < TT);
;                 const unsigned ooff = ((unsigned)Rc * (unsigned)LDP + (unsigned)(OFF_XBC + ch0)) * 2u;
; #pragma unroll
;                 for (int bn = 0; bn < 4; ++bn) { const int bj = bn >> 1, n = bn & 1; const int co = bj * HALF + 4 * n;
;                     const unsigned woff = (unsigned)(ch0 + co) * 4u;
;                     const f32x4 w0 = *(const f32x4*)((const char*)cw + woff), w1 = *(const f32x4*)((const char*)cw + woff + XBCW * 4), w2 = *(const f32x4*)((const char*)cw + woff + 2 * XBCW * 4), w3 = *(const f32x4*)((const char*)cw + woff + 3 * XBCW * 4), bs = *(const f32x4*)((const char*)cb + woff);
;                     const LAS unsigned char* hp = hb + (prev * H * NCH + chl + co) * 2;
;                     const u32x2 q1 = *(const LAS u32x2*)(hp + hr1 * NCH * 2), q2 = *(const LAS u32x2*)(hp + hr2 * NCH * 2), q3 = *(const LAS u32x2*)(hp + hr3 * NCH * 2);
;                     const float h1[4] = {__builtin_bit_cast(float, q1.x << 16), __builtin_bit_cast(float, q1.x & 0xffff0000u), __builtin_bit_cast(float, q1.y << 16), __builtin_bit_cast(float, q1.y & 0xffff0000u)};
;                     const float h2[4] = {__builtin_bit_cast(float, q2.x << 16), __builtin_bit_cast(float, q2.x & 0xffff0000u), __builtin_bit_cast(float, q2.y << 16), __builtin_bit_cast(float, q2.y & 0xffff0000u)};
;                     const float h3[4] = {__builtin_bit_cast(float, q3.x << 16), __builtin_bit_cast(float, q3.x & 0xffff0000u), __builtin_bit_cast(float, q3.y << 16), __builtin_bit_cast(float, q3.y & 0xffff0000u)};
;                     const f32x4 gv = acc[ai][bj][m][n];
;                     float o[4];
; #pragma unroll
;                     for (int j = 0; j < 4; ++j) { const float g = gv[j];
;                         float g1 = dpp_row_shr<1>(h1[j], g), g2 = dpp_row_shr<2>(h2[j], g), g3 = dpp_row_shr<3>(h3[j], g);
.LBB0_215:
	s_or_b64 exec, exec, s[22:23]
	v_add_u32_e32 v64, 0x80, v161
	v_add_u32_e32 v65, s17, v64
	v_max_i32_e32 v66, 0, v65
	v_mul_hi_u32 v67, v66, s56
	v_lshrrev_b32_e32 v67, 11, v67
	v_cmp_lt_i32_e32 vcc, 2, v64
	v_mul_lo_u32 v64, v66, s51
	v_mul_u32_u24_e32 v67, 0x1010, v67
	v_add_lshl_u32 v136, v64, v164, 1
	v_add_u32_e32 v64, s41, v165
	v_sub_u32_e32 v67, v66, v67
	v_cmp_gt_i32_e64 s[4:5], s50, v65
	v_lshl_add_u32 v66, v64, 1, s53
	s_and_b64 s[2:3], vcc, s[4:5]
	v_cmp_eq_u32_e64 s[8:9], 0, v67
	v_cmp_lt_u32_e64 s[6:7], 1, v67
	v_cmp_lt_u32_e64 s[4:5], 2, v67
	v_add_u32_e32 v67, v66, v163
	ds_read_b64 v[64:65], v66 offset:1024
	v_add_u32_e32 v68, v66, v162
	ds_read_b64 v[82:83], v67 offset:512
	ds_read_b64 v[84:85], v68
	v_readlane_b32 s22, v237, 58
	v_readlane_b32 s23, v237, 59
	s_waitcnt lgkmcnt(0)
	v_lshlrev_b32_e32 v79, 16, v64
	v_and_b32_e32 v80, 0xffff0000, v64
	v_lshlrev_b32_e32 v73, 16, v65
	v_and_b32_e32 v74, 0xffff0000, v65
	v_lshlrev_b32_e32 v77, 16, v82
	v_and_b32_e32 v78, 0xffff0000, v82
	v_lshlrev_b32_e32 v71, 16, v83
	v_and_b32_e32 v72, 0xffff0000, v83
	v_lshlrev_b32_e32 v75, 16, v84
	v_and_b32_e32 v76, 0xffff0000, v84
	v_lshlrev_b32_e32 v69, 16, v85
	v_and_b32_e32 v70, 0xffff0000, v85
	v_mov_b32_dpp v79, v60 row_shr:1 row_mask:0xf bank_mask:0xf
	v_mov_b32_dpp v77, v60 row_shr:2 row_mask:0xf bank_mask:0xf
	v_mov_b32_dpp v75, v60 row_shr:3 row_mask:0xf bank_mask:0xf
	v_mov_b32_dpp v80, v61 row_shr:1 row_mask:0xf bank_mask:0xf
	v_mov_b32_dpp v78, v61 row_shr:2 row_mask:0xf bank_mask:0xf
	v_mov_b32_dpp v76, v61 row_shr:3 row_mask:0xf bank_mask:0xf
	v_mov_b32_dpp v73, v62 row_shr:1 row_mask:0xf bank_mask:0xf
	v_mov_b32_dpp v71, v62 row_shr:2 row_mask:0xf bank_mask:0xf
	v_mov_b32_dpp v69, v62 row_shr:3 row_mask:0xf bank_mask:0xf
	v_mov_b32_dpp v74, v63 row_shr:1 row_mask:0xf bank_mask:0xf
	v_mov_b32_dpp v72, v63 row_shr:2 row_mask:0xf bank_mask:0xf
	v_mov_b32_dpp v70, v63 row_shr:3 row_mask:0xf bank_mask:0xf
	v_lshl_add_u64 v[64:65], s[22:23], 0, v[136:137]
	s_and_saveexec_b64 s[22:23], s[2:3]
	s_cbranch_execz .LBB0_217
	ds_read_b128 v[82:85], v238 offset:4096
	ds_read_b128 v[86:89], v238 offset:3072
	ds_read_b128 v[90:93], v238 offset:2048
	v_cndmask_b32_e64 v81, v80, 0, s[8:9]
	ds_read_b128 v[94:97], v238 offset:1024
	s_nop 0
	ds_read_b128 v[98:101], v238
	v_cndmask_b32_e64 v80, v79, 0, s[8:9]
	v_cndmask_b32_e64 v79, 0, v78, s[6:7]
	v_cndmask_b32_e64 v78, 0, v77, s[6:7]
	v_cndmask_b32_e64 v77, 0, v76, s[4:5]
	v_cndmask_b32_e64 v76, 0, v75, s[4:5]
	s_waitcnt lgkmcnt(0)
	v_pk_fma_f32 v[60:61], v[60:61], v[86:87], v[82:83]
	v_pk_fma_f32 v[62:63], v[62:63], v[88:89], v[84:85]
	v_pk_fma_f32 v[60:61], v[80:81], v[90:91], v[60:61]
	s_nop 0
	v_pk_fma_f32 v[60:61], v[78:79], v[94:95], v[60:61]
	s_nop 0
	v_pk_fma_f32 v[60:61], v[76:77], v[98:99], v[60:61]
	s_nop 0
	v_pk_mul_f32 v[76:77], v[60:61], s[98:99] op_sel_hi:[1,0]
	v_exp_f32_e32 v76, v76
	v_exp_f32_e32 v77, v77
	s_nop 0
	v_pk_add_f32 v[76:77], v[76:77], 1.0 op_sel_hi:[1,0]
	v_rcp_f32_e32 v76, v76
	v_rcp_f32_e32 v77, v77
	v_cndmask_b32_e64 v75, v74, 0, s[8:9]
	v_cndmask_b32_e64 v74, v73, 0, s[8:9]
	v_pk_fma_f32 v[62:63], v[74:75], v[92:93], v[62:63]
	v_cndmask_b32_e64 v73, 0, v72, s[6:7]
	v_cndmask_b32_e64 v72, 0, v71, s[6:7]
	v_pk_fma_f32 v[62:63], v[72:73], v[96:97], v[62:63]
	v_cndmask_b32_e64 v71, 0, v70, s[4:5]
	v_cndmask_b32_e64 v70, 0, v69, s[4:5]
	v_pk_mul_f32 v[60:61], v[60:61], v[76:77]
	v_pk_fma_f32 v[62:63], v[70:71], v[100:101], v[62:63]
	v_cvt_pk_bf16_f32 v60, v60, v61
	v_pk_mul_f32 v[70:71], v[62:63], s[98:99] op_sel_hi:[1,0]
	v_exp_f32_e32 v70, v70
	v_exp_f32_e32 v71, v71
	s_nop 0
	v_pk_add_f32 v[70:71], v[70:71], 1.0 op_sel_hi:[1,0]
	v_rcp_f32_e32 v70, v70
	v_rcp_f32_e32 v71, v71
	s_nop 0
	v_pk_mul_f32 v[62:63], v[62:63], v[70:71]
	s_nop 0
	v_cvt_pk_bf16_f32 v61, v62, v63
	global_store_dwordx2 v[64:65], v[60:61], off
.LBB0_217:
	s_or_b64 exec, exec, s[22:23]
	ds_read_b64 v[60:61], v66 offset:1032
	ds_read_b64 v[62:63], v67 offset:520
	ds_read_b64 v[78:79], v68 offset:8
	s_waitcnt lgkmcnt(0)
	v_lshlrev_b32_e32 v75, 16, v60
	v_and_b32_e32 v76, 0xffff0000, v60
	v_lshlrev_b32_e32 v69, 16, v61
	v_and_b32_e32 v70, 0xffff0000, v61
	v_lshlrev_b32_e32 v73, 16, v62
	v_and_b32_e32 v74, 0xffff0000, v62
	v_lshlrev_b32_e32 v62, 16, v63
	v_and_b32_e32 v63, 0xffff0000, v63
	v_lshlrev_b32_e32 v71, 16, v78
	v_and_b32_e32 v72, 0xffff0000, v78
	v_lshlrev_b32_e32 v60, 16, v79
	v_and_b32_e32 v61, 0xffff0000, v79
	v_mov_b32_dpp v75, v56 row_shr:1 row_mask:0xf bank_mask:0xf
	v_mov_b32_dpp v73, v56 row_shr:2 row_mask:0xf bank_mask:0xf
	v_mov_b32_dpp v71, v56 row_shr:3 row_mask:0xf bank_mask:0xf
	v_mov_b32_dpp v76, v57 row_shr:1 row_mask:0xf bank_mask:0xf
	v_mov_b32_dpp v74, v57 row_shr:2 row_mask:0xf bank_mask:0xf
	v_mov_b32_dpp v72, v57 row_shr:3 row_mask:0xf bank_mask:0xf
	v_mov_b32_dpp v69, v58 row_shr:1 row_mask:0xf bank_mask:0xf
	v_mov_b32_dpp v62, v58 row_shr:2 row_mask:0xf bank_mask:0xf
	v_mov_b32_dpp v60, v58 row_shr:3 row_mask:0xf bank_mask:0xf
	v_mov_b32_dpp v70, v59 row_shr:1 row_mask:0xf bank_mask:0xf
	v_mov_b32_dpp v63, v59 row_shr:2 row_mask:0xf bank_mask:0xf
	v_mov_b32_dpp v61, v59 row_shr:3 row_mask:0xf bank_mask:0xf
	s_and_saveexec_b64 s[22:23], s[2:3]
	s_cbranch_execz .LBB0_219
;     __device__ __forceinline__ void operator()(const f32x4 (&acc)[2][2][4][2], const Unit& u, int wr, int wc, int fr, int fq, LAS unsigned char* hb) const {
;     ...
;             for (int m = 0; m < 4; ++m) { asm volatile("" ::: "memory"); __builtin_amdgcn_sched_barrier(0);
;                 const int q = 8 * ai + 4 * wr + m, prev = q > 0 ? q - 1 : 0; const int lr = ai * HALF + wr * 64 + m * 16 + fr, R = R0 + lr;
;                 const int Rc = R < 0 ? 0 : R; const int b = Rc / LL, p = Rc - b * LL;
;                 const bool ok = (lr >= H && R < TT);
;                 const unsigned ooff = ((unsigned)Rc * (unsigned)LDP + (unsigned)(OFF_XBC + ch0)) * 2u;
; #pragma unroll
;                 for (int bn = 0; bn < 4; ++bn) { const int bj = bn >> 1, n = bn & 1; const int co = bj * HALF + 4 * n;
;                     const unsigned woff = (unsigned)(ch0 + co) * 4u;
;                     const f32x4 w0 = *(const f32x4*)((const char*)cw + woff), w1 = *(const f32x4*)((const char*)cw + woff + XBCW * 4), w2 = *(const f32x4*)((const char*)cw + woff + 2 * XBCW * 4), w3 = *(const f32x4*)((const char*)cw + woff + 3 * XBCW * 4), bs = *(const f32x4*)((const char*)cb + woff);
;                     const LAS unsigned char* hp = hb + (prev * H * NCH + chl + co) * 2;
;                     const u32x2 q1 = *(const LAS u32x2*)(hp + hr1 * NCH * 2), q2 = *(const LAS u32x2*)(hp + hr2 * NCH * 2), q3 = *(const LAS u32x2*)(hp + hr3 * NCH * 2);
;                     const float h1[4] = {__builtin_bit_cast(float, q1.x << 16), __builtin_bit_cast(float, q1.x & 0xffff0000u), __builtin_bit_cast(float, q1.y << 16), __builtin_bit_cast(float, q1.y & 0xffff0000u)};
;                     const float h2[4] = {__builtin_bit_cast(float, q2.x << 16), __builtin_bit_cast(float, q2.x & 0xffff0000u), __builtin_bit_cast(float, q2.y << 16), __builtin_bit_cast(float, q2.y & 0xffff0000u)};
;                     const float h3[4] = {__builtin_bit_cast(float, q3.x << 16), __builtin_bit_cast(float, q3.x & 0xffff0000u), __builtin_bit_cast(float, q3.y << 16), __builtin_bit_cast(float, q3.y & 0xffff0000u)};
;                     const f32x4 gv = acc[ai][bj][m][n];
;                     float o[4];
; #pragma unroll
;                     for (int j = 0; j < 4; ++j) { const float g = gv[j];
;                         float g1 = dpp_row_shr<1>(h1[j], g), g2 = dpp_row_shr<2>(h2[j], g), g3 = dpp_row_shr<3>(h3[j], g);
	ds_read_b128 v[78:81], v238 offset:4112
	ds_read_b128 v[82:85], v238 offset:3088
	ds_read_b128 v[86:89], v238 offset:2064
	v_cndmask_b32_e64 v77, v76, 0, s[8:9]
	ds_read_b128 v[90:93], v238 offset:1040
	s_nop 0
	ds_read_b128 v[94:97], v238 offset:16
	v_cndmask_b32_e64 v76, v75, 0, s[8:9]
	v_cndmask_b32_e64 v75, 0, v74, s[6:7]
	v_cndmask_b32_e64 v74, 0, v73, s[6:7]
	v_cndmask_b32_e64 v73, 0, v72, s[4:5]
	v_cndmask_b32_e64 v72, 0, v71, s[4:5]
	v_cndmask_b32_e64 v63, 0, v63, s[6:7]
	v_cndmask_b32_e64 v62, 0, v62, s[6:7]
	v_cndmask_b32_e64 v61, 0, v61, s[4:5]
	v_cndmask_b32_e64 v60, 0, v60, s[4:5]
	s_waitcnt lgkmcnt(0)
	v_pk_fma_f32 v[56:57], v[56:57], v[82:83], v[78:79]
	v_pk_fma_f32 v[58:59], v[58:59], v[84:85], v[80:81]
	v_pk_fma_f32 v[56:57], v[76:77], v[86:87], v[56:57]
	s_nop 0
	v_pk_fma_f32 v[56:57], v[74:75], v[90:91], v[56:57]
	s_nop 0
	v_pk_fma_f32 v[56:57], v[72:73], v[94:95], v[56:57]
	s_nop 0
	v_pk_mul_f32 v[72:73], v[56:57], s[98:99] op_sel_hi:[1,0]
	v_exp_f32_e32 v72, v72
	v_exp_f32_e32 v73, v73
	s_nop 0
	v_pk_add_f32 v[72:73], v[72:73], 1.0 op_sel_hi:[1,0]
	v_rcp_f32_e32 v72, v72
	v_rcp_f32_e32 v73, v73
	v_cndmask_b32_e64 v71, v70, 0, s[8:9]
	v_cndmask_b32_e64 v70, v69, 0, s[8:9]
	v_pk_fma_f32 v[58:59], v[70:71], v[88:89], v[58:59]
	v_pk_mul_f32 v[56:57], v[56:57], v[72:73]
	v_pk_fma_f32 v[58:59], v[62:63], v[92:93], v[58:59]
	v_cvt_pk_bf16_f32 v56, v56, v57
	v_pk_fma_f32 v[58:59], v[60:61], v[96:97], v[58:59]
	s_nop 0
	v_pk_mul_f32 v[60:61], v[58:59], s[98:99] op_sel_hi:[1,0]
	v_exp_f32_e32 v60, v60
	v_exp_f32_e32 v61, v61
	s_nop 0
	v_pk_add_f32 v[60:61], v[60:61], 1.0 op_sel_hi:[1,0]
	v_rcp_f32_e32 v60, v60
	v_rcp_f32_e32 v61, v61
	s_nop 0
	v_pk_mul_f32 v[58:59], v[58:59], v[60:61]
	s_nop 0
	v_cvt_pk_bf16_f32 v57, v58, v59
	global_store_dwordx2 v[64:65], v[56:57], off offset:8
.LBB0_219:
	s_or_b64 exec, exec, s[22:23]
	ds_read_b64 v[56:57], v66 offset:1280
	ds_read_b64 v[58:59], v67 offset:768
	ds_read_b64 v[74:75], v68 offset:256
	s_waitcnt lgkmcnt(0)
	v_lshlrev_b32_e32 v71, 16, v56
	v_and_b32_e32 v72, 0xffff0000, v56
	v_lshlrev_b32_e32 v60, 16, v57
	v_and_b32_e32 v61, 0xffff0000, v57
	v_lshlrev_b32_e32 v69, 16, v58
	v_and_b32_e32 v70, 0xffff0000, v58
	v_lshlrev_b32_e32 v58, 16, v59
	v_and_b32_e32 v59, 0xffff0000, v59
	v_lshlrev_b32_e32 v62, 16, v74
	v_and_b32_e32 v63, 0xffff0000, v74
	v_lshlrev_b32_e32 v56, 16, v75
	v_and_b32_e32 v57, 0xffff0000, v75
	v_mov_b32_dpp v71, v52 row_shr:1 row_mask:0xf bank_mask:0xf
	v_mov_b32_dpp v69, v52 row_shr:2 row_mask:0xf bank_mask:0xf
	v_mov_b32_dpp v62, v52 row_shr:3 row_mask:0xf bank_mask:0xf
	v_mov_b32_dpp v72, v53 row_shr:1 row_mask:0xf bank_mask:0xf
	v_mov_b32_dpp v70, v53 row_shr:2 row_mask:0xf bank_mask:0xf
	v_mov_b32_dpp v63, v53 row_shr:3 row_mask:0xf bank_mask:0xf
	v_mov_b32_dpp v60, v54 row_shr:1 row_mask:0xf bank_mask:0xf
	v_mov_b32_dpp v58, v54 row_shr:2 row_mask:0xf bank_mask:0xf
	v_mov_b32_dpp v56, v54 row_shr:3 row_mask:0xf bank_mask:0xf
	v_mov_b32_dpp v61, v55 row_shr:1 row_mask:0xf bank_mask:0xf
	v_mov_b32_dpp v59, v55 row_shr:2 row_mask:0xf bank_mask:0xf
	v_mov_b32_dpp v57, v55 row_shr:3 row_mask:0xf bank_mask:0xf
	s_and_saveexec_b64 s[22:23], s[2:3]
	s_cbranch_execz .LBB0_221
	ds_read_b128 v[74:77], v238 offset:4608
	ds_read_b128 v[78:81], v238 offset:3584
	ds_read_b128 v[82:85], v238 offset:2560
	v_cndmask_b32_e64 v73, v72, 0, s[8:9]
	ds_read_b128 v[86:89], v238 offset:1536
	s_nop 0
	ds_read_b128 v[90:93], v238 offset:512
	v_cndmask_b32_e64 v72, v71, 0, s[8:9]
	v_cndmask_b32_e64 v71, 0, v70, s[6:7]
	v_cndmask_b32_e64 v70, 0, v69, s[6:7]
	v_cndmask_b32_e64 v63, 0, v63, s[4:5]
	v_cndmask_b32_e64 v62, 0, v62, s[4:5]
	v_cndmask_b32_e64 v61, v61, 0, s[8:9]
	v_cndmask_b32_e64 v60, v60, 0, s[8:9]
	v_cndmask_b32_e64 v59, 0, v59, s[6:7]
	v_cndmask_b32_e64 v58, 0, v58, s[6:7]
	v_cndmask_b32_e64 v57, 0, v57, s[4:5]
	v_cndmask_b32_e64 v56, 0, v56, s[4:5]
	s_waitcnt lgkmcnt(0)
	v_pk_fma_f32 v[52:53], v[52:53], v[78:79], v[74:75]
	v_pk_fma_f32 v[54:55], v[54:55], v[80:81], v[76:77]
	v_pk_fma_f32 v[52:53], v[72:73], v[82:83], v[52:53]
	v_pk_fma_f32 v[54:55], v[60:61], v[84:85], v[54:55]
	v_pk_fma_f32 v[52:53], v[70:71], v[86:87], v[52:53]
	s_nop 0
	v_pk_fma_f32 v[52:53], v[62:63], v[90:91], v[52:53]
	v_pk_fma_f32 v[54:55], v[58:59], v[88:89], v[54:55]
	v_pk_fma_f32 v[54:55], v[56:57], v[92:93], v[54:55]
	v_pk_mul_f32 v[62:63], v[52:53], s[98:99] op_sel_hi:[1,0]
	v_exp_f32_e32 v62, v62
	v_exp_f32_e32 v63, v63
	s_nop 0
	v_pk_add_f32 v[62:63], v[62:63], 1.0 op_sel_hi:[1,0]
	v_rcp_f32_e32 v62, v62
	v_rcp_f32_e32 v63, v63
	s_nop 0
	v_pk_mul_f32 v[52:53], v[52:53], v[62:63]
	s_nop 0
	v_cvt_pk_bf16_f32 v52, v52, v53
	v_pk_mul_f32 v[56:57], v[54:55], s[98:99] op_sel_hi:[1,0]
	v_exp_f32_e32 v56, v56
	v_exp_f32_e32 v57, v57
	s_nop 0
	v_pk_add_f32 v[56:57], v[56:57], 1.0 op_sel_hi:[1,0]
	v_rcp_f32_e32 v56, v56
	v_rcp_f32_e32 v57, v57
	s_nop 0
	v_pk_mul_f32 v[54:55], v[54:55], v[56:57]
	s_nop 0
	v_cvt_pk_bf16_f32 v53, v54, v55
	global_store_dwordx2 v[64:65], v[52:53], off offset:256
;     __device__ __forceinline__ void operator()(const f32x4 (&acc)[2][2][4][2], const Unit& u, int wr, int wc, int fr, int fq, LAS unsigned char* hb) const {
;     ...
;             for (int m = 0; m < 4; ++m) { asm volatile("" ::: "memory"); __builtin_amdgcn_sched_barrier(0);
;                 const int q = 8 * ai + 4 * wr + m, prev = q > 0 ? q - 1 : 0; const int lr = ai * HALF + wr * 64 + m * 16 + fr, R = R0 + lr;
;                 const int Rc = R < 0 ? 0 : R; const int b = Rc / LL, p = Rc - b * LL;
;                 const bool ok = (lr >= H && R < TT);
;                 const unsigned ooff = ((unsigned)Rc * (unsigned)LDP + (unsigned)(OFF_XBC + ch0)) * 2u;
; #pragma unroll
;                 for (int bn = 0; bn < 4; ++bn) { const int bj = bn >> 1, n = bn & 1; const int co = bj * HALF + 4 * n;
;                     const unsigned woff = (unsigned)(ch0 + co) * 4u;
;                     const f32x4 w0 = *(const f32x4*)((const char*)cw + woff), w1 = *(const f32x4*)((const char*)cw + woff + XBCW * 4), w2 = *(const f32x4*)((const char*)cw + woff + 2 * XBCW * 4), w3 = *(const f32x4*)((const char*)cw + woff + 3 * XBCW * 4), bs = *(const f32x4*)((const char*)cb + woff);
;                     const LAS unsigned char* hp = hb + (prev * H * NCH + chl + co) * 2;
;                     const u32x2 q1 = *(const LAS u32x2*)(hp + hr1 * NCH * 2), q2 = *(const LAS u32x2*)(hp + hr2 * NCH * 2), q3 = *(const LAS u32x2*)(hp + hr3 * NCH * 2);
;                     const float h1[4] = {__builtin_bit_cast(float, q1.x << 16), __builtin_bit_cast(float, q1.x & 0xffff0000u), __builtin_bit_cast(float, q1.y << 16), __builtin_bit_cast(float, q1.y & 0xffff0000u)};
;                     const float h2[4] = {__builtin_bit_cast(float, q2.x << 16), __builtin_bit_cast(float, q2.x & 0xffff0000u), __builtin_bit_cast(float, q2.y << 16), __builtin_bit_cast(float, q2.y & 0xffff0000u)};
;                     const float h3[4] = {__builtin_bit_cast(float, q3.x << 16), __builtin_bit_cast(float, q3.x & 0xffff0000u), __builtin_bit_cast(float, q3.y << 16), __builtin_bit_cast(float, q3.y & 0xffff0000u)};
;                     const f32x4 gv = acc[ai][bj][m][n];
;                     float o[4];
; #pragma unroll
;                     for (int j = 0; j < 4; ++j) { const float g = gv[j];
;                         float g1 = dpp_row_shr<1>(h1[j], g), g2 = dpp_row_shr<2>(h2[j], g), g3 = dpp_row_shr<3>(h3[j], g);
.LBB0_221:
	s_or_b64 exec, exec, s[22:23]
	ds_read_b64 v[52:53], v66 offset:1288
	ds_read_b64 v[54:55], v67 offset:776
	ds_read_b64 v[66:67], v68 offset:264
	s_waitcnt lgkmcnt(0)
	v_lshlrev_b32_e32 v62, 16, v52
	v_and_b32_e32 v63, 0xffff0000, v52
	v_lshlrev_b32_e32 v56, 16, v53
	v_and_b32_e32 v57, 0xffff0000, v53
	v_lshlrev_b32_e32 v60, 16, v54
	v_and_b32_e32 v61, 0xffff0000, v54
	v_lshlrev_b32_e32 v54, 16, v55
	v_and_b32_e32 v55, 0xffff0000, v55
	v_lshlrev_b32_e32 v58, 16, v66
	v_and_b32_e32 v59, 0xffff0000, v66
	v_lshlrev_b32_e32 v52, 16, v67
	v_and_b32_e32 v53, 0xffff0000, v67
	v_mov_b32_dpp v62, v48 row_shr:1 row_mask:0xf bank_mask:0xf
	v_mov_b32_dpp v60, v48 row_shr:2 row_mask:0xf bank_mask:0xf
	v_mov_b32_dpp v58, v48 row_shr:3 row_mask:0xf bank_mask:0xf
	v_mov_b32_dpp v63, v49 row_shr:1 row_mask:0xf bank_mask:0xf
	v_mov_b32_dpp v61, v49 row_shr:2 row_mask:0xf bank_mask:0xf
	v_mov_b32_dpp v59, v49 row_shr:3 row_mask:0xf bank_mask:0xf
	v_mov_b32_dpp v56, v50 row_shr:1 row_mask:0xf bank_mask:0xf
	v_mov_b32_dpp v54, v50 row_shr:2 row_mask:0xf bank_mask:0xf
	v_mov_b32_dpp v52, v50 row_shr:3 row_mask:0xf bank_mask:0xf
	v_mov_b32_dpp v57, v51 row_shr:1 row_mask:0xf bank_mask:0xf
	v_mov_b32_dpp v55, v51 row_shr:2 row_mask:0xf bank_mask:0xf
	v_mov_b32_dpp v53, v51 row_shr:3 row_mask:0xf bank_mask:0xf
	s_and_saveexec_b64 s[22:23], s[2:3]
	s_cbranch_execz .LBB0_223
	ds_read_b128 v[66:69], v238 offset:4624
	ds_read_b128 v[70:73], v238 offset:3600
	ds_read_b128 v[74:77], v238 offset:2576
	v_cndmask_b32_e64 v63, v63, 0, s[8:9]
	ds_read_b128 v[78:81], v238 offset:1552
	s_nop 0
	ds_read_b128 v[82:85], v238 offset:528
	v_cndmask_b32_e64 v62, v62, 0, s[8:9]
	v_cndmask_b32_e64 v61, 0, v61, s[6:7]
	v_cndmask_b32_e64 v60, 0, v60, s[6:7]
	v_cndmask_b32_e64 v59, 0, v59, s[4:5]
	v_cndmask_b32_e64 v58, 0, v58, s[4:5]
	v_cndmask_b32_e64 v57, v57, 0, s[8:9]
	v_cndmask_b32_e64 v56, v56, 0, s[8:9]
	v_cndmask_b32_e64 v55, 0, v55, s[6:7]
	v_cndmask_b32_e64 v54, 0, v54, s[6:7]
	v_cndmask_b32_e64 v53, 0, v53, s[4:5]
	v_cndmask_b32_e64 v52, 0, v52, s[4:5]
	s_waitcnt lgkmcnt(0)
	v_pk_fma_f32 v[48:49], v[48:49], v[70:71], v[66:67]
	v_pk_fma_f32 v[50:51], v[50:51], v[72:73], v[68:69]
	v_pk_fma_f32 v[48:49], v[62:63], v[74:75], v[48:49]
	v_pk_fma_f32 v[50:51], v[56:57], v[76:77], v[50:51]
	v_pk_fma_f32 v[48:49], v[60:61], v[78:79], v[48:49]
	s_nop 0
	v_pk_fma_f32 v[48:49], v[58:59], v[82:83], v[48:49]
	v_pk_fma_f32 v[50:51], v[54:55], v[80:81], v[50:51]
	v_pk_fma_f32 v[50:51], v[52:53], v[84:85], v[50:51]
	v_pk_mul_f32 v[58:59], v[48:49], s[98:99] op_sel_hi:[1,0]
	v_exp_f32_e32 v58, v58
	v_exp_f32_e32 v59, v59
	s_nop 0
	v_pk_add_f32 v[58:59], v[58:59], 1.0 op_sel_hi:[1,0]
	v_rcp_f32_e32 v58, v58
	v_rcp_f32_e32 v59, v59
	s_nop 0
	v_pk_mul_f32 v[48:49], v[48:49], v[58:59]
	s_nop 0
	v_cvt_pk_bf16_f32 v48, v48, v49
	v_pk_mul_f32 v[52:53], v[50:51], s[98:99] op_sel_hi:[1,0]
	v_exp_f32_e32 v52, v52
	v_exp_f32_e32 v53, v53
	s_nop 0
	v_pk_add_f32 v[52:53], v[52:53], 1.0 op_sel_hi:[1,0]
	v_rcp_f32_e32 v52, v52
	v_rcp_f32_e32 v53, v53
	s_nop 0
	v_pk_mul_f32 v[50:51], v[50:51], v[52:53]
	s_nop 0
	v_cvt_pk_bf16_f32 v49, v50, v51
	global_store_dwordx2 v[64:65], v[48:49], off offset:264
.LBB0_223:
	s_or_b64 exec, exec, s[22:23]
	v_add_u32_e32 v48, 0x90, v161
	v_add_u32_e32 v49, s17, v48
	v_max_i32_e32 v50, 0, v49
	v_mul_hi_u32 v51, v50, s56
	v_lshrrev_b32_e32 v51, 11, v51
	v_cmp_lt_i32_e32 vcc, 2, v48
	v_mul_lo_u32 v48, v50, s51
	v_mul_u32_u24_e32 v51, 0x1010, v51
	v_add_lshl_u32 v136, v48, v164, 1
	v_add_u32_e32 v48, s42, v165
	v_sub_u32_e32 v51, v50, v51
	v_cmp_gt_i32_e64 s[4:5], s50, v49
	v_lshl_add_u32 v50, v48, 1, s53
	s_and_b64 s[2:3], vcc, s[4:5]
	v_cmp_eq_u32_e64 s[8:9], 0, v51
	v_cmp_lt_u32_e64 s[6:7], 1, v51
	v_cmp_lt_u32_e64 s[4:5], 2, v51
	v_add_u32_e32 v51, v50, v163
	ds_read_b64 v[48:49], v50 offset:1024
	v_add_u32_e32 v52, v50, v162
	ds_read_b64 v[66:67], v51 offset:512
	ds_read_b64 v[68:69], v52
	v_readlane_b32 s22, v237, 58
	v_readlane_b32 s23, v237, 59
	s_waitcnt lgkmcnt(0)
	v_lshlrev_b32_e32 v63, 16, v48
	v_and_b32_e32 v64, 0xffff0000, v48
	v_lshlrev_b32_e32 v57, 16, v49
	v_and_b32_e32 v58, 0xffff0000, v49
	v_lshlrev_b32_e32 v61, 16, v66
	v_and_b32_e32 v62, 0xffff0000, v66
	v_lshlrev_b32_e32 v55, 16, v67
	v_and_b32_e32 v56, 0xffff0000, v67
	v_lshlrev_b32_e32 v59, 16, v68
	v_and_b32_e32 v60, 0xffff0000, v68
	v_lshlrev_b32_e32 v53, 16, v69
	v_and_b32_e32 v54, 0xffff0000, v69
	v_mov_b32_dpp v63, v44 row_shr:1 row_mask:0xf bank_mask:0xf
	v_mov_b32_dpp v61, v44 row_shr:2 row_mask:0xf bank_mask:0xf
	v_mov_b32_dpp v59, v44 row_shr:3 row_mask:0xf bank_mask:0xf
	v_mov_b32_dpp v64, v45 row_shr:1 row_mask:0xf bank_mask:0xf
	v_mov_b32_dpp v62, v45 row_shr:2 row_mask:0xf bank_mask:0xf
	v_mov_b32_dpp v60, v45 row_shr:3 row_mask:0xf bank_mask:0xf
	v_mov_b32_dpp v57, v46 row_shr:1 row_mask:0xf bank_mask:0xf
	v_mov_b32_dpp v55, v46 row_shr:2 row_mask:0xf bank_mask:0xf
	v_mov_b32_dpp v53, v46 row_shr:3 row_mask:0xf bank_mask:0xf
	v_mov_b32_dpp v58, v47 row_shr:1 row_mask:0xf bank_mask:0xf
	v_mov_b32_dpp v56, v47 row_shr:2 row_mask:0xf bank_mask:0xf
	v_mov_b32_dpp v54, v47 row_shr:3 row_mask:0xf bank_mask:0xf
	v_lshl_add_u64 v[48:49], s[22:23], 0, v[136:137]
	s_and_saveexec_b64 s[22:23], s[2:3]
	s_cbranch_execz .LBB0_225
;     __device__ __forceinline__ void operator()(const f32x4 (&acc)[2][2][4][2], const Unit& u, int wr, int wc, int fr, int fq, LAS unsigned char* hb) const {
;     ...
;             for (int m = 0; m < 4; ++m) { asm volatile("" ::: "memory"); __builtin_amdgcn_sched_barrier(0);
;                 const int q = 8 * ai + 4 * wr + m, prev = q > 0 ? q - 1 : 0; const int lr = ai * HALF + wr * 64 + m * 16 + fr, R = R0 + lr;
;                 const int Rc = R < 0 ? 0 : R; const int b = Rc / LL, p = Rc - b * LL;
;                 const bool ok = (lr >= H && R < TT);
;                 const unsigned ooff = ((unsigned)Rc * (unsigned)LDP + (unsigned)(OFF_XBC + ch0)) * 2u;
; #pragma unroll
;                 for (int bn = 0; bn < 4; ++bn) { const int bj = bn >> 1, n = bn & 1; const int co = bj * HALF + 4 * n;
;                     const unsigned woff = (unsigned)(ch0 + co) * 4u;
;                     const f32x4 w0 = *(const f32x4*)((const char*)cw + woff), w1 = *(const f32x4*)((const char*)cw + woff + XBCW * 4), w2 = *(const f32x4*)((const char*)cw + woff + 2 * XBCW * 4), w3 = *(const f32x4*)((const char*)cw + woff + 3 * XBCW * 4), bs = *(const f32x4*)((const char*)cb + woff);
;                     const LAS unsigned char* hp = hb + (prev * H * NCH + chl + co) * 2;
;                     const u32x2 q1 = *(const LAS u32x2*)(hp + hr1 * NCH * 2), q2 = *(const LAS u32x2*)(hp + hr2 * NCH * 2), q3 = *(const LAS u32x2*)(hp + hr3 * NCH * 2);
;                     const float h1[4] = {__builtin_bit_cast(float, q1.x << 16), __builtin_bit_cast(float, q1.x & 0xffff0000u), __builtin_bit_cast(float, q1.y << 16), __builtin_bit_cast(float, q1.y & 0xffff0000u)};
;                     const float h2[4] = {__builtin_bit_cast(float, q2.x << 16), __builtin_bit_cast(float, q2.x & 0xffff0000u), __builtin_bit_cast(float, q2.y << 16), __builtin_bit_cast(float, q2.y & 0xffff0000u)};
;                     const float h3[4] = {__builtin_bit_cast(float, q3.x << 16), __builtin_bit_cast(float, q3.x & 0xffff0000u), __builtin_bit_cast(float, q3.y << 16), __builtin_bit_cast(float, q3.y & 0xffff0000u)};
;                     const f32x4 gv = acc[ai][bj][m][n];
;                     float o[4];
; #pragma unroll
;                     for (int j = 0; j < 4; ++j) { const float g = gv[j];
;                         float g1 = dpp_row_shr<1>(h1[j], g), g2 = dpp_row_shr<2>(h2[j], g), g3 = dpp_row_shr<3>(h3[j], g);
	ds_read_b128 v[66:69], v238 offset:4096
	ds_read_b128 v[70:73], v238 offset:3072
	ds_read_b128 v[74:77], v238 offset:2048
	v_cndmask_b32_e64 v65, v64, 0, s[8:9]
	ds_read_b128 v[78:81], v238 offset:1024
	s_nop 0
	ds_read_b128 v[82:85], v238
	v_cndmask_b32_e64 v64, v63, 0, s[8:9]
	v_cndmask_b32_e64 v63, 0, v62, s[6:7]
	v_cndmask_b32_e64 v62, 0, v61, s[6:7]
	v_cndmask_b32_e64 v61, 0, v60, s[4:5]
	v_cndmask_b32_e64 v60, 0, v59, s[4:5]
	s_waitcnt lgkmcnt(0)
	v_pk_fma_f32 v[44:45], v[44:45], v[70:71], v[66:67]
	v_pk_fma_f32 v[46:47], v[46:47], v[72:73], v[68:69]
	v_pk_fma_f32 v[44:45], v[64:65], v[74:75], v[44:45]
	s_nop 0
	v_pk_fma_f32 v[44:45], v[62:63], v[78:79], v[44:45]
	s_nop 0
	v_pk_fma_f32 v[44:45], v[60:61], v[82:83], v[44:45]
	s_nop 0
	v_pk_mul_f32 v[60:61], v[44:45], s[98:99] op_sel_hi:[1,0]
	v_exp_f32_e32 v60, v60
	v_exp_f32_e32 v61, v61
	s_nop 0
	v_pk_add_f32 v[60:61], v[60:61], 1.0 op_sel_hi:[1,0]
	v_rcp_f32_e32 v60, v60
	v_rcp_f32_e32 v61, v61
	v_cndmask_b32_e64 v59, v58, 0, s[8:9]
	v_cndmask_b32_e64 v58, v57, 0, s[8:9]
	v_pk_fma_f32 v[46:47], v[58:59], v[76:77], v[46:47]
	v_cndmask_b32_e64 v57, 0, v56, s[6:7]
	v_cndmask_b32_e64 v56, 0, v55, s[6:7]
	v_pk_fma_f32 v[46:47], v[56:57], v[80:81], v[46:47]
	v_cndmask_b32_e64 v55, 0, v54, s[4:5]
	v_cndmask_b32_e64 v54, 0, v53, s[4:5]
	v_pk_mul_f32 v[44:45], v[44:45], v[60:61]
	v_pk_fma_f32 v[46:47], v[54:55], v[84:85], v[46:47]
	v_cvt_pk_bf16_f32 v44, v44, v45
	v_pk_mul_f32 v[54:55], v[46:47], s[98:99] op_sel_hi:[1,0]
	v_exp_f32_e32 v54, v54
	v_exp_f32_e32 v55, v55
	s_nop 0
	v_pk_add_f32 v[54:55], v[54:55], 1.0 op_sel_hi:[1,0]
	v_rcp_f32_e32 v54, v54
	v_rcp_f32_e32 v55, v55
	s_nop 0
	v_pk_mul_f32 v[46:47], v[46:47], v[54:55]
	s_nop 0
	v_cvt_pk_bf16_f32 v45, v46, v47
	global_store_dwordx2 v[48:49], v[44:45], off
.LBB0_225:
	s_or_b64 exec, exec, s[22:23]
	ds_read_b64 v[44:45], v50 offset:1032
	ds_read_b64 v[46:47], v51 offset:520
	ds_read_b64 v[62:63], v52 offset:8
	s_waitcnt lgkmcnt(0)
	v_lshlrev_b32_e32 v59, 16, v44
	v_and_b32_e32 v60, 0xffff0000, v44
	v_lshlrev_b32_e32 v53, 16, v45
	v_and_b32_e32 v54, 0xffff0000, v45
	v_lshlrev_b32_e32 v57, 16, v46
	v_and_b32_e32 v58, 0xffff0000, v46
	v_lshlrev_b32_e32 v46, 16, v47
	v_and_b32_e32 v47, 0xffff0000, v47
	v_lshlrev_b32_e32 v55, 16, v62
	v_and_b32_e32 v56, 0xffff0000, v62
	v_lshlrev_b32_e32 v44, 16, v63
	v_and_b32_e32 v45, 0xffff0000, v63
	v_mov_b32_dpp v59, v40 row_shr:1 row_mask:0xf bank_mask:0xf
	v_mov_b32_dpp v57, v40 row_shr:2 row_mask:0xf bank_mask:0xf
	v_mov_b32_dpp v55, v40 row_shr:3 row_mask:0xf bank_mask:0xf
	v_mov_b32_dpp v60, v41 row_shr:1 row_mask:0xf bank_mask:0xf
	v_mov_b32_dpp v58, v41 row_shr:2 row_mask:0xf bank_mask:0xf
	v_mov_b32_dpp v56, v41 row_shr:3 row_mask:0xf bank_mask:0xf
	v_mov_b32_dpp v53, v42 row_shr:1 row_mask:0xf bank_mask:0xf
	v_mov_b32_dpp v46, v42 row_shr:2 row_mask:0xf bank_mask:0xf
	v_mov_b32_dpp v44, v42 row_shr:3 row_mask:0xf bank_mask:0xf
	v_mov_b32_dpp v54, v43 row_shr:1 row_mask:0xf bank_mask:0xf
	v_mov_b32_dpp v47, v43 row_shr:2 row_mask:0xf bank_mask:0xf
	v_mov_b32_dpp v45, v43 row_shr:3 row_mask:0xf bank_mask:0xf
	s_and_saveexec_b64 s[22:23], s[2:3]
	s_cbranch_execz .LBB0_227
	ds_read_b128 v[62:65], v238 offset:4112
	ds_read_b128 v[66:69], v238 offset:3088
	ds_read_b128 v[70:73], v238 offset:2064
	v_cndmask_b32_e64 v61, v60, 0, s[8:9]
	ds_read_b128 v[74:77], v238 offset:1040
	s_nop 0
	ds_read_b128 v[78:81], v238 offset:16
	v_cndmask_b32_e64 v60, v59, 0, s[8:9]
	v_cndmask_b32_e64 v59, 0, v58, s[6:7]
	v_cndmask_b32_e64 v58, 0, v57, s[6:7]
	v_cndmask_b32_e64 v57, 0, v56, s[4:5]
	v_cndmask_b32_e64 v56, 0, v55, s[4:5]
	v_cndmask_b32_e64 v47, 0, v47, s[6:7]
	v_cndmask_b32_e64 v46, 0, v46, s[6:7]
	v_cndmask_b32_e64 v45, 0, v45, s[4:5]
	v_cndmask_b32_e64 v44, 0, v44, s[4:5]
	s_waitcnt lgkmcnt(0)
	v_pk_fma_f32 v[40:41], v[40:41], v[66:67], v[62:63]
	v_pk_fma_f32 v[42:43], v[42:43], v[68:69], v[64:65]
	v_pk_fma_f32 v[40:41], v[60:61], v[70:71], v[40:41]
	s_nop 0
	v_pk_fma_f32 v[40:41], v[58:59], v[74:75], v[40:41]
	s_nop 0
	v_pk_fma_f32 v[40:41], v[56:57], v[78:79], v[40:41]
	s_nop 0
	v_pk_mul_f32 v[56:57], v[40:41], s[98:99] op_sel_hi:[1,0]
	v_exp_f32_e32 v56, v56
	v_exp_f32_e32 v57, v57
	s_nop 0
	v_pk_add_f32 v[56:57], v[56:57], 1.0 op_sel_hi:[1,0]
	v_rcp_f32_e32 v56, v56
	v_rcp_f32_e32 v57, v57
	v_cndmask_b32_e64 v55, v54, 0, s[8:9]
	v_cndmask_b32_e64 v54, v53, 0, s[8:9]
	v_pk_fma_f32 v[42:43], v[54:55], v[72:73], v[42:43]
	v_pk_mul_f32 v[40:41], v[40:41], v[56:57]
	v_pk_fma_f32 v[42:43], v[46:47], v[76:77], v[42:43]
	v_cvt_pk_bf16_f32 v40, v40, v41
	v_pk_fma_f32 v[42:43], v[44:45], v[80:81], v[42:43]
	s_nop 0
	v_pk_mul_f32 v[44:45], v[42:43], s[98:99] op_sel_hi:[1,0]
	v_exp_f32_e32 v44, v44
	v_exp_f32_e32 v45, v45
	s_nop 0
	v_pk_add_f32 v[44:45], v[44:45], 1.0 op_sel_hi:[1,0]
	v_rcp_f32_e32 v44, v44
	v_rcp_f32_e32 v45, v45
	s_nop 0
	v_pk_mul_f32 v[42:43], v[42:43], v[44:45]
	s_nop 0
	v_cvt_pk_bf16_f32 v41, v42, v43
	global_store_dwordx2 v[48:49], v[40:41], off offset:8
;     __device__ __forceinline__ void operator()(const f32x4 (&acc)[2][2][4][2], const Unit& u, int wr, int wc, int fr, int fq, LAS unsigned char* hb) const {
;     ...
;             for (int m = 0; m < 4; ++m) { asm volatile("" ::: "memory"); __builtin_amdgcn_sched_barrier(0);
;                 const int q = 8 * ai + 4 * wr + m, prev = q > 0 ? q - 1 : 0; const int lr = ai * HALF + wr * 64 + m * 16 + fr, R = R0 + lr;
;                 const int Rc = R < 0 ? 0 : R; const int b = Rc / LL, p = Rc - b * LL;
;                 const bool ok = (lr >= H && R < TT);
;                 const unsigned ooff = ((unsigned)Rc * (unsigned)LDP + (unsigned)(OFF_XBC + ch0)) * 2u;
; #pragma unroll
;                 for (int bn = 0; bn < 4; ++bn) { const int bj = bn >> 1, n = bn & 1; const int co = bj * HALF + 4 * n;
;                     const unsigned woff = (unsigned)(ch0 + co) * 4u;
;                     const f32x4 w0 = *(const f32x4*)((const char*)cw + woff), w1 = *(const f32x4*)((const char*)cw + woff + XBCW * 4), w2 = *(const f32x4*)((const char*)cw + woff + 2 * XBCW * 4), w3 = *(const f32x4*)((const char*)cw + woff + 3 * XBCW * 4), bs = *(const f32x4*)((const char*)cb + woff);
;                     const LAS unsigned char* hp = hb + (prev * H * NCH + chl + co) * 2;
;                     const u32x2 q1 = *(const LAS u32x2*)(hp + hr1 * NCH * 2), q2 = *(const LAS u32x2*)(hp + hr2 * NCH * 2), q3 = *(const LAS u32x2*)(hp + hr3 * NCH * 2);
;                     const float h1[4] = {__builtin_bit_cast(float, q1.x << 16), __builtin_bit_cast(float, q1.x & 0xffff0000u), __builtin_bit_cast(float, q1.y << 16), __builtin_bit_cast(float, q1.y & 0xffff0000u)};
;                     const float h2[4] = {__builtin_bit_cast(float, q2.x << 16), __builtin_bit_cast(float, q2.x & 0xffff0000u), __builtin_bit_cast(float, q2.y << 16), __builtin_bit_cast(float, q2.y & 0xffff0000u)};
;                     const float h3[4] = {__builtin_bit_cast(float, q3.x << 16), __builtin_bit_cast(float, q3.x & 0xffff0000u), __builtin_bit_cast(float, q3.y << 16), __builtin_bit_cast(float, q3.y & 0xffff0000u)};
;                     const f32x4 gv = acc[ai][bj][m][n];
;                     float o[4];
; #pragma unroll
;                     for (int j = 0; j < 4; ++j) { const float g = gv[j];
;                         float g1 = dpp_row_shr<1>(h1[j], g), g2 = dpp_row_shr<2>(h2[j], g), g3 = dpp_row_shr<3>(h3[j], g);
.LBB0_227:
	s_or_b64 exec, exec, s[22:23]
	ds_read_b64 v[40:41], v50 offset:1280
	ds_read_b64 v[42:43], v51 offset:768
	ds_read_b64 v[58:59], v52 offset:256
	s_waitcnt lgkmcnt(0)
	v_lshlrev_b32_e32 v55, 16, v40
	v_and_b32_e32 v56, 0xffff0000, v40
	v_lshlrev_b32_e32 v44, 16, v41
	v_and_b32_e32 v45, 0xffff0000, v41
	v_lshlrev_b32_e32 v53, 16, v42
	v_and_b32_e32 v54, 0xffff0000, v42
	v_lshlrev_b32_e32 v42, 16, v43
	v_and_b32_e32 v43, 0xffff0000, v43
	v_lshlrev_b32_e32 v46, 16, v58
	v_and_b32_e32 v47, 0xffff0000, v58
	v_lshlrev_b32_e32 v40, 16, v59
	v_and_b32_e32 v41, 0xffff0000, v59
	v_mov_b32_dpp v55, v36 row_shr:1 row_mask:0xf bank_mask:0xf
	v_mov_b32_dpp v53, v36 row_shr:2 row_mask:0xf bank_mask:0xf
	v_mov_b32_dpp v46, v36 row_shr:3 row_mask:0xf bank_mask:0xf
	v_mov_b32_dpp v56, v37 row_shr:1 row_mask:0xf bank_mask:0xf
	v_mov_b32_dpp v54, v37 row_shr:2 row_mask:0xf bank_mask:0xf
	v_mov_b32_dpp v47, v37 row_shr:3 row_mask:0xf bank_mask:0xf
	v_mov_b32_dpp v44, v38 row_shr:1 row_mask:0xf bank_mask:0xf
	v_mov_b32_dpp v42, v38 row_shr:2 row_mask:0xf bank_mask:0xf
	v_mov_b32_dpp v40, v38 row_shr:3 row_mask:0xf bank_mask:0xf
	v_mov_b32_dpp v45, v39 row_shr:1 row_mask:0xf bank_mask:0xf
	v_mov_b32_dpp v43, v39 row_shr:2 row_mask:0xf bank_mask:0xf
	v_mov_b32_dpp v41, v39 row_shr:3 row_mask:0xf bank_mask:0xf
	s_and_saveexec_b64 s[22:23], s[2:3]
	s_cbranch_execz .LBB0_229
	ds_read_b128 v[58:61], v238 offset:4608
	ds_read_b128 v[62:65], v238 offset:3584
	ds_read_b128 v[66:69], v238 offset:2560
	v_cndmask_b32_e64 v57, v56, 0, s[8:9]
	ds_read_b128 v[70:73], v238 offset:1536
	s_nop 0
	ds_read_b128 v[74:77], v238 offset:512
	v_cndmask_b32_e64 v56, v55, 0, s[8:9]
	v_cndmask_b32_e64 v55, 0, v54, s[6:7]
	v_cndmask_b32_e64 v54, 0, v53, s[6:7]
	v_cndmask_b32_e64 v47, 0, v47, s[4:5]
	v_cndmask_b32_e64 v46, 0, v46, s[4:5]
	v_cndmask_b32_e64 v45, v45, 0, s[8:9]
	v_cndmask_b32_e64 v44, v44, 0, s[8:9]
	v_cndmask_b32_e64 v43, 0, v43, s[6:7]
	v_cndmask_b32_e64 v42, 0, v42, s[6:7]
	v_cndmask_b32_e64 v41, 0, v41, s[4:5]
	v_cndmask_b32_e64 v40, 0, v40, s[4:5]
	s_waitcnt lgkmcnt(0)
	v_pk_fma_f32 v[36:37], v[36:37], v[62:63], v[58:59]
	v_pk_fma_f32 v[38:39], v[38:39], v[64:65], v[60:61]
	v_pk_fma_f32 v[36:37], v[56:57], v[66:67], v[36:37]
	v_pk_fma_f32 v[38:39], v[44:45], v[68:69], v[38:39]
	v_pk_fma_f32 v[36:37], v[54:55], v[70:71], v[36:37]
	s_nop 0
	v_pk_fma_f32 v[36:37], v[46:47], v[74:75], v[36:37]
	v_pk_fma_f32 v[38:39], v[42:43], v[72:73], v[38:39]
	v_pk_fma_f32 v[38:39], v[40:41], v[76:77], v[38:39]
	v_pk_mul_f32 v[46:47], v[36:37], s[98:99] op_sel_hi:[1,0]
	v_exp_f32_e32 v46, v46
	v_exp_f32_e32 v47, v47
	s_nop 0
	v_pk_add_f32 v[46:47], v[46:47], 1.0 op_sel_hi:[1,0]
	v_rcp_f32_e32 v46, v46
	v_rcp_f32_e32 v47, v47
	s_nop 0
	v_pk_mul_f32 v[36:37], v[36:37], v[46:47]
	s_nop 0
	v_cvt_pk_bf16_f32 v36, v36, v37
	v_pk_mul_f32 v[40:41], v[38:39], s[98:99] op_sel_hi:[1,0]
	v_exp_f32_e32 v40, v40
	v_exp_f32_e32 v41, v41
	s_nop 0
	v_pk_add_f32 v[40:41], v[40:41], 1.0 op_sel_hi:[1,0]
	v_rcp_f32_e32 v40, v40
	v_rcp_f32_e32 v41, v41
	s_nop 0
	v_pk_mul_f32 v[38:39], v[38:39], v[40:41]
	s_nop 0
	v_cvt_pk_bf16_f32 v37, v38, v39
	global_store_dwordx2 v[48:49], v[36:37], off offset:256
.LBB0_229:
	s_or_b64 exec, exec, s[22:23]
	ds_read_b64 v[36:37], v50 offset:1288
	ds_read_b64 v[38:39], v51 offset:776
	ds_read_b64 v[50:51], v52 offset:264
	s_waitcnt lgkmcnt(0)
	v_lshlrev_b32_e32 v46, 16, v36
	v_and_b32_e32 v47, 0xffff0000, v36
	v_lshlrev_b32_e32 v40, 16, v37
	v_and_b32_e32 v41, 0xffff0000, v37
	v_lshlrev_b32_e32 v44, 16, v38
	v_and_b32_e32 v45, 0xffff0000, v38
	v_lshlrev_b32_e32 v38, 16, v39
	v_and_b32_e32 v39, 0xffff0000, v39
	v_lshlrev_b32_e32 v42, 16, v50
	v_and_b32_e32 v43, 0xffff0000, v50
	v_lshlrev_b32_e32 v36, 16, v51
	v_and_b32_e32 v37, 0xffff0000, v51
	v_mov_b32_dpp v46, v32 row_shr:1 row_mask:0xf bank_mask:0xf
	v_mov_b32_dpp v44, v32 row_shr:2 row_mask:0xf bank_mask:0xf
	v_mov_b32_dpp v42, v32 row_shr:3 row_mask:0xf bank_mask:0xf
	v_mov_b32_dpp v47, v33 row_shr:1 row_mask:0xf bank_mask:0xf
	v_mov_b32_dpp v45, v33 row_shr:2 row_mask:0xf bank_mask:0xf
	v_mov_b32_dpp v43, v33 row_shr:3 row_mask:0xf bank_mask:0xf
	v_mov_b32_dpp v40, v34 row_shr:1 row_mask:0xf bank_mask:0xf
	v_mov_b32_dpp v38, v34 row_shr:2 row_mask:0xf bank_mask:0xf
	v_mov_b32_dpp v36, v34 row_shr:3 row_mask:0xf bank_mask:0xf
	v_mov_b32_dpp v41, v35 row_shr:1 row_mask:0xf bank_mask:0xf
	v_mov_b32_dpp v39, v35 row_shr:2 row_mask:0xf bank_mask:0xf
	v_mov_b32_dpp v37, v35 row_shr:3 row_mask:0xf bank_mask:0xf
	s_and_saveexec_b64 s[22:23], s[2:3]
	s_cbranch_execz .LBB0_231
	ds_read_b128 v[50:53], v238 offset:4624
	ds_read_b128 v[54:57], v238 offset:3600
	ds_read_b128 v[58:61], v238 offset:2576
	v_cndmask_b32_e64 v47, v47, 0, s[8:9]
	ds_read_b128 v[62:65], v238 offset:1552
	s_nop 0
	ds_read_b128 v[66:69], v238 offset:528
	v_cndmask_b32_e64 v46, v46, 0, s[8:9]
	v_cndmask_b32_e64 v45, 0, v45, s[6:7]
	v_cndmask_b32_e64 v44, 0, v44, s[6:7]
	v_cndmask_b32_e64 v43, 0, v43, s[4:5]
	v_cndmask_b32_e64 v42, 0, v42, s[4:5]
	v_cndmask_b32_e64 v41, v41, 0, s[8:9]
	v_cndmask_b32_e64 v40, v40, 0, s[8:9]
	v_cndmask_b32_e64 v39, 0, v39, s[6:7]
	v_cndmask_b32_e64 v38, 0, v38, s[6:7]
	v_cndmask_b32_e64 v37, 0, v37, s[4:5]
	v_cndmask_b32_e64 v36, 0, v36, s[4:5]
	s_waitcnt lgkmcnt(0)
	v_pk_fma_f32 v[32:33], v[32:33], v[54:55], v[50:51]
	v_pk_fma_f32 v[34:35], v[34:35], v[56:57], v[52:53]
	v_pk_fma_f32 v[32:33], v[46:47], v[58:59], v[32:33]
	v_pk_fma_f32 v[34:35], v[40:41], v[60:61], v[34:35]
	v_pk_fma_f32 v[32:33], v[44:45], v[62:63], v[32:33]
	s_nop 0
	v_pk_fma_f32 v[32:33], v[42:43], v[66:67], v[32:33]
	v_pk_fma_f32 v[34:35], v[38:39], v[64:65], v[34:35]
	v_pk_fma_f32 v[34:35], v[36:37], v[68:69], v[34:35]
	v_pk_mul_f32 v[42:43], v[32:33], s[98:99] op_sel_hi:[1,0]
	v_exp_f32_e32 v42, v42
	v_exp_f32_e32 v43, v43
	s_nop 0
	v_pk_add_f32 v[42:43], v[42:43], 1.0 op_sel_hi:[1,0]
	v_rcp_f32_e32 v42, v42
	v_rcp_f32_e32 v43, v43
	s_nop 0
	v_pk_mul_f32 v[32:33], v[32:33], v[42:43]
	s_nop 0
	v_cvt_pk_bf16_f32 v32, v32, v33
	v_pk_mul_f32 v[36:37], v[34:35], s[98:99] op_sel_hi:[1,0]
	v_exp_f32_e32 v36, v36
	v_exp_f32_e32 v37, v37
	s_nop 0
	v_pk_add_f32 v[36:37], v[36:37], 1.0 op_sel_hi:[1,0]
	v_rcp_f32_e32 v36, v36
	v_rcp_f32_e32 v37, v37
	s_nop 0
	v_pk_mul_f32 v[34:35], v[34:35], v[36:37]
	s_nop 0
	v_cvt_pk_bf16_f32 v33, v34, v35
	global_store_dwordx2 v[48:49], v[32:33], off offset:264
;     __device__ __forceinline__ void operator()(const f32x4 (&acc)[2][2][4][2], const Unit& u, int wr, int wc, int fr, int fq, LAS unsigned char* hb) const {
;     ...
;             for (int m = 0; m < 4; ++m) { asm volatile("" ::: "memory"); __builtin_amdgcn_sched_barrier(0);
;                 const int q = 8 * ai + 4 * wr + m, prev = q > 0 ? q - 1 : 0; const int lr = ai * HALF + wr * 64 + m * 16 + fr, R = R0 + lr;
;                 const int Rc = R < 0 ? 0 : R; const int b = Rc / LL, p = Rc - b * LL;
;                 const bool ok = (lr >= H && R < TT);
;                 const unsigned ooff = ((unsigned)Rc * (unsigned)LDP + (unsigned)(OFF_XBC + ch0)) * 2u;
; #pragma unroll
;                 for (int bn = 0; bn < 4; ++bn) { const int bj = bn >> 1, n = bn & 1; const int co = bj * HALF + 4 * n;
;                     const unsigned woff = (unsigned)(ch0 + co) * 4u;
;                     const f32x4 w0 = *(const f32x4*)((const char*)cw + woff), w1 = *(const f32x4*)((const char*)cw + woff + XBCW * 4), w2 = *(const f32x4*)((const char*)cw + woff + 2 * XBCW * 4), w3 = *(const f32x4*)((const char*)cw + woff + 3 * XBCW * 4), bs = *(const f32x4*)((const char*)cb + woff);
;                     const LAS unsigned char* hp = hb + (prev * H * NCH + chl + co) * 2;
;                     const u32x2 q1 = *(const LAS u32x2*)(hp + hr1 * NCH * 2), q2 = *(const LAS u32x2*)(hp + hr2 * NCH * 2), q3 = *(const LAS u32x2*)(hp + hr3 * NCH * 2);
;                     const float h1[4] = {__builtin_bit_cast(float, q1.x << 16), __builtin_bit_cast(float, q1.x & 0xffff0000u), __builtin_bit_cast(float, q1.y << 16), __builtin_bit_cast(float, q1.y & 0xffff0000u)};
;                     const float h2[4] = {__builtin_bit_cast(float, q2.x << 16), __builtin_bit_cast(float, q2.x & 0xffff0000u), __builtin_bit_cast(float, q2.y << 16), __builtin_bit_cast(float, q2.y & 0xffff0000u)};
;                     const float h3[4] = {__builtin_bit_cast(float, q3.x << 16), __builtin_bit_cast(float, q3.x & 0xffff0000u), __builtin_bit_cast(float, q3.y << 16), __builtin_bit_cast(float, q3.y & 0xffff0000u)};
;                     const f32x4 gv = acc[ai][bj][m][n];
;                     float o[4];
; #pragma unroll
;                     for (int j = 0; j < 4; ++j) { const float g = gv[j];
;                         float g1 = dpp_row_shr<1>(h1[j], g), g2 = dpp_row_shr<2>(h2[j], g), g3 = dpp_row_shr<3>(h3[j], g);
.LBB0_231:
	s_or_b64 exec, exec, s[22:23]
	v_add_u32_e32 v32, 0xa0, v161
	v_add_u32_e32 v33, s17, v32
	v_max_i32_e32 v34, 0, v33
	v_mul_hi_u32 v35, v34, s56
	v_lshrrev_b32_e32 v35, 11, v35
	v_cmp_lt_i32_e32 vcc, 2, v32
	v_mul_lo_u32 v32, v34, s51
	v_mul_u32_u24_e32 v35, 0x1010, v35
	v_add_lshl_u32 v136, v32, v164, 1
	v_add_u32_e32 v32, s43, v165
	v_sub_u32_e32 v35, v34, v35
	v_cmp_gt_i32_e64 s[4:5], s50, v33
	v_lshl_add_u32 v34, v32, 1, s53
	s_and_b64 s[2:3], vcc, s[4:5]
	v_cmp_eq_u32_e64 s[8:9], 0, v35
	v_cmp_lt_u32_e64 s[6:7], 1, v35
	v_cmp_lt_u32_e64 s[4:5], 2, v35
	v_add_u32_e32 v35, v34, v163
	ds_read_b64 v[32:33], v34 offset:1024
	v_add_u32_e32 v36, v34, v162
	ds_read_b64 v[50:51], v35 offset:512
	ds_read_b64 v[52:53], v36
	v_readlane_b32 s22, v237, 58
	v_readlane_b32 s23, v237, 59
	s_waitcnt lgkmcnt(0)
	v_lshlrev_b32_e32 v47, 16, v32
	v_and_b32_e32 v48, 0xffff0000, v32
	v_lshlrev_b32_e32 v41, 16, v33
	v_and_b32_e32 v42, 0xffff0000, v33
	v_lshlrev_b32_e32 v45, 16, v50
	v_and_b32_e32 v46, 0xffff0000, v50
	v_lshlrev_b32_e32 v39, 16, v51
	v_and_b32_e32 v40, 0xffff0000, v51
	v_lshlrev_b32_e32 v43, 16, v52
	v_and_b32_e32 v44, 0xffff0000, v52
	v_lshlrev_b32_e32 v37, 16, v53
	v_and_b32_e32 v38, 0xffff0000, v53
	v_mov_b32_dpp v47, v28 row_shr:1 row_mask:0xf bank_mask:0xf
	v_mov_b32_dpp v45, v28 row_shr:2 row_mask:0xf bank_mask:0xf
	v_mov_b32_dpp v43, v28 row_shr:3 row_mask:0xf bank_mask:0xf
	v_mov_b32_dpp v48, v29 row_shr:1 row_mask:0xf bank_mask:0xf
	v_mov_b32_dpp v46, v29 row_shr:2 row_mask:0xf bank_mask:0xf
	v_mov_b32_dpp v44, v29 row_shr:3 row_mask:0xf bank_mask:0xf
	v_mov_b32_dpp v41, v30 row_shr:1 row_mask:0xf bank_mask:0xf
	v_mov_b32_dpp v39, v30 row_shr:2 row_mask:0xf bank_mask:0xf
	v_mov_b32_dpp v37, v30 row_shr:3 row_mask:0xf bank_mask:0xf
	v_mov_b32_dpp v42, v31 row_shr:1 row_mask:0xf bank_mask:0xf
	v_mov_b32_dpp v40, v31 row_shr:2 row_mask:0xf bank_mask:0xf
	v_mov_b32_dpp v38, v31 row_shr:3 row_mask:0xf bank_mask:0xf
	v_lshl_add_u64 v[32:33], s[22:23], 0, v[136:137]
	s_and_saveexec_b64 s[22:23], s[2:3]
	s_cbranch_execz .LBB0_233
	ds_read_b128 v[50:53], v238 offset:4096
	ds_read_b128 v[54:57], v238 offset:3072
	ds_read_b128 v[58:61], v238 offset:2048
	v_cndmask_b32_e64 v49, v48, 0, s[8:9]
	ds_read_b128 v[62:65], v238 offset:1024
	s_nop 0
	ds_read_b128 v[66:69], v238
	v_cndmask_b32_e64 v48, v47, 0, s[8:9]
	v_cndmask_b32_e64 v47, 0, v46, s[6:7]
	v_cndmask_b32_e64 v46, 0, v45, s[6:7]
	v_cndmask_b32_e64 v45, 0, v44, s[4:5]
	v_cndmask_b32_e64 v44, 0, v43, s[4:5]
	s_waitcnt lgkmcnt(0)
	v_pk_fma_f32 v[28:29], v[28:29], v[54:55], v[50:51]
	v_pk_fma_f32 v[30:31], v[30:31], v[56:57], v[52:53]
	v_pk_fma_f32 v[28:29], v[48:49], v[58:59], v[28:29]
	s_nop 0
	v_pk_fma_f32 v[28:29], v[46:47], v[62:63], v[28:29]
	s_nop 0
	v_pk_fma_f32 v[28:29], v[44:45], v[66:67], v[28:29]
	s_nop 0
	v_pk_mul_f32 v[44:45], v[28:29], s[98:99] op_sel_hi:[1,0]
	v_exp_f32_e32 v44, v44
	v_exp_f32_e32 v45, v45
	s_nop 0
	v_pk_add_f32 v[44:45], v[44:45], 1.0 op_sel_hi:[1,0]
	v_rcp_f32_e32 v44, v44
	v_rcp_f32_e32 v45, v45
	v_cndmask_b32_e64 v43, v42, 0, s[8:9]
	v_cndmask_b32_e64 v42, v41, 0, s[8:9]
	v_pk_fma_f32 v[30:31], v[42:43], v[60:61], v[30:31]
	v_cndmask_b32_e64 v41, 0, v40, s[6:7]
	v_cndmask_b32_e64 v40, 0, v39, s[6:7]
	v_pk_fma_f32 v[30:31], v[40:41], v[64:65], v[30:31]
	v_cndmask_b32_e64 v39, 0, v38, s[4:5]
	v_cndmask_b32_e64 v38, 0, v37, s[4:5]
	v_pk_mul_f32 v[28:29], v[28:29], v[44:45]
	v_pk_fma_f32 v[30:31], v[38:39], v[68:69], v[30:31]
	v_cvt_pk_bf16_f32 v28, v28, v29
	v_pk_mul_f32 v[38:39], v[30:31], s[98:99] op_sel_hi:[1,0]
	v_exp_f32_e32 v38, v38
	v_exp_f32_e32 v39, v39
	s_nop 0
	v_pk_add_f32 v[38:39], v[38:39], 1.0 op_sel_hi:[1,0]
	v_rcp_f32_e32 v38, v38
	v_rcp_f32_e32 v39, v39
	s_nop 0
	v_pk_mul_f32 v[30:31], v[30:31], v[38:39]
	s_nop 0
	v_cvt_pk_bf16_f32 v29, v30, v31
	global_store_dwordx2 v[32:33], v[28:29], off
.LBB0_233:
	s_or_b64 exec, exec, s[22:23]
	ds_read_b64 v[28:29], v34 offset:1032
	ds_read_b64 v[30:31], v35 offset:520
	ds_read_b64 v[46:47], v36 offset:8
	s_waitcnt lgkmcnt(0)
	v_lshlrev_b32_e32 v43, 16, v28
	v_and_b32_e32 v44, 0xffff0000, v28
	v_lshlrev_b32_e32 v37, 16, v29
	v_and_b32_e32 v38, 0xffff0000, v29
	v_lshlrev_b32_e32 v41, 16, v30
	v_and_b32_e32 v42, 0xffff0000, v30
	v_lshlrev_b32_e32 v30, 16, v31
	v_and_b32_e32 v31, 0xffff0000, v31
	v_lshlrev_b32_e32 v39, 16, v46
	v_and_b32_e32 v40, 0xffff0000, v46
	v_lshlrev_b32_e32 v28, 16, v47
	v_and_b32_e32 v29, 0xffff0000, v47
	v_mov_b32_dpp v43, v24 row_shr:1 row_mask:0xf bank_mask:0xf
	v_mov_b32_dpp v41, v24 row_shr:2 row_mask:0xf bank_mask:0xf
	v_mov_b32_dpp v39, v24 row_shr:3 row_mask:0xf bank_mask:0xf
	v_mov_b32_dpp v44, v25 row_shr:1 row_mask:0xf bank_mask:0xf
	v_mov_b32_dpp v42, v25 row_shr:2 row_mask:0xf bank_mask:0xf
	v_mov_b32_dpp v40, v25 row_shr:3 row_mask:0xf bank_mask:0xf
	v_mov_b32_dpp v37, v26 row_shr:1 row_mask:0xf bank_mask:0xf
	v_mov_b32_dpp v30, v26 row_shr:2 row_mask:0xf bank_mask:0xf
	v_mov_b32_dpp v28, v26 row_shr:3 row_mask:0xf bank_mask:0xf
	v_mov_b32_dpp v38, v27 row_shr:1 row_mask:0xf bank_mask:0xf
	v_mov_b32_dpp v31, v27 row_shr:2 row_mask:0xf bank_mask:0xf
	v_mov_b32_dpp v29, v27 row_shr:3 row_mask:0xf bank_mask:0xf
	s_and_saveexec_b64 s[22:23], s[2:3]
	s_cbranch_execz .LBB0_235
;     __device__ __forceinline__ void operator()(const f32x4 (&acc)[2][2][4][2], const Unit& u, int wr, int wc, int fr, int fq, LAS unsigned char* hb) const {
;     ...
;             for (int m = 0; m < 4; ++m) { asm volatile("" ::: "memory"); __builtin_amdgcn_sched_barrier(0);
;                 const int q = 8 * ai + 4 * wr + m, prev = q > 0 ? q - 1 : 0; const int lr = ai * HALF + wr * 64 + m * 16 + fr, R = R0 + lr;
;                 const int Rc = R < 0 ? 0 : R; const int b = Rc / LL, p = Rc - b * LL;
;                 const bool ok = (lr >= H && R < TT);
;                 const unsigned ooff = ((unsigned)Rc * (unsigned)LDP + (unsigned)(OFF_XBC + ch0)) * 2u;
; #pragma unroll
;                 for (int bn = 0; bn < 4; ++bn) { const int bj = bn >> 1, n = bn & 1; const int co = bj * HALF + 4 * n;
;                     const unsigned woff = (unsigned)(ch0 + co) * 4u;
;                     const f32x4 w0 = *(const f32x4*)((const char*)cw + woff), w1 = *(const f32x4*)((const char*)cw + woff + XBCW * 4), w2 = *(const f32x4*)((const char*)cw + woff + 2 * XBCW * 4), w3 = *(const f32x4*)((const char*)cw + woff + 3 * XBCW * 4), bs = *(const f32x4*)((const char*)cb + woff);
;                     const LAS unsigned char* hp = hb + (prev * H * NCH + chl + co) * 2;
;                     const u32x2 q1 = *(const LAS u32x2*)(hp + hr1 * NCH * 2), q2 = *(const LAS u32x2*)(hp + hr2 * NCH * 2), q3 = *(const LAS u32x2*)(hp + hr3 * NCH * 2);
;                     const float h1[4] = {__builtin_bit_cast(float, q1.x << 16), __builtin_bit_cast(float, q1.x & 0xffff0000u), __builtin_bit_cast(float, q1.y << 16), __builtin_bit_cast(float, q1.y & 0xffff0000u)};
;                     const float h2[4] = {__builtin_bit_cast(float, q2.x << 16), __builtin_bit_cast(float, q2.x & 0xffff0000u), __builtin_bit_cast(float, q2.y << 16), __builtin_bit_cast(float, q2.y & 0xffff0000u)};
;                     const float h3[4] = {__builtin_bit_cast(float, q3.x << 16), __builtin_bit_cast(float, q3.x & 0xffff0000u), __builtin_bit_cast(float, q3.y << 16), __builtin_bit_cast(float, q3.y & 0xffff0000u)};
;                     const f32x4 gv = acc[ai][bj][m][n];
;                     float o[4];
; #pragma unroll
;                     for (int j = 0; j < 4; ++j) { const float g = gv[j];
;                         float g1 = dpp_row_shr<1>(h1[j], g), g2 = dpp_row_shr<2>(h2[j], g), g3 = dpp_row_shr<3>(h3[j], g);
	ds_read_b128 v[46:49], v238 offset:4112
	ds_read_b128 v[50:53], v238 offset:3088
	ds_read_b128 v[54:57], v238 offset:2064
	v_cndmask_b32_e64 v45, v44, 0, s[8:9]
	ds_read_b128 v[58:61], v238 offset:1040
	s_nop 0
	ds_read_b128 v[62:65], v238 offset:16
	v_cndmask_b32_e64 v44, v43, 0, s[8:9]
	v_cndmask_b32_e64 v43, 0, v42, s[6:7]
	v_cndmask_b32_e64 v42, 0, v41, s[6:7]
	v_cndmask_b32_e64 v41, 0, v40, s[4:5]
	v_cndmask_b32_e64 v40, 0, v39, s[4:5]
	v_cndmask_b32_e64 v31, 0, v31, s[6:7]
	v_cndmask_b32_e64 v30, 0, v30, s[6:7]
	v_cndmask_b32_e64 v29, 0, v29, s[4:5]
	v_cndmask_b32_e64 v28, 0, v28, s[4:5]
	s_waitcnt lgkmcnt(0)
	v_pk_fma_f32 v[24:25], v[24:25], v[50:51], v[46:47]
	v_pk_fma_f32 v[26:27], v[26:27], v[52:53], v[48:49]
	v_pk_fma_f32 v[24:25], v[44:45], v[54:55], v[24:25]
	s_nop 0
	v_pk_fma_f32 v[24:25], v[42:43], v[58:59], v[24:25]
	s_nop 0
	v_pk_fma_f32 v[24:25], v[40:41], v[62:63], v[24:25]
	s_nop 0
	v_pk_mul_f32 v[40:41], v[24:25], s[98:99] op_sel_hi:[1,0]
	v_exp_f32_e32 v40, v40
	v_exp_f32_e32 v41, v41
	s_nop 0
	v_pk_add_f32 v[40:41], v[40:41], 1.0 op_sel_hi:[1,0]
	v_rcp_f32_e32 v40, v40
	v_rcp_f32_e32 v41, v41
	v_cndmask_b32_e64 v39, v38, 0, s[8:9]
	v_cndmask_b32_e64 v38, v37, 0, s[8:9]
	v_pk_fma_f32 v[26:27], v[38:39], v[56:57], v[26:27]
	v_pk_mul_f32 v[24:25], v[24:25], v[40:41]
	v_pk_fma_f32 v[26:27], v[30:31], v[60:61], v[26:27]
	v_cvt_pk_bf16_f32 v24, v24, v25
	v_pk_fma_f32 v[26:27], v[28:29], v[64:65], v[26:27]
	s_nop 0
	v_pk_mul_f32 v[28:29], v[26:27], s[98:99] op_sel_hi:[1,0]
	v_exp_f32_e32 v28, v28
	v_exp_f32_e32 v29, v29
	s_nop 0
	v_pk_add_f32 v[28:29], v[28:29], 1.0 op_sel_hi:[1,0]
	v_rcp_f32_e32 v28, v28
	v_rcp_f32_e32 v29, v29
	s_nop 0
	v_pk_mul_f32 v[26:27], v[26:27], v[28:29]
	s_nop 0
	v_cvt_pk_bf16_f32 v25, v26, v27
	global_store_dwordx2 v[32:33], v[24:25], off offset:8
.LBB0_235:
	s_or_b64 exec, exec, s[22:23]
	ds_read_b64 v[24:25], v34 offset:1280
	ds_read_b64 v[26:27], v35 offset:768
	ds_read_b64 v[42:43], v36 offset:256
	s_waitcnt lgkmcnt(0)
	v_lshlrev_b32_e32 v39, 16, v24
	v_and_b32_e32 v40, 0xffff0000, v24
	v_lshlrev_b32_e32 v28, 16, v25
	v_and_b32_e32 v29, 0xffff0000, v25
	v_lshlrev_b32_e32 v37, 16, v26
	v_and_b32_e32 v38, 0xffff0000, v26
	v_lshlrev_b32_e32 v26, 16, v27
	v_and_b32_e32 v27, 0xffff0000, v27
	v_lshlrev_b32_e32 v30, 16, v42
	v_and_b32_e32 v31, 0xffff0000, v42
	v_lshlrev_b32_e32 v24, 16, v43
	v_and_b32_e32 v25, 0xffff0000, v43
	v_mov_b32_dpp v39, v20 row_shr:1 row_mask:0xf bank_mask:0xf
	v_mov_b32_dpp v37, v20 row_shr:2 row_mask:0xf bank_mask:0xf
	v_mov_b32_dpp v30, v20 row_shr:3 row_mask:0xf bank_mask:0xf
	v_mov_b32_dpp v40, v21 row_shr:1 row_mask:0xf bank_mask:0xf
	v_mov_b32_dpp v38, v21 row_shr:2 row_mask:0xf bank_mask:0xf
	v_mov_b32_dpp v31, v21 row_shr:3 row_mask:0xf bank_mask:0xf
	v_mov_b32_dpp v28, v22 row_shr:1 row_mask:0xf bank_mask:0xf
	v_mov_b32_dpp v26, v22 row_shr:2 row_mask:0xf bank_mask:0xf
	v_mov_b32_dpp v24, v22 row_shr:3 row_mask:0xf bank_mask:0xf
	v_mov_b32_dpp v29, v23 row_shr:1 row_mask:0xf bank_mask:0xf
	v_mov_b32_dpp v27, v23 row_shr:2 row_mask:0xf bank_mask:0xf
	v_mov_b32_dpp v25, v23 row_shr:3 row_mask:0xf bank_mask:0xf
	s_and_saveexec_b64 s[22:23], s[2:3]
	s_cbranch_execz .LBB0_237
	ds_read_b128 v[42:45], v238 offset:4608
	ds_read_b128 v[46:49], v238 offset:3584
	ds_read_b128 v[50:53], v238 offset:2560
	v_cndmask_b32_e64 v41, v40, 0, s[8:9]
	ds_read_b128 v[54:57], v238 offset:1536
	s_nop 0
	ds_read_b128 v[58:61], v238 offset:512
	v_cndmask_b32_e64 v40, v39, 0, s[8:9]
	v_cndmask_b32_e64 v39, 0, v38, s[6:7]
	v_cndmask_b32_e64 v38, 0, v37, s[6:7]
	v_cndmask_b32_e64 v31, 0, v31, s[4:5]
	v_cndmask_b32_e64 v30, 0, v30, s[4:5]
	v_cndmask_b32_e64 v29, v29, 0, s[8:9]
	v_cndmask_b32_e64 v28, v28, 0, s[8:9]
	v_cndmask_b32_e64 v27, 0, v27, s[6:7]
	v_cndmask_b32_e64 v26, 0, v26, s[6:7]
	v_cndmask_b32_e64 v25, 0, v25, s[4:5]
	v_cndmask_b32_e64 v24, 0, v24, s[4:5]
	s_waitcnt lgkmcnt(0)
	v_pk_fma_f32 v[20:21], v[20:21], v[46:47], v[42:43]
	v_pk_fma_f32 v[22:23], v[22:23], v[48:49], v[44:45]
	v_pk_fma_f32 v[20:21], v[40:41], v[50:51], v[20:21]
	v_pk_fma_f32 v[22:23], v[28:29], v[52:53], v[22:23]
	v_pk_fma_f32 v[20:21], v[38:39], v[54:55], v[20:21]
	s_nop 0
	v_pk_fma_f32 v[20:21], v[30:31], v[58:59], v[20:21]
	v_pk_fma_f32 v[22:23], v[26:27], v[56:57], v[22:23]
	v_pk_fma_f32 v[22:23], v[24:25], v[60:61], v[22:23]
	v_pk_mul_f32 v[30:31], v[20:21], s[98:99] op_sel_hi:[1,0]
	v_exp_f32_e32 v30, v30
	v_exp_f32_e32 v31, v31
	s_nop 0
	v_pk_add_f32 v[30:31], v[30:31], 1.0 op_sel_hi:[1,0]
	v_rcp_f32_e32 v30, v30
	v_rcp_f32_e32 v31, v31
	s_nop 0
	v_pk_mul_f32 v[20:21], v[20:21], v[30:31]
	s_nop 0
	v_cvt_pk_bf16_f32 v20, v20, v21
	v_pk_mul_f32 v[24:25], v[22:23], s[98:99] op_sel_hi:[1,0]
	v_exp_f32_e32 v24, v24
	v_exp_f32_e32 v25, v25
	s_nop 0
	v_pk_add_f32 v[24:25], v[24:25], 1.0 op_sel_hi:[1,0]
	v_rcp_f32_e32 v24, v24
	v_rcp_f32_e32 v25, v25
	s_nop 0
	v_pk_mul_f32 v[22:23], v[22:23], v[24:25]
	s_nop 0
	v_cvt_pk_bf16_f32 v21, v22, v23
	global_store_dwordx2 v[32:33], v[20:21], off offset:256
;     __device__ __forceinline__ void operator()(const f32x4 (&acc)[2][2][4][2], const Unit& u, int wr, int wc, int fr, int fq, LAS unsigned char* hb) const {
;     ...
;             for (int m = 0; m < 4; ++m) { asm volatile("" ::: "memory"); __builtin_amdgcn_sched_barrier(0);
;                 const int q = 8 * ai + 4 * wr + m, prev = q > 0 ? q - 1 : 0; const int lr = ai * HALF + wr * 64 + m * 16 + fr, R = R0 + lr;
;                 const int Rc = R < 0 ? 0 : R; const int b = Rc / LL, p = Rc - b * LL;
;                 const bool ok = (lr >= H && R < TT);
;                 const unsigned ooff = ((unsigned)Rc * (unsigned)LDP + (unsigned)(OFF_XBC + ch0)) * 2u;
; #pragma unroll
;                 for (int bn = 0; bn < 4; ++bn) { const int bj = bn >> 1, n = bn & 1; const int co = bj * HALF + 4 * n;
;                     const unsigned woff = (unsigned)(ch0 + co) * 4u;
;                     const f32x4 w0 = *(const f32x4*)((const char*)cw + woff), w1 = *(const f32x4*)((const char*)cw + woff + XBCW * 4), w2 = *(const f32x4*)((const char*)cw + woff + 2 * XBCW * 4), w3 = *(const f32x4*)((const char*)cw + woff + 3 * XBCW * 4), bs = *(const f32x4*)((const char*)cb + woff);
;                     const LAS unsigned char* hp = hb + (prev * H * NCH + chl + co) * 2;
;                     const u32x2 q1 = *(const LAS u32x2*)(hp + hr1 * NCH * 2), q2 = *(const LAS u32x2*)(hp + hr2 * NCH * 2), q3 = *(const LAS u32x2*)(hp + hr3 * NCH * 2);
;                     const float h1[4] = {__builtin_bit_cast(float, q1.x << 16), __builtin_bit_cast(float, q1.x & 0xffff0000u), __builtin_bit_cast(float, q1.y << 16), __builtin_bit_cast(float, q1.y & 0xffff0000u)};
;                     const float h2[4] = {__builtin_bit_cast(float, q2.x << 16), __builtin_bit_cast(float, q2.x & 0xffff0000u), __builtin_bit_cast(float, q2.y << 16), __builtin_bit_cast(float, q2.y & 0xffff0000u)};
;                     const float h3[4] = {__builtin_bit_cast(float, q3.x << 16), __builtin_bit_cast(float, q3.x & 0xffff0000u), __builtin_bit_cast(float, q3.y << 16), __builtin_bit_cast(float, q3.y & 0xffff0000u)};
;                     const f32x4 gv = acc[ai][bj][m][n];
;                     float o[4];
; #pragma unroll
;                     for (int j = 0; j < 4; ++j) { const float g = gv[j];
;                         float g1 = dpp_row_shr<1>(h1[j], g), g2 = dpp_row_shr<2>(h2[j], g), g3 = dpp_row_shr<3>(h3[j], g);
.LBB0_237:
	s_or_b64 exec, exec, s[22:23]
	ds_read_b64 v[20:21], v34 offset:1288
	ds_read_b64 v[22:23], v35 offset:776
	ds_read_b64 v[34:35], v36 offset:264
	s_waitcnt lgkmcnt(0)
	v_lshlrev_b32_e32 v30, 16, v20
	v_and_b32_e32 v31, 0xffff0000, v20
	v_lshlrev_b32_e32 v24, 16, v21
	v_and_b32_e32 v25, 0xffff0000, v21
	v_lshlrev_b32_e32 v28, 16, v22
	v_and_b32_e32 v29, 0xffff0000, v22
	v_lshlrev_b32_e32 v22, 16, v23
	v_and_b32_e32 v23, 0xffff0000, v23
	v_lshlrev_b32_e32 v26, 16, v34
	v_and_b32_e32 v27, 0xffff0000, v34
	v_lshlrev_b32_e32 v20, 16, v35
	v_and_b32_e32 v21, 0xffff0000, v35
	v_mov_b32_dpp v30, v16 row_shr:1 row_mask:0xf bank_mask:0xf
	v_mov_b32_dpp v28, v16 row_shr:2 row_mask:0xf bank_mask:0xf
	v_mov_b32_dpp v26, v16 row_shr:3 row_mask:0xf bank_mask:0xf
	v_mov_b32_dpp v31, v17 row_shr:1 row_mask:0xf bank_mask:0xf
	v_mov_b32_dpp v29, v17 row_shr:2 row_mask:0xf bank_mask:0xf
	v_mov_b32_dpp v27, v17 row_shr:3 row_mask:0xf bank_mask:0xf
	v_mov_b32_dpp v24, v18 row_shr:1 row_mask:0xf bank_mask:0xf
	v_mov_b32_dpp v22, v18 row_shr:2 row_mask:0xf bank_mask:0xf
	v_mov_b32_dpp v20, v18 row_shr:3 row_mask:0xf bank_mask:0xf
	v_mov_b32_dpp v25, v19 row_shr:1 row_mask:0xf bank_mask:0xf
	v_mov_b32_dpp v23, v19 row_shr:2 row_mask:0xf bank_mask:0xf
	v_mov_b32_dpp v21, v19 row_shr:3 row_mask:0xf bank_mask:0xf
	s_and_saveexec_b64 s[22:23], s[2:3]
	s_cbranch_execz .LBB0_239
	ds_read_b128 v[34:37], v238 offset:4624
	ds_read_b128 v[38:41], v238 offset:3600
	ds_read_b128 v[42:45], v238 offset:2576
	v_cndmask_b32_e64 v31, v31, 0, s[8:9]
	ds_read_b128 v[46:49], v238 offset:1552
	s_nop 0
	ds_read_b128 v[50:53], v238 offset:528
	v_cndmask_b32_e64 v30, v30, 0, s[8:9]
	v_cndmask_b32_e64 v29, 0, v29, s[6:7]
	v_cndmask_b32_e64 v28, 0, v28, s[6:7]
	v_cndmask_b32_e64 v27, 0, v27, s[4:5]
	v_cndmask_b32_e64 v26, 0, v26, s[4:5]
	v_cndmask_b32_e64 v25, v25, 0, s[8:9]
	v_cndmask_b32_e64 v24, v24, 0, s[8:9]
	v_cndmask_b32_e64 v23, 0, v23, s[6:7]
	v_cndmask_b32_e64 v22, 0, v22, s[6:7]
	v_cndmask_b32_e64 v21, 0, v21, s[4:5]
	v_cndmask_b32_e64 v20, 0, v20, s[4:5]
	s_waitcnt lgkmcnt(0)
	v_pk_fma_f32 v[16:17], v[16:17], v[38:39], v[34:35]
	v_pk_fma_f32 v[18:19], v[18:19], v[40:41], v[36:37]
	v_pk_fma_f32 v[16:17], v[30:31], v[42:43], v[16:17]
	v_pk_fma_f32 v[18:19], v[24:25], v[44:45], v[18:19]
	v_pk_fma_f32 v[16:17], v[28:29], v[46:47], v[16:17]
	s_nop 0
	v_pk_fma_f32 v[16:17], v[26:27], v[50:51], v[16:17]
	v_pk_fma_f32 v[18:19], v[22:23], v[48:49], v[18:19]
	v_pk_fma_f32 v[18:19], v[20:21], v[52:53], v[18:19]
	v_pk_mul_f32 v[26:27], v[16:17], s[98:99] op_sel_hi:[1,0]
	v_exp_f32_e32 v26, v26
	v_exp_f32_e32 v27, v27
	s_nop 0
	v_pk_add_f32 v[26:27], v[26:27], 1.0 op_sel_hi:[1,0]
	v_rcp_f32_e32 v26, v26
	v_rcp_f32_e32 v27, v27
	s_nop 0
	v_pk_mul_f32 v[16:17], v[16:17], v[26:27]
	s_nop 0
	v_cvt_pk_bf16_f32 v16, v16, v17
	v_pk_mul_f32 v[20:21], v[18:19], s[98:99] op_sel_hi:[1,0]
	v_exp_f32_e32 v20, v20
	v_exp_f32_e32 v21, v21
	s_nop 0
	v_pk_add_f32 v[20:21], v[20:21], 1.0 op_sel_hi:[1,0]
	v_rcp_f32_e32 v20, v20
	v_rcp_f32_e32 v21, v21
	s_nop 0
	v_pk_mul_f32 v[18:19], v[18:19], v[20:21]
	s_nop 0
	v_cvt_pk_bf16_f32 v17, v18, v19
	global_store_dwordx2 v[32:33], v[16:17], off offset:264
.LBB0_239:
	s_or_b64 exec, exec, s[22:23]
	v_add_u32_e32 v16, 0xb0, v161
	v_add_u32_e32 v17, s17, v16
	v_max_i32_e32 v18, 0, v17
	v_mul_hi_u32 v19, v18, s56
	v_lshrrev_b32_e32 v19, 11, v19
	v_cmp_lt_i32_e32 vcc, 2, v16
	v_mul_lo_u32 v16, v18, s51
	v_mul_u32_u24_e32 v19, 0x1010, v19
	v_add_lshl_u32 v136, v16, v164, 1
	v_add_u32_e32 v16, s44, v165
	v_sub_u32_e32 v19, v18, v19
	v_cmp_gt_i32_e64 s[4:5], s50, v17
	v_lshl_add_u32 v18, v16, 1, s53
	s_and_b64 s[2:3], vcc, s[4:5]
	v_cmp_eq_u32_e64 s[8:9], 0, v19
	v_cmp_lt_u32_e64 s[6:7], 1, v19
	v_cmp_lt_u32_e64 s[4:5], 2, v19
	v_add_u32_e32 v19, v18, v163
	ds_read_b64 v[16:17], v18 offset:1024
	v_add_u32_e32 v20, v18, v162
	ds_read_b64 v[34:35], v19 offset:512
	ds_read_b64 v[36:37], v20
	v_readlane_b32 s22, v237, 58
	v_readlane_b32 s23, v237, 59
	s_waitcnt lgkmcnt(0)
	v_lshlrev_b32_e32 v31, 16, v16
	v_and_b32_e32 v32, 0xffff0000, v16
	v_lshlrev_b32_e32 v25, 16, v17
	v_and_b32_e32 v26, 0xffff0000, v17
	v_lshlrev_b32_e32 v29, 16, v34
	v_and_b32_e32 v30, 0xffff0000, v34
	v_lshlrev_b32_e32 v23, 16, v35
	v_and_b32_e32 v24, 0xffff0000, v35
	v_lshlrev_b32_e32 v27, 16, v36
	v_and_b32_e32 v28, 0xffff0000, v36
	v_lshlrev_b32_e32 v21, 16, v37
	v_and_b32_e32 v22, 0xffff0000, v37
	v_mov_b32_dpp v31, v12 row_shr:1 row_mask:0xf bank_mask:0xf
	v_mov_b32_dpp v29, v12 row_shr:2 row_mask:0xf bank_mask:0xf
	v_mov_b32_dpp v27, v12 row_shr:3 row_mask:0xf bank_mask:0xf
	v_mov_b32_dpp v32, v13 row_shr:1 row_mask:0xf bank_mask:0xf
	v_mov_b32_dpp v30, v13 row_shr:2 row_mask:0xf bank_mask:0xf
	v_mov_b32_dpp v28, v13 row_shr:3 row_mask:0xf bank_mask:0xf
	v_mov_b32_dpp v25, v14 row_shr:1 row_mask:0xf bank_mask:0xf
	v_mov_b32_dpp v23, v14 row_shr:2 row_mask:0xf bank_mask:0xf
	v_mov_b32_dpp v21, v14 row_shr:3 row_mask:0xf bank_mask:0xf
	v_mov_b32_dpp v26, v15 row_shr:1 row_mask:0xf bank_mask:0xf
	v_mov_b32_dpp v24, v15 row_shr:2 row_mask:0xf bank_mask:0xf
	v_mov_b32_dpp v22, v15 row_shr:3 row_mask:0xf bank_mask:0xf
	v_lshl_add_u64 v[16:17], s[22:23], 0, v[136:137]
	s_and_saveexec_b64 s[22:23], s[2:3]
	s_cbranch_execz .LBB0_241
;     __device__ __forceinline__ void operator()(const f32x4 (&acc)[2][2][4][2], const Unit& u, int wr, int wc, int fr, int fq, LAS unsigned char* hb) const {
;     ...
;             for (int m = 0; m < 4; ++m) { asm volatile("" ::: "memory"); __builtin_amdgcn_sched_barrier(0);
;                 const int q = 8 * ai + 4 * wr + m, prev = q > 0 ? q - 1 : 0; const int lr = ai * HALF + wr * 64 + m * 16 + fr, R = R0 + lr;
;                 const int Rc = R < 0 ? 0 : R; const int b = Rc / LL, p = Rc - b * LL;
;                 const bool ok = (lr >= H && R < TT);
;                 const unsigned ooff = ((unsigned)Rc * (unsigned)LDP + (unsigned)(OFF_XBC + ch0)) * 2u;
; #pragma unroll
;                 for (int bn = 0; bn < 4; ++bn) { const int bj = bn >> 1, n = bn & 1; const int co = bj * HALF + 4 * n;
;                     const unsigned woff = (unsigned)(ch0 + co) * 4u;
;                     const f32x4 w0 = *(const f32x4*)((const char*)cw + woff), w1 = *(const f32x4*)((const char*)cw + woff + XBCW * 4), w2 = *(const f32x4*)((const char*)cw + woff + 2 * XBCW * 4), w3 = *(const f32x4*)((const char*)cw + woff + 3 * XBCW * 4), bs = *(const f32x4*)((const char*)cb + woff);
;                     const LAS unsigned char* hp = hb + (prev * H * NCH + chl + co) * 2;
;                     const u32x2 q1 = *(const LAS u32x2*)(hp + hr1 * NCH * 2), q2 = *(const LAS u32x2*)(hp + hr2 * NCH * 2), q3 = *(const LAS u32x2*)(hp + hr3 * NCH * 2);
;                     const float h1[4] = {__builtin_bit_cast(float, q1.x << 16), __builtin_bit_cast(float, q1.x & 0xffff0000u), __builtin_bit_cast(float, q1.y << 16), __builtin_bit_cast(float, q1.y & 0xffff0000u)};
;                     const float h2[4] = {__builtin_bit_cast(float, q2.x << 16), __builtin_bit_cast(float, q2.x & 0xffff0000u), __builtin_bit_cast(float, q2.y << 16), __builtin_bit_cast(float, q2.y & 0xffff0000u)};
;                     const float h3[4] = {__builtin_bit_cast(float, q3.x << 16), __builtin_bit_cast(float, q3.x & 0xffff0000u), __builtin_bit_cast(float, q3.y << 16), __builtin_bit_cast(float, q3.y & 0xffff0000u)};
;                     const f32x4 gv = acc[ai][bj][m][n];
;                     float o[4];
; #pragma unroll
;                     for (int j = 0; j < 4; ++j) { const float g = gv[j];
;                         float g1 = dpp_row_shr<1>(h1[j], g), g2 = dpp_row_shr<2>(h2[j], g), g3 = dpp_row_shr<3>(h3[j], g);
	ds_read_b128 v[34:37], v238 offset:4096
	ds_read_b128 v[38:41], v238 offset:3072
	ds_read_b128 v[42:45], v238 offset:2048
	v_cndmask_b32_e64 v33, v32, 0, s[8:9]
	ds_read_b128 v[46:49], v238 offset:1024
	s_nop 0
	ds_read_b128 v[50:53], v238
	v_cndmask_b32_e64 v32, v31, 0, s[8:9]
	v_cndmask_b32_e64 v31, 0, v30, s[6:7]
	v_cndmask_b32_e64 v30, 0, v29, s[6:7]
	v_cndmask_b32_e64 v29, 0, v28, s[4:5]
	v_cndmask_b32_e64 v28, 0, v27, s[4:5]
	s_waitcnt lgkmcnt(0)
	v_pk_fma_f32 v[12:13], v[12:13], v[38:39], v[34:35]
	v_pk_fma_f32 v[14:15], v[14:15], v[40:41], v[36:37]
	v_pk_fma_f32 v[12:13], v[32:33], v[42:43], v[12:13]
	s_nop 0
	v_pk_fma_f32 v[12:13], v[30:31], v[46:47], v[12:13]
	s_nop 0
	v_pk_fma_f32 v[12:13], v[28:29], v[50:51], v[12:13]
	s_nop 0
	v_pk_mul_f32 v[28:29], v[12:13], s[98:99] op_sel_hi:[1,0]
	v_exp_f32_e32 v28, v28
	v_exp_f32_e32 v29, v29
	s_nop 0
	v_pk_add_f32 v[28:29], v[28:29], 1.0 op_sel_hi:[1,0]
	v_rcp_f32_e32 v28, v28
	v_rcp_f32_e32 v29, v29
	v_cndmask_b32_e64 v27, v26, 0, s[8:9]
	v_cndmask_b32_e64 v26, v25, 0, s[8:9]
	v_pk_fma_f32 v[14:15], v[26:27], v[44:45], v[14:15]
	v_cndmask_b32_e64 v25, 0, v24, s[6:7]
	v_cndmask_b32_e64 v24, 0, v23, s[6:7]
	v_pk_fma_f32 v[14:15], v[24:25], v[48:49], v[14:15]
	v_cndmask_b32_e64 v23, 0, v22, s[4:5]
	v_cndmask_b32_e64 v22, 0, v21, s[4:5]
	v_pk_mul_f32 v[12:13], v[12:13], v[28:29]
	v_pk_fma_f32 v[14:15], v[22:23], v[52:53], v[14:15]
	v_cvt_pk_bf16_f32 v12, v12, v13
	v_pk_mul_f32 v[22:23], v[14:15], s[98:99] op_sel_hi:[1,0]
	v_exp_f32_e32 v22, v22
	v_exp_f32_e32 v23, v23
	s_nop 0
	v_pk_add_f32 v[22:23], v[22:23], 1.0 op_sel_hi:[1,0]
	v_rcp_f32_e32 v22, v22
	v_rcp_f32_e32 v23, v23
	s_nop 0
	v_pk_mul_f32 v[14:15], v[14:15], v[22:23]
	s_nop 0
	v_cvt_pk_bf16_f32 v13, v14, v15
	global_store_dwordx2 v[16:17], v[12:13], off
.LBB0_241:
	s_or_b64 exec, exec, s[22:23]
	ds_read_b64 v[12:13], v18 offset:1032
	ds_read_b64 v[14:15], v19 offset:520
	ds_read_b64 v[30:31], v20 offset:8
	s_waitcnt lgkmcnt(0)
	v_lshlrev_b32_e32 v27, 16, v12
	v_and_b32_e32 v28, 0xffff0000, v12
	v_lshlrev_b32_e32 v21, 16, v13
	v_and_b32_e32 v22, 0xffff0000, v13
	v_lshlrev_b32_e32 v25, 16, v14
	v_and_b32_e32 v26, 0xffff0000, v14
	v_lshlrev_b32_e32 v14, 16, v15
	v_and_b32_e32 v15, 0xffff0000, v15
	v_lshlrev_b32_e32 v23, 16, v30
	v_and_b32_e32 v24, 0xffff0000, v30
	v_lshlrev_b32_e32 v12, 16, v31
	v_and_b32_e32 v13, 0xffff0000, v31
	v_mov_b32_dpp v27, v8 row_shr:1 row_mask:0xf bank_mask:0xf
	v_mov_b32_dpp v25, v8 row_shr:2 row_mask:0xf bank_mask:0xf
	v_mov_b32_dpp v23, v8 row_shr:3 row_mask:0xf bank_mask:0xf
	v_mov_b32_dpp v28, v9 row_shr:1 row_mask:0xf bank_mask:0xf
	v_mov_b32_dpp v26, v9 row_shr:2 row_mask:0xf bank_mask:0xf
	v_mov_b32_dpp v24, v9 row_shr:3 row_mask:0xf bank_mask:0xf
	v_mov_b32_dpp v21, v10 row_shr:1 row_mask:0xf bank_mask:0xf
	v_mov_b32_dpp v14, v10 row_shr:2 row_mask:0xf bank_mask:0xf
	v_mov_b32_dpp v12, v10 row_shr:3 row_mask:0xf bank_mask:0xf
	v_mov_b32_dpp v22, v11 row_shr:1 row_mask:0xf bank_mask:0xf
	v_mov_b32_dpp v15, v11 row_shr:2 row_mask:0xf bank_mask:0xf
	v_mov_b32_dpp v13, v11 row_shr:3 row_mask:0xf bank_mask:0xf
	s_and_saveexec_b64 s[22:23], s[2:3]
	s_cbranch_execz .LBB0_243
	ds_read_b128 v[30:33], v238 offset:4112
	ds_read_b128 v[34:37], v238 offset:3088
	ds_read_b128 v[38:41], v238 offset:2064
	v_cndmask_b32_e64 v29, v28, 0, s[8:9]
	ds_read_b128 v[42:45], v238 offset:1040
	s_nop 0
	ds_read_b128 v[46:49], v238 offset:16
	v_cndmask_b32_e64 v28, v27, 0, s[8:9]
	v_cndmask_b32_e64 v27, 0, v26, s[6:7]
	v_cndmask_b32_e64 v26, 0, v25, s[6:7]
	v_cndmask_b32_e64 v25, 0, v24, s[4:5]
	v_cndmask_b32_e64 v24, 0, v23, s[4:5]
	v_cndmask_b32_e64 v15, 0, v15, s[6:7]
	v_cndmask_b32_e64 v14, 0, v14, s[6:7]
	v_cndmask_b32_e64 v13, 0, v13, s[4:5]
	v_cndmask_b32_e64 v12, 0, v12, s[4:5]
	s_waitcnt lgkmcnt(0)
	v_pk_fma_f32 v[8:9], v[8:9], v[34:35], v[30:31]
	v_pk_fma_f32 v[10:11], v[10:11], v[36:37], v[32:33]
	v_pk_fma_f32 v[8:9], v[28:29], v[38:39], v[8:9]
	s_nop 0
	v_pk_fma_f32 v[8:9], v[26:27], v[42:43], v[8:9]
	s_nop 0
	v_pk_fma_f32 v[8:9], v[24:25], v[46:47], v[8:9]
	s_nop 0
	v_pk_mul_f32 v[24:25], v[8:9], s[98:99] op_sel_hi:[1,0]
	v_exp_f32_e32 v24, v24
	v_exp_f32_e32 v25, v25
	s_nop 0
	v_pk_add_f32 v[24:25], v[24:25], 1.0 op_sel_hi:[1,0]
	v_rcp_f32_e32 v24, v24
	v_rcp_f32_e32 v25, v25
	v_cndmask_b32_e64 v23, v22, 0, s[8:9]
	v_cndmask_b32_e64 v22, v21, 0, s[8:9]
	v_pk_fma_f32 v[10:11], v[22:23], v[40:41], v[10:11]
	v_pk_mul_f32 v[8:9], v[8:9], v[24:25]
	v_pk_fma_f32 v[10:11], v[14:15], v[44:45], v[10:11]
	v_cvt_pk_bf16_f32 v8, v8, v9
	v_pk_fma_f32 v[10:11], v[12:13], v[48:49], v[10:11]
	s_nop 0
	v_pk_mul_f32 v[12:13], v[10:11], s[98:99] op_sel_hi:[1,0]
	v_exp_f32_e32 v12, v12
	v_exp_f32_e32 v13, v13
	s_nop 0
	v_pk_add_f32 v[12:13], v[12:13], 1.0 op_sel_hi:[1,0]
	v_rcp_f32_e32 v12, v12
	v_rcp_f32_e32 v13, v13
	s_nop 0
	v_pk_mul_f32 v[10:11], v[10:11], v[12:13]
	s_nop 0
	v_cvt_pk_bf16_f32 v9, v10, v11
	global_store_dwordx2 v[16:17], v[8:9], off offset:8
;     __device__ __forceinline__ void operator()(const f32x4 (&acc)[2][2][4][2], const Unit& u, int wr, int wc, int fr, int fq, LAS unsigned char* hb) const {
;     ...
;             for (int m = 0; m < 4; ++m) { asm volatile("" ::: "memory"); __builtin_amdgcn_sched_barrier(0);
;                 const int q = 8 * ai + 4 * wr + m, prev = q > 0 ? q - 1 : 0; const int lr = ai * HALF + wr * 64 + m * 16 + fr, R = R0 + lr;
;                 const int Rc = R < 0 ? 0 : R; const int b = Rc / LL, p = Rc - b * LL;
;                 const bool ok = (lr >= H && R < TT);
;                 const unsigned ooff = ((unsigned)Rc * (unsigned)LDP + (unsigned)(OFF_XBC + ch0)) * 2u;
; #pragma unroll
;                 for (int bn = 0; bn < 4; ++bn) { const int bj = bn >> 1, n = bn & 1; const int co = bj * HALF + 4 * n;
;                     const unsigned woff = (unsigned)(ch0 + co) * 4u;
;                     const f32x4 w0 = *(const f32x4*)((const char*)cw + woff), w1 = *(const f32x4*)((const char*)cw + woff + XBCW * 4), w2 = *(const f32x4*)((const char*)cw + woff + 2 * XBCW * 4), w3 = *(const f32x4*)((const char*)cw + woff + 3 * XBCW * 4), bs = *(const f32x4*)((const char*)cb + woff);
;                     const LAS unsigned char* hp = hb + (prev * H * NCH + chl + co) * 2;
;                     const u32x2 q1 = *(const LAS u32x2*)(hp + hr1 * NCH * 2), q2 = *(const LAS u32x2*)(hp + hr2 * NCH * 2), q3 = *(const LAS u32x2*)(hp + hr3 * NCH * 2);
;                     const float h1[4] = {__builtin_bit_cast(float, q1.x << 16), __builtin_bit_cast(float, q1.x & 0xffff0000u), __builtin_bit_cast(float, q1.y << 16), __builtin_bit_cast(float, q1.y & 0xffff0000u)};
;                     const float h2[4] = {__builtin_bit_cast(float, q2.x << 16), __builtin_bit_cast(float, q2.x & 0xffff0000u), __builtin_bit_cast(float, q2.y << 16), __builtin_bit_cast(float, q2.y & 0xffff0000u)};
;                     const float h3[4] = {__builtin_bit_cast(float, q3.x << 16), __builtin_bit_cast(float, q3.x & 0xffff0000u), __builtin_bit_cast(float, q3.y << 16), __builtin_bit_cast(float, q3.y & 0xffff0000u)};
;                     const f32x4 gv = acc[ai][bj][m][n];
;                     float o[4];
; #pragma unroll
;                     for (int j = 0; j < 4; ++j) { const float g = gv[j];
;                         float g1 = dpp_row_shr<1>(h1[j], g), g2 = dpp_row_shr<2>(h2[j], g), g3 = dpp_row_shr<3>(h3[j], g);
.LBB0_243:
	s_or_b64 exec, exec, s[22:23]
	ds_read_b64 v[8:9], v18 offset:1280
	ds_read_b64 v[10:11], v19 offset:768
	ds_read_b64 v[26:27], v20 offset:256
	s_waitcnt lgkmcnt(0)
	v_lshlrev_b32_e32 v23, 16, v8
	v_and_b32_e32 v24, 0xffff0000, v8
	v_lshlrev_b32_e32 v12, 16, v9
	v_and_b32_e32 v13, 0xffff0000, v9
	v_lshlrev_b32_e32 v21, 16, v10
	v_and_b32_e32 v22, 0xffff0000, v10
	v_lshlrev_b32_e32 v10, 16, v11
	v_and_b32_e32 v11, 0xffff0000, v11
	v_lshlrev_b32_e32 v14, 16, v26
	v_and_b32_e32 v15, 0xffff0000, v26
	v_lshlrev_b32_e32 v8, 16, v27
	v_and_b32_e32 v9, 0xffff0000, v27
	v_mov_b32_dpp v23, v4 row_shr:1 row_mask:0xf bank_mask:0xf
	v_mov_b32_dpp v21, v4 row_shr:2 row_mask:0xf bank_mask:0xf
	v_mov_b32_dpp v14, v4 row_shr:3 row_mask:0xf bank_mask:0xf
	v_mov_b32_dpp v24, v5 row_shr:1 row_mask:0xf bank_mask:0xf
	v_mov_b32_dpp v22, v5 row_shr:2 row_mask:0xf bank_mask:0xf
	v_mov_b32_dpp v15, v5 row_shr:3 row_mask:0xf bank_mask:0xf
	v_mov_b32_dpp v12, v6 row_shr:1 row_mask:0xf bank_mask:0xf
	v_mov_b32_dpp v10, v6 row_shr:2 row_mask:0xf bank_mask:0xf
	v_mov_b32_dpp v8, v6 row_shr:3 row_mask:0xf bank_mask:0xf
	v_mov_b32_dpp v13, v7 row_shr:1 row_mask:0xf bank_mask:0xf
	v_mov_b32_dpp v11, v7 row_shr:2 row_mask:0xf bank_mask:0xf
	v_mov_b32_dpp v9, v7 row_shr:3 row_mask:0xf bank_mask:0xf
	s_and_saveexec_b64 s[22:23], s[2:3]
	s_cbranch_execz .LBB0_245
	ds_read_b128 v[26:29], v238 offset:4608
	ds_read_b128 v[30:33], v238 offset:3584
	ds_read_b128 v[34:37], v238 offset:2560
	v_cndmask_b32_e64 v25, v24, 0, s[8:9]
	ds_read_b128 v[38:41], v238 offset:1536
	s_nop 0
	ds_read_b128 v[42:45], v238 offset:512
	v_cndmask_b32_e64 v24, v23, 0, s[8:9]
	v_cndmask_b32_e64 v23, 0, v22, s[6:7]
	v_cndmask_b32_e64 v22, 0, v21, s[6:7]
	v_cndmask_b32_e64 v15, 0, v15, s[4:5]
	v_cndmask_b32_e64 v14, 0, v14, s[4:5]
	v_cndmask_b32_e64 v13, v13, 0, s[8:9]
	v_cndmask_b32_e64 v12, v12, 0, s[8:9]
	v_cndmask_b32_e64 v11, 0, v11, s[6:7]
	v_cndmask_b32_e64 v10, 0, v10, s[6:7]
	v_cndmask_b32_e64 v9, 0, v9, s[4:5]
	v_cndmask_b32_e64 v8, 0, v8, s[4:5]
	s_waitcnt lgkmcnt(0)
	v_pk_fma_f32 v[4:5], v[4:5], v[30:31], v[26:27]
	v_pk_fma_f32 v[6:7], v[6:7], v[32:33], v[28:29]
	v_pk_fma_f32 v[4:5], v[24:25], v[34:35], v[4:5]
	v_pk_fma_f32 v[6:7], v[12:13], v[36:37], v[6:7]
	v_pk_fma_f32 v[4:5], v[22:23], v[38:39], v[4:5]
	s_nop 0
	v_pk_fma_f32 v[4:5], v[14:15], v[42:43], v[4:5]
	v_pk_fma_f32 v[6:7], v[10:11], v[40:41], v[6:7]
	v_pk_fma_f32 v[6:7], v[8:9], v[44:45], v[6:7]
	v_pk_mul_f32 v[14:15], v[4:5], s[98:99] op_sel_hi:[1,0]
	v_exp_f32_e32 v14, v14
	v_exp_f32_e32 v15, v15
	s_nop 0
	v_pk_add_f32 v[14:15], v[14:15], 1.0 op_sel_hi:[1,0]
	v_rcp_f32_e32 v14, v14
	v_rcp_f32_e32 v15, v15
	s_nop 0
	v_pk_mul_f32 v[4:5], v[4:5], v[14:15]
	s_nop 0
	v_cvt_pk_bf16_f32 v4, v4, v5
	v_pk_mul_f32 v[8:9], v[6:7], s[98:99] op_sel_hi:[1,0]
	v_exp_f32_e32 v8, v8
	v_exp_f32_e32 v9, v9
	s_nop 0
	v_pk_add_f32 v[8:9], v[8:9], 1.0 op_sel_hi:[1,0]
	v_rcp_f32_e32 v8, v8
	v_rcp_f32_e32 v9, v9
	s_nop 0
	v_pk_mul_f32 v[6:7], v[6:7], v[8:9]
	s_nop 0
	v_cvt_pk_bf16_f32 v5, v6, v7
	global_store_dwordx2 v[16:17], v[4:5], off offset:256
.LBB0_245:
	s_or_b64 exec, exec, s[22:23]
	ds_read_b64 v[4:5], v18 offset:1288
	ds_read_b64 v[6:7], v19 offset:776
	ds_read_b64 v[18:19], v20 offset:264
	s_waitcnt lgkmcnt(0)
	v_lshlrev_b32_e32 v14, 16, v4
	v_and_b32_e32 v15, 0xffff0000, v4
	v_lshlrev_b32_e32 v8, 16, v5
	v_and_b32_e32 v9, 0xffff0000, v5
	v_lshlrev_b32_e32 v12, 16, v6
	v_and_b32_e32 v13, 0xffff0000, v6
	v_lshlrev_b32_e32 v6, 16, v7
	v_and_b32_e32 v7, 0xffff0000, v7
	v_lshlrev_b32_e32 v10, 16, v18
	v_and_b32_e32 v11, 0xffff0000, v18
	v_lshlrev_b32_e32 v4, 16, v19
	v_and_b32_e32 v5, 0xffff0000, v19
	v_mov_b32_dpp v14, v0 row_shr:1 row_mask:0xf bank_mask:0xf
	v_mov_b32_dpp v12, v0 row_shr:2 row_mask:0xf bank_mask:0xf
	v_mov_b32_dpp v10, v0 row_shr:3 row_mask:0xf bank_mask:0xf
	v_mov_b32_dpp v15, v1 row_shr:1 row_mask:0xf bank_mask:0xf
	v_mov_b32_dpp v13, v1 row_shr:2 row_mask:0xf bank_mask:0xf
	v_mov_b32_dpp v11, v1 row_shr:3 row_mask:0xf bank_mask:0xf
	v_mov_b32_dpp v8, v2 row_shr:1 row_mask:0xf bank_mask:0xf
	v_mov_b32_dpp v6, v2 row_shr:2 row_mask:0xf bank_mask:0xf
	v_mov_b32_dpp v4, v2 row_shr:3 row_mask:0xf bank_mask:0xf
	v_mov_b32_dpp v9, v3 row_shr:1 row_mask:0xf bank_mask:0xf
	v_mov_b32_dpp v7, v3 row_shr:2 row_mask:0xf bank_mask:0xf
	v_mov_b32_dpp v5, v3 row_shr:3 row_mask:0xf bank_mask:0xf
	s_and_saveexec_b64 s[22:23], s[2:3]
	s_cbranch_execz .LBB0_247
	ds_read_b128 v[18:21], v238 offset:4624
	ds_read_b128 v[22:25], v238 offset:3600
	ds_read_b128 v[26:29], v238 offset:2576
	v_cndmask_b32_e64 v15, v15, 0, s[8:9]
	ds_read_b128 v[30:33], v238 offset:1552
	s_nop 0
	ds_read_b128 v[34:37], v238 offset:528
	v_cndmask_b32_e64 v14, v14, 0, s[8:9]
	v_cndmask_b32_e64 v13, 0, v13, s[6:7]
	v_cndmask_b32_e64 v12, 0, v12, s[6:7]
	v_cndmask_b32_e64 v11, 0, v11, s[4:5]
	v_cndmask_b32_e64 v10, 0, v10, s[4:5]
	v_cndmask_b32_e64 v9, v9, 0, s[8:9]
	v_cndmask_b32_e64 v8, v8, 0, s[8:9]
	v_cndmask_b32_e64 v7, 0, v7, s[6:7]
	v_cndmask_b32_e64 v6, 0, v6, s[6:7]
	v_cndmask_b32_e64 v5, 0, v5, s[4:5]
	v_cndmask_b32_e64 v4, 0, v4, s[4:5]
	s_waitcnt lgkmcnt(0)
	v_pk_fma_f32 v[0:1], v[0:1], v[22:23], v[18:19]
	v_pk_fma_f32 v[2:3], v[2:3], v[24:25], v[20:21]
	v_pk_fma_f32 v[0:1], v[14:15], v[26:27], v[0:1]
	v_pk_fma_f32 v[2:3], v[8:9], v[28:29], v[2:3]
	v_pk_fma_f32 v[0:1], v[12:13], v[30:31], v[0:1]
	s_nop 0
	v_pk_fma_f32 v[0:1], v[10:11], v[34:35], v[0:1]
	v_pk_fma_f32 v[2:3], v[6:7], v[32:33], v[2:3]
	v_pk_fma_f32 v[2:3], v[4:5], v[36:37], v[2:3]
	v_pk_mul_f32 v[10:11], v[0:1], s[98:99] op_sel_hi:[1,0]
	v_exp_f32_e32 v10, v10
	v_exp_f32_e32 v11, v11
	s_nop 0
	v_pk_add_f32 v[10:11], v[10:11], 1.0 op_sel_hi:[1,0]
	v_rcp_f32_e32 v10, v10
	v_rcp_f32_e32 v11, v11
	s_nop 0
	v_pk_mul_f32 v[0:1], v[0:1], v[10:11]
	s_nop 0
	v_cvt_pk_bf16_f32 v0, v0, v1
	v_pk_mul_f32 v[4:5], v[2:3], s[98:99] op_sel_hi:[1,0]
	v_exp_f32_e32 v4, v4
	v_exp_f32_e32 v5, v5
	s_nop 0
	v_pk_add_f32 v[4:5], v[4:5], 1.0 op_sel_hi:[1,0]
	v_rcp_f32_e32 v4, v4
	v_rcp_f32_e32 v5, v5
	s_nop 0
	v_pk_mul_f32 v[2:3], v[2:3], v[4:5]
	s_nop 0
	v_cvt_pk_bf16_f32 v1, v2, v3
	global_store_dwordx2 v[16:17], v[0:1], off offset:264
